# de-serialized residual/Q/K GEMM epilogues and scanB (batched loads, counted vmcnt), hoisted gla_norm_g loads out of scanC task loop, attention loop rescheduled
# speedup vs baseline: 1.0267x; 1.0228x over previous
;   __device__ __forceinline__ void operator()(f32x4 (&acc)[2][2][4][2], int pm, int pn, int wr_, int wc_, int fr_, int fq_, bf16_t* shm, int tid) const {
;     ...
;     const float* Xr = (!fdown && l == 0) ? (pm < 256 ? p.x : p.ctx - (long)NLAT * DM) : (const float*)X;
;     const long bio = (long)row_bi(pm * 256) * 6144;
;     f2_t* red = (f2_t*)((char*)shm + 128 * 1024);
;     f2_t* rst = (f2_t*)((char*)shm + 128 * 1024 + 8192);
;     float s1[8], s2[8];
; #pragma unroll
;     for (int i = 0; i < 8; ++i) { s1[i] = 0.f; s2[i] = 0.f; }
; #pragma unroll
;     for (int bj = 0; bj < 2; ++bj)
; #pragma unroll
;       for (int n = 0; n < 2; ++n) {
;         asm volatile("" ::: "memory");
;         const int col = pn * 256 + bj * 128 + wc * 32 + n * 16 + fq * 4;
;         f32x4 lg = {1.f, 1.f, 1.f, 1.f}, lb = {0.f, 0.f, 0.f, 0.f};
;         if (stats) { lg = *(const f32x4*)(lng + col); lb = *(const f32x4*)(lnb + col); }
;         const f32x4 gv = *(const f32x4*)(g + bio + col);
; #pragma unroll
;         for (int ai = 0; ai < 2; ++ai)
; #pragma unroll
;           for (int m = 0; m < 4; ++m) {
;             const int row = pm * 256 + ai * 128 + wr * 64 + m * 16 + fr;
;             const f32x4 v = acc[ai][bj][m][n];
;             f32x4* xp = (f32x4*)(X + (long)row * DM + col);
;             f32x4 xv = *(const f32x4*)(Xr + (long)row * DM + col);
;             if (stats) { const float mu = stats[2 * row], rs = stats[2 * row + 1]; xv = (xv - mu) * rs * lg + lb; }
;             xv = xv * ALPHA + gv * v; *xp = xv;
;             acc[ai][bj][m][n] = xv;
;             s1[ai * 4 + m] += (xv[0] + xv[1]) + (xv[2] + xv[3]);
;             s2[ai * 4 + m] += (xv[0] * xv[0] + xv[1] * xv[1]) + (xv[2] * xv[2] + xv[3] * xv[3]);
;           }
.LBB0_130:
	v_readlane_b32 s1, v250, 0
	s_nop 15
	s_nop 15
	v_mbcnt_lo_u32_b32 v138, -1, 0
	v_mbcnt_hi_u32_b32 v138, -1, v138
	s_lshl_b32 s0, s29, 8
	v_bfe_u32 v216, v138, 4, 2
	v_add_u32_e32 v148, s1, v138
	v_bfe_u32 v215, v148, 6, 2
	v_lshlrev_b32_e32 v0, 5, v215
	v_lshlrev_b32_e32 v130, 2, v216
	v_or3_b32 v0, v0, v130, s0
	v_readlane_b32 s0, v250, 51
	v_readlane_b32 s1, v250, 52
	v_lshlrev_b64 v[146:147], 2, v[0:1]
	s_andn2_b64 vcc, exec, s[0:1]
	v_cndmask_b32_e64 v130, 0, 1, s[0:1]
	v_cmp_ne_u32_e64 s[8:9], 1, v130
	v_lshl_add_u64 v[162:163], s[84:85], 0, v[146:147]
	v_lshl_add_u64 v[164:165], s[86:87], 0, v[146:147]
	s_min_i32 s0, s28, 0x10000
	s_ashr_i32 s0, s0, 11
	s_mul_hi_i32 s1, s0, 0x1800
	s_mulk_i32 s0, 0x1800
	s_lshl_b64 s[0:1], s[0:1], 2
	v_and_b32_e32 v149, 15, v138
	v_ashrrev_i32_e32 v138, 2, v148
	v_and_b32_e32 v214, 0xffffffc0, v138
	v_or_b32_e32 v138, s28, v149
	v_add_u32_e32 v227, v214, v138
	s_add_u32 s50, s78, s0
	s_addc_u32 s51, s79, s1
	v_readlane_b32 s52, v252, 24
	v_readlane_b32 s53, v252, 25
	v_readlane_b32 s44, v253, 21
	v_readlane_b32 s45, v253, 22
	s_mov_b64 s[54:55], s[52:53]
	s_and_b64 vcc, exec, s[8:9]
	s_cselect_b32 s44, s54, s44
	s_cselect_b32 s45, s55, s45
	s_cselect_b32 s46, s50, s84
	s_cselect_b32 s47, s51, s85
	s_cselect_b32 s48, s50, s86
	s_cselect_b32 s49, s51, s87
	v_lshlrev_b32_e32 v225, 3, v227
	v_lshlrev_b32_e32 v217, 12, v227
	v_add_u32_e32 v217, v217, v146
	v_add_u32_e32 v218, 0x10000, v217
	v_add_u32_e32 v219, 0x20000, v217
	v_add_u32_e32 v220, 0x30000, v217
	v_add_u32_e32 v221, 0x80000, v217
	v_add_u32_e32 v222, 0x90000, v217
	v_add_u32_e32 v223, 0xa0000, v217
	v_add_u32_e32 v224, 0xb0000, v217
	global_load_dwordx2 v[130:131], v225, s[44:45]
	global_load_dwordx2 v[132:133], v225, s[44:45] offset:128
	global_load_dwordx2 v[134:135], v225, s[44:45] offset:256
	global_load_dwordx2 v[136:137], v225, s[44:45] offset:384
	global_load_dwordx2 v[138:139], v225, s[44:45] offset:1024
	global_load_dwordx2 v[140:141], v225, s[44:45] offset:1152
	global_load_dwordx2 v[142:143], v225, s[44:45] offset:1280
	global_load_dwordx2 v[144:145], v225, s[44:45] offset:1408
	global_load_dwordx4 v[228:231], v146, s[46:47]
	global_load_dwordx4 v[232:235], v146, s[48:49]
	global_load_dwordx4 v[236:239], v146, s[50:51]
	global_load_dwordx4 v[150:153], v217, s[52:53]
	global_load_dwordx4 v[154:157], v218, s[52:53]
	global_load_dwordx4 v[158:161], v219, s[52:53]
	global_load_dwordx4 v[162:165], v220, s[52:53]
	global_load_dwordx4 v[166:169], v221, s[52:53]
	global_load_dwordx4 v[170:173], v222, s[52:53]
	global_load_dwordx4 v[174:177], v223, s[52:53]
	global_load_dwordx4 v[178:181], v224, s[52:53]
	global_load_dwordx4 v[182:185], v217, s[52:53] offset:64
	global_load_dwordx4 v[186:189], v218, s[52:53] offset:64
	global_load_dwordx4 v[190:193], v219, s[52:53] offset:64
	global_load_dwordx4 v[194:197], v220, s[52:53] offset:64
	global_load_dwordx4 v[240:243], v146, s[46:47] offset:64
	global_load_dwordx4 v[244:247], v146, s[48:49] offset:64
	global_load_dwordx4 v[198:201], v146, s[50:51] offset:64
	s_waitcnt vmcnt(14)
	s_cbranch_vccnz .Lres_r1_skip0
	v_sub_f32_e32 v153, v153, v130
	v_sub_f32_e32 v152, v152, v130
	v_sub_f32_e32 v151, v151, v130
	v_sub_f32_e32 v150, v150, v130
	v_pk_mul_f32 v[150:151], v[150:151], v[130:131] op_sel:[0,1]
	v_pk_mul_f32 v[152:153], v[152:153], v[130:131] op_sel:[0,1]
	v_pk_fma_f32 v[150:151], v[228:229], v[150:151], v[232:233]
	v_pk_fma_f32 v[152:153], v[230:231], v[152:153], v[234:235]
.Lres_r1_skip0:
	v_pk_mul_f32 v[150:151], v[150:151], s[92:93] op_sel_hi:[1,0]
	v_pk_mul_f32 v[152:153], v[152:153], s[92:93] op_sel_hi:[1,0]
	v_pk_fma_f32 v[2:3], v[2:3], v[236:237], v[150:151]
	v_pk_fma_f32 v[4:5], v[4:5], v[238:239], v[152:153]
	global_store_dwordx4 v217, v[2:5], s[54:55]
	global_load_dwordx4 v[150:153], v221, s[52:53] offset:64
	s_waitcnt vmcnt(15)
	s_cbranch_vccnz .Lres_r1_skip1
	v_sub_f32_e32 v157, v157, v132
	v_sub_f32_e32 v156, v156, v132
	v_sub_f32_e32 v155, v155, v132
	v_sub_f32_e32 v154, v154, v132
	v_pk_mul_f32 v[154:155], v[154:155], v[132:133] op_sel:[0,1]
	v_pk_mul_f32 v[156:157], v[156:157], v[132:133] op_sel:[0,1]
	v_pk_fma_f32 v[154:155], v[228:229], v[154:155], v[232:233]
	v_pk_fma_f32 v[156:157], v[230:231], v[156:157], v[234:235]
.Lres_r1_skip1:
	v_pk_mul_f32 v[154:155], v[154:155], s[92:93] op_sel_hi:[1,0]
	v_pk_mul_f32 v[156:157], v[156:157], s[92:93] op_sel_hi:[1,0]
	v_pk_fma_f32 v[6:7], v[6:7], v[236:237], v[154:155]
	v_pk_fma_f32 v[8:9], v[8:9], v[238:239], v[156:157]
	global_store_dwordx4 v218, v[6:9], s[54:55]
	global_load_dwordx4 v[154:157], v222, s[52:53] offset:64
	s_waitcnt vmcnt(16)
	s_cbranch_vccnz .Lres_r1_skip2
	v_sub_f32_e32 v161, v161, v134
	v_sub_f32_e32 v160, v160, v134
	v_sub_f32_e32 v159, v159, v134
	v_sub_f32_e32 v158, v158, v134
	v_pk_mul_f32 v[158:159], v[158:159], v[134:135] op_sel:[0,1]
	v_pk_mul_f32 v[160:161], v[160:161], v[134:135] op_sel:[0,1]
	v_pk_fma_f32 v[158:159], v[228:229], v[158:159], v[232:233]
	v_pk_fma_f32 v[160:161], v[230:231], v[160:161], v[234:235]
.Lres_r1_skip2:
	v_pk_mul_f32 v[158:159], v[158:159], s[92:93] op_sel_hi:[1,0]
	v_pk_mul_f32 v[160:161], v[160:161], s[92:93] op_sel_hi:[1,0]
	v_pk_fma_f32 v[10:11], v[10:11], v[236:237], v[158:159]
	v_pk_fma_f32 v[12:13], v[12:13], v[238:239], v[160:161]
	global_store_dwordx4 v219, v[10:13], s[54:55]
	global_load_dwordx4 v[158:161], v223, s[52:53] offset:64
	s_waitcnt vmcnt(17)
	s_cbranch_vccnz .Lres_r1_skip3
	v_sub_f32_e32 v165, v165, v136
	v_sub_f32_e32 v164, v164, v136
	v_sub_f32_e32 v163, v163, v136
	v_sub_f32_e32 v162, v162, v136
	v_pk_mul_f32 v[162:163], v[162:163], v[136:137] op_sel:[0,1]
	v_pk_mul_f32 v[164:165], v[164:165], v[136:137] op_sel:[0,1]
	v_pk_fma_f32 v[162:163], v[228:229], v[162:163], v[232:233]
	v_pk_fma_f32 v[164:165], v[230:231], v[164:165], v[234:235]
;   __device__ __forceinline__ void operator()(f32x4 (&acc)[2][2][4][2], int pm, int pn, int wr_, int wc_, int fr_, int fq_, bf16_t* shm, int tid) const {
;     ...
;         for (int ai = 0; ai < 2; ++ai)
; #pragma unroll
;           for (int m = 0; m < 4; ++m) {
;             const int row = pm * 256 + ai * 128 + wr * 64 + m * 16 + fr;
;             const f32x4 v = acc[ai][bj][m][n];
;             f32x4* xp = (f32x4*)(X + (long)row * DM + col);
;             f32x4 xv = *(const f32x4*)(Xr + (long)row * DM + col);
;             if (stats) { const float mu = stats[2 * row], rs = stats[2 * row + 1]; xv = (xv - mu) * rs * lg + lb; }
;             xv = xv * ALPHA + gv * v; *xp = xv;
;             acc[ai][bj][m][n] = xv;
.Lres_r1_skip3:
	v_pk_mul_f32 v[162:163], v[162:163], s[92:93] op_sel_hi:[1,0]
	v_pk_mul_f32 v[164:165], v[164:165], s[92:93] op_sel_hi:[1,0]
	v_pk_fma_f32 v[14:15], v[14:15], v[236:237], v[162:163]
	v_pk_fma_f32 v[16:17], v[16:17], v[238:239], v[164:165]
	global_store_dwordx4 v220, v[14:17], s[54:55]
	global_load_dwordx4 v[162:165], v224, s[52:53] offset:64
	s_waitcnt vmcnt(18)
	s_cbranch_vccnz .Lres_r1_skip4
	v_sub_f32_e32 v169, v169, v138
	v_sub_f32_e32 v168, v168, v138
	v_sub_f32_e32 v167, v167, v138
	v_sub_f32_e32 v166, v166, v138
	v_pk_mul_f32 v[166:167], v[166:167], v[138:139] op_sel:[0,1]
	v_pk_mul_f32 v[168:169], v[168:169], v[138:139] op_sel:[0,1]
	v_pk_fma_f32 v[166:167], v[228:229], v[166:167], v[232:233]
	v_pk_fma_f32 v[168:169], v[230:231], v[168:169], v[234:235]
.Lres_r1_skip4:
	v_pk_mul_f32 v[166:167], v[166:167], s[92:93] op_sel_hi:[1,0]
	v_pk_mul_f32 v[168:169], v[168:169], s[92:93] op_sel_hi:[1,0]
	v_pk_fma_f32 v[18:19], v[18:19], v[236:237], v[166:167]
	v_pk_fma_f32 v[20:21], v[20:21], v[238:239], v[168:169]
	global_store_dwordx4 v221, v[18:21], s[54:55]
	global_load_dwordx4 v[166:169], v217, s[52:53] offset:512
	s_waitcnt vmcnt(19)
	s_cbranch_vccnz .Lres_r1_skip5
	v_sub_f32_e32 v173, v173, v140
	v_sub_f32_e32 v172, v172, v140
	v_sub_f32_e32 v171, v171, v140
	v_sub_f32_e32 v170, v170, v140
	v_pk_mul_f32 v[170:171], v[170:171], v[140:141] op_sel:[0,1]
	v_pk_mul_f32 v[172:173], v[172:173], v[140:141] op_sel:[0,1]
	v_pk_fma_f32 v[170:171], v[228:229], v[170:171], v[232:233]
	v_pk_fma_f32 v[172:173], v[230:231], v[172:173], v[234:235]
.Lres_r1_skip5:
	v_pk_mul_f32 v[170:171], v[170:171], s[92:93] op_sel_hi:[1,0]
	v_pk_mul_f32 v[172:173], v[172:173], s[92:93] op_sel_hi:[1,0]
	v_pk_fma_f32 v[22:23], v[22:23], v[236:237], v[170:171]
	v_pk_fma_f32 v[24:25], v[24:25], v[238:239], v[172:173]
	global_store_dwordx4 v222, v[22:25], s[54:55]
	global_load_dwordx4 v[170:173], v218, s[52:53] offset:512
	s_waitcnt vmcnt(20)
	s_cbranch_vccnz .Lres_r1_skip6
	v_sub_f32_e32 v177, v177, v142
	v_sub_f32_e32 v176, v176, v142
	v_sub_f32_e32 v175, v175, v142
	v_sub_f32_e32 v174, v174, v142
	v_pk_mul_f32 v[174:175], v[174:175], v[142:143] op_sel:[0,1]
	v_pk_mul_f32 v[176:177], v[176:177], v[142:143] op_sel:[0,1]
	v_pk_fma_f32 v[174:175], v[228:229], v[174:175], v[232:233]
	v_pk_fma_f32 v[176:177], v[230:231], v[176:177], v[234:235]
.Lres_r1_skip6:
	v_pk_mul_f32 v[174:175], v[174:175], s[92:93] op_sel_hi:[1,0]
	v_pk_mul_f32 v[176:177], v[176:177], s[92:93] op_sel_hi:[1,0]
	v_pk_fma_f32 v[26:27], v[26:27], v[236:237], v[174:175]
	v_pk_fma_f32 v[28:29], v[28:29], v[238:239], v[176:177]
	global_store_dwordx4 v223, v[26:29], s[54:55]
	global_load_dwordx4 v[174:177], v219, s[52:53] offset:512
	s_waitcnt vmcnt(21)
	s_cbranch_vccnz .Lres_r1_skip7
	v_sub_f32_e32 v181, v181, v144
	v_sub_f32_e32 v180, v180, v144
	v_sub_f32_e32 v179, v179, v144
	v_sub_f32_e32 v178, v178, v144
	v_pk_mul_f32 v[178:179], v[178:179], v[144:145] op_sel:[0,1]
	v_pk_mul_f32 v[180:181], v[180:181], v[144:145] op_sel:[0,1]
	v_pk_fma_f32 v[178:179], v[228:229], v[178:179], v[232:233]
	v_pk_fma_f32 v[180:181], v[230:231], v[180:181], v[234:235]
.Lres_r1_skip7:
	v_pk_mul_f32 v[178:179], v[178:179], s[92:93] op_sel_hi:[1,0]
	v_pk_mul_f32 v[180:181], v[180:181], s[92:93] op_sel_hi:[1,0]
	v_pk_fma_f32 v[34:35], v[34:35], v[236:237], v[178:179]
	v_pk_fma_f32 v[36:37], v[36:37], v[238:239], v[180:181]
	global_store_dwordx4 v224, v[34:37], s[54:55]
	global_load_dwordx4 v[178:181], v220, s[52:53] offset:512
	global_load_dwordx4 v[228:231], v146, s[46:47] offset:512
	global_load_dwordx4 v[232:235], v146, s[48:49] offset:512
	global_load_dwordx4 v[236:239], v146, s[50:51] offset:512
	s_waitcnt vmcnt(25)
	s_cbranch_vccnz .Lres_r1_skip8
	v_sub_f32_e32 v185, v185, v130
	v_sub_f32_e32 v184, v184, v130
	v_sub_f32_e32 v183, v183, v130
	v_sub_f32_e32 v182, v182, v130
	v_pk_mul_f32 v[182:183], v[182:183], v[130:131] op_sel:[0,1]
	v_pk_mul_f32 v[184:185], v[184:185], v[130:131] op_sel:[0,1]
	v_pk_fma_f32 v[182:183], v[240:241], v[182:183], v[244:245]
	v_pk_fma_f32 v[184:185], v[242:243], v[184:185], v[246:247]
.Lres_r1_skip8:
	v_pk_mul_f32 v[182:183], v[182:183], s[92:93] op_sel_hi:[1,0]
	v_pk_mul_f32 v[184:185], v[184:185], s[92:93] op_sel_hi:[1,0]
	v_pk_fma_f32 v[30:31], v[30:31], v[198:199], v[182:183]
	v_pk_fma_f32 v[32:33], v[32:33], v[200:201], v[184:185]
	global_store_dwordx4 v217, v[30:33], s[54:55] offset:64
	global_load_dwordx4 v[182:185], v221, s[52:53] offset:512
	s_waitcnt vmcnt(26)
	s_cbranch_vccnz .Lres_r1_skip9
	v_sub_f32_e32 v189, v189, v132
	v_sub_f32_e32 v188, v188, v132
	v_sub_f32_e32 v187, v187, v132
	v_sub_f32_e32 v186, v186, v132
	v_pk_mul_f32 v[186:187], v[186:187], v[132:133] op_sel:[0,1]
	v_pk_mul_f32 v[188:189], v[188:189], v[132:133] op_sel:[0,1]
	v_pk_fma_f32 v[186:187], v[240:241], v[186:187], v[244:245]
	v_pk_fma_f32 v[188:189], v[242:243], v[188:189], v[246:247]
.Lres_r1_skip9:
	v_pk_mul_f32 v[186:187], v[186:187], s[92:93] op_sel_hi:[1,0]
	v_pk_mul_f32 v[188:189], v[188:189], s[92:93] op_sel_hi:[1,0]
	v_pk_fma_f32 v[38:39], v[38:39], v[198:199], v[186:187]
	v_pk_fma_f32 v[40:41], v[40:41], v[200:201], v[188:189]
	global_store_dwordx4 v218, v[38:41], s[54:55] offset:64
	global_load_dwordx4 v[186:189], v222, s[52:53] offset:512
	s_waitcnt vmcnt(27)
	s_cbranch_vccnz .Lres_r1_skip10
	v_sub_f32_e32 v193, v193, v134
	v_sub_f32_e32 v192, v192, v134
	v_sub_f32_e32 v191, v191, v134
	v_sub_f32_e32 v190, v190, v134
	v_pk_mul_f32 v[190:191], v[190:191], v[134:135] op_sel:[0,1]
	v_pk_mul_f32 v[192:193], v[192:193], v[134:135] op_sel:[0,1]
	v_pk_fma_f32 v[190:191], v[240:241], v[190:191], v[244:245]
	v_pk_fma_f32 v[192:193], v[242:243], v[192:193], v[246:247]
;   __device__ __forceinline__ void operator()(f32x4 (&acc)[2][2][4][2], int pm, int pn, int wr_, int wc_, int fr_, int fq_, bf16_t* shm, int tid) const {
;     ...
;         for (int ai = 0; ai < 2; ++ai)
; #pragma unroll
;           for (int m = 0; m < 4; ++m) {
;             const int row = pm * 256 + ai * 128 + wr * 64 + m * 16 + fr;
;             const f32x4 v = acc[ai][bj][m][n];
;             f32x4* xp = (f32x4*)(X + (long)row * DM + col);
;             f32x4 xv = *(const f32x4*)(Xr + (long)row * DM + col);
;             if (stats) { const float mu = stats[2 * row], rs = stats[2 * row + 1]; xv = (xv - mu) * rs * lg + lb; }
;             xv = xv * ALPHA + gv * v; *xp = xv;
;             acc[ai][bj][m][n] = xv;
.Lres_r1_skip10:
	v_pk_mul_f32 v[190:191], v[190:191], s[92:93] op_sel_hi:[1,0]
	v_pk_mul_f32 v[192:193], v[192:193], s[92:93] op_sel_hi:[1,0]
	v_pk_fma_f32 v[42:43], v[42:43], v[198:199], v[190:191]
	v_pk_fma_f32 v[44:45], v[44:45], v[200:201], v[192:193]
	global_store_dwordx4 v219, v[42:45], s[54:55] offset:64
	global_load_dwordx4 v[190:193], v223, s[52:53] offset:512
	s_waitcnt vmcnt(28)
	s_cbranch_vccnz .Lres_r1_skip11
	v_sub_f32_e32 v197, v197, v136
	v_sub_f32_e32 v196, v196, v136
	v_sub_f32_e32 v195, v195, v136
	v_sub_f32_e32 v194, v194, v136
	v_pk_mul_f32 v[194:195], v[194:195], v[136:137] op_sel:[0,1]
	v_pk_mul_f32 v[196:197], v[196:197], v[136:137] op_sel:[0,1]
	v_pk_fma_f32 v[194:195], v[240:241], v[194:195], v[244:245]
	v_pk_fma_f32 v[196:197], v[242:243], v[196:197], v[246:247]
.Lres_r1_skip11:
	v_pk_mul_f32 v[194:195], v[194:195], s[92:93] op_sel_hi:[1,0]
	v_pk_mul_f32 v[196:197], v[196:197], s[92:93] op_sel_hi:[1,0]
	v_pk_fma_f32 v[46:47], v[46:47], v[198:199], v[194:195]
	v_pk_fma_f32 v[48:49], v[48:49], v[200:201], v[196:197]
	global_store_dwordx4 v220, v[46:49], s[54:55] offset:64
	global_load_dwordx4 v[194:197], v224, s[52:53] offset:512
	s_waitcnt vmcnt(25)
	s_cbranch_vccnz .Lres_r1_skip12
	v_sub_f32_e32 v153, v153, v138
	v_sub_f32_e32 v152, v152, v138
	v_sub_f32_e32 v151, v151, v138
	v_sub_f32_e32 v150, v150, v138
	v_pk_mul_f32 v[150:151], v[150:151], v[138:139] op_sel:[0,1]
	v_pk_mul_f32 v[152:153], v[152:153], v[138:139] op_sel:[0,1]
	v_pk_fma_f32 v[150:151], v[240:241], v[150:151], v[244:245]
	v_pk_fma_f32 v[152:153], v[242:243], v[152:153], v[246:247]
.Lres_r1_skip12:
	v_pk_mul_f32 v[150:151], v[150:151], s[92:93] op_sel_hi:[1,0]
	v_pk_mul_f32 v[152:153], v[152:153], s[92:93] op_sel_hi:[1,0]
	v_pk_fma_f32 v[50:51], v[50:51], v[198:199], v[150:151]
	v_pk_fma_f32 v[52:53], v[52:53], v[200:201], v[152:153]
	global_store_dwordx4 v221, v[50:53], s[54:55] offset:64
	global_load_dwordx4 v[150:153], v217, s[52:53] offset:576
	s_waitcnt vmcnt(25)
	s_cbranch_vccnz .Lres_r1_skip13
	v_sub_f32_e32 v157, v157, v140
	v_sub_f32_e32 v156, v156, v140
	v_sub_f32_e32 v155, v155, v140
	v_sub_f32_e32 v154, v154, v140
	v_pk_mul_f32 v[154:155], v[154:155], v[140:141] op_sel:[0,1]
	v_pk_mul_f32 v[156:157], v[156:157], v[140:141] op_sel:[0,1]
	v_pk_fma_f32 v[154:155], v[240:241], v[154:155], v[244:245]
	v_pk_fma_f32 v[156:157], v[242:243], v[156:157], v[246:247]
.Lres_r1_skip13:
	v_pk_mul_f32 v[154:155], v[154:155], s[92:93] op_sel_hi:[1,0]
	v_pk_mul_f32 v[156:157], v[156:157], s[92:93] op_sel_hi:[1,0]
	v_pk_fma_f32 v[54:55], v[54:55], v[198:199], v[154:155]
	v_pk_fma_f32 v[56:57], v[56:57], v[200:201], v[156:157]
	global_store_dwordx4 v222, v[54:57], s[54:55] offset:64
	global_load_dwordx4 v[154:157], v218, s[52:53] offset:576
	s_waitcnt vmcnt(25)
	s_cbranch_vccnz .Lres_r1_skip14
	v_sub_f32_e32 v161, v161, v142
	v_sub_f32_e32 v160, v160, v142
	v_sub_f32_e32 v159, v159, v142
	v_sub_f32_e32 v158, v158, v142
	v_pk_mul_f32 v[158:159], v[158:159], v[142:143] op_sel:[0,1]
	v_pk_mul_f32 v[160:161], v[160:161], v[142:143] op_sel:[0,1]
	v_pk_fma_f32 v[158:159], v[240:241], v[158:159], v[244:245]
	v_pk_fma_f32 v[160:161], v[242:243], v[160:161], v[246:247]
.Lres_r1_skip14:
	v_pk_mul_f32 v[158:159], v[158:159], s[92:93] op_sel_hi:[1,0]
	v_pk_mul_f32 v[160:161], v[160:161], s[92:93] op_sel_hi:[1,0]
	v_pk_fma_f32 v[58:59], v[58:59], v[198:199], v[158:159]
	v_pk_fma_f32 v[60:61], v[60:61], v[200:201], v[160:161]
	global_store_dwordx4 v223, v[58:61], s[54:55] offset:64
	global_load_dwordx4 v[158:161], v219, s[52:53] offset:576
	s_waitcnt vmcnt(25)
	s_cbranch_vccnz .Lres_r1_skip15
	v_sub_f32_e32 v165, v165, v144
	v_sub_f32_e32 v164, v164, v144
	v_sub_f32_e32 v163, v163, v144
	v_sub_f32_e32 v162, v162, v144
	v_pk_mul_f32 v[162:163], v[162:163], v[144:145] op_sel:[0,1]
	v_pk_mul_f32 v[164:165], v[164:165], v[144:145] op_sel:[0,1]
	v_pk_fma_f32 v[162:163], v[240:241], v[162:163], v[244:245]
	v_pk_fma_f32 v[164:165], v[242:243], v[164:165], v[246:247]
.Lres_r1_skip15:
	v_pk_mul_f32 v[162:163], v[162:163], s[92:93] op_sel_hi:[1,0]
	v_pk_mul_f32 v[164:165], v[164:165], s[92:93] op_sel_hi:[1,0]
	v_pk_fma_f32 v[66:67], v[66:67], v[198:199], v[162:163]
	v_pk_fma_f32 v[68:69], v[68:69], v[200:201], v[164:165]
	global_store_dwordx4 v224, v[66:69], s[54:55] offset:64
	global_load_dwordx4 v[162:165], v220, s[52:53] offset:576
	global_load_dwordx4 v[240:243], v146, s[46:47] offset:576
	global_load_dwordx4 v[244:247], v146, s[48:49] offset:576
	global_load_dwordx4 v[198:201], v146, s[50:51] offset:576
	s_waitcnt vmcnt(28)
	s_cbranch_vccnz .Lres_r1_skip16
	v_sub_f32_e32 v169, v169, v130
	v_sub_f32_e32 v168, v168, v130
	v_sub_f32_e32 v167, v167, v130
	v_sub_f32_e32 v166, v166, v130
	v_pk_mul_f32 v[166:167], v[166:167], v[130:131] op_sel:[0,1]
	v_pk_mul_f32 v[168:169], v[168:169], v[130:131] op_sel:[0,1]
	v_pk_fma_f32 v[166:167], v[228:229], v[166:167], v[232:233]
	v_pk_fma_f32 v[168:169], v[230:231], v[168:169], v[234:235]
.Lres_r1_skip16:
	v_pk_mul_f32 v[166:167], v[166:167], s[92:93] op_sel_hi:[1,0]
	v_pk_mul_f32 v[168:169], v[168:169], s[92:93] op_sel_hi:[1,0]
	v_pk_fma_f32 v[62:63], v[62:63], v[236:237], v[166:167]
	v_pk_fma_f32 v[64:65], v[64:65], v[238:239], v[168:169]
	global_store_dwordx4 v217, v[62:65], s[54:55] offset:512
	global_load_dwordx4 v[166:169], v221, s[52:53] offset:576
	s_waitcnt vmcnt(28)
	s_cbranch_vccnz .Lres_r1_skip17
	v_sub_f32_e32 v173, v173, v132
	v_sub_f32_e32 v172, v172, v132
	v_sub_f32_e32 v171, v171, v132
	v_sub_f32_e32 v170, v170, v132
	v_pk_mul_f32 v[170:171], v[170:171], v[132:133] op_sel:[0,1]
	v_pk_mul_f32 v[172:173], v[172:173], v[132:133] op_sel:[0,1]
	v_pk_fma_f32 v[170:171], v[228:229], v[170:171], v[232:233]
	v_pk_fma_f32 v[172:173], v[230:231], v[172:173], v[234:235]
;   __device__ __forceinline__ void operator()(f32x4 (&acc)[2][2][4][2], int pm, int pn, int wr_, int wc_, int fr_, int fq_, bf16_t* shm, int tid) const {
;     ...
;         for (int ai = 0; ai < 2; ++ai)
; #pragma unroll
;           for (int m = 0; m < 4; ++m) {
;             const int row = pm * 256 + ai * 128 + wr * 64 + m * 16 + fr;
;             const f32x4 v = acc[ai][bj][m][n];
;             f32x4* xp = (f32x4*)(X + (long)row * DM + col);
;             f32x4 xv = *(const f32x4*)(Xr + (long)row * DM + col);
;             if (stats) { const float mu = stats[2 * row], rs = stats[2 * row + 1]; xv = (xv - mu) * rs * lg + lb; }
;             xv = xv * ALPHA + gv * v; *xp = xv;
;             acc[ai][bj][m][n] = xv;
.Lres_r1_skip17:
	v_pk_mul_f32 v[170:171], v[170:171], s[92:93] op_sel_hi:[1,0]
	v_pk_mul_f32 v[172:173], v[172:173], s[92:93] op_sel_hi:[1,0]
	v_pk_fma_f32 v[70:71], v[70:71], v[236:237], v[170:171]
	v_pk_fma_f32 v[72:73], v[72:73], v[238:239], v[172:173]
	global_store_dwordx4 v218, v[70:73], s[54:55] offset:512
	global_load_dwordx4 v[170:173], v222, s[52:53] offset:576
	s_waitcnt vmcnt(28)
	s_cbranch_vccnz .Lres_r1_skip18
	v_sub_f32_e32 v177, v177, v134
	v_sub_f32_e32 v176, v176, v134
	v_sub_f32_e32 v175, v175, v134
	v_sub_f32_e32 v174, v174, v134
	v_pk_mul_f32 v[174:175], v[174:175], v[134:135] op_sel:[0,1]
	v_pk_mul_f32 v[176:177], v[176:177], v[134:135] op_sel:[0,1]
	v_pk_fma_f32 v[174:175], v[228:229], v[174:175], v[232:233]
	v_pk_fma_f32 v[176:177], v[230:231], v[176:177], v[234:235]
.Lres_r1_skip18:
	v_pk_mul_f32 v[174:175], v[174:175], s[92:93] op_sel_hi:[1,0]
	v_pk_mul_f32 v[176:177], v[176:177], s[92:93] op_sel_hi:[1,0]
	v_pk_fma_f32 v[74:75], v[74:75], v[236:237], v[174:175]
	v_pk_fma_f32 v[76:77], v[76:77], v[238:239], v[176:177]
	global_store_dwordx4 v219, v[74:77], s[54:55] offset:512
	global_load_dwordx4 v[174:177], v223, s[52:53] offset:576
	s_waitcnt vmcnt(28)
	s_cbranch_vccnz .Lres_r1_skip19
	v_sub_f32_e32 v181, v181, v136
	v_sub_f32_e32 v180, v180, v136
	v_sub_f32_e32 v179, v179, v136
	v_sub_f32_e32 v178, v178, v136
	v_pk_mul_f32 v[178:179], v[178:179], v[136:137] op_sel:[0,1]
	v_pk_mul_f32 v[180:181], v[180:181], v[136:137] op_sel:[0,1]
	v_pk_fma_f32 v[178:179], v[228:229], v[178:179], v[232:233]
	v_pk_fma_f32 v[180:181], v[230:231], v[180:181], v[234:235]
.Lres_r1_skip19:
	v_pk_mul_f32 v[178:179], v[178:179], s[92:93] op_sel_hi:[1,0]
	v_pk_mul_f32 v[180:181], v[180:181], s[92:93] op_sel_hi:[1,0]
	v_pk_fma_f32 v[78:79], v[78:79], v[236:237], v[178:179]
	v_pk_fma_f32 v[80:81], v[80:81], v[238:239], v[180:181]
	global_store_dwordx4 v220, v[78:81], s[54:55] offset:512
	global_load_dwordx4 v[178:181], v224, s[52:53] offset:576
	s_waitcnt vmcnt(25)
	s_cbranch_vccnz .Lres_r1_skip20
	v_sub_f32_e32 v185, v185, v138
	v_sub_f32_e32 v184, v184, v138
	v_sub_f32_e32 v183, v183, v138
	v_sub_f32_e32 v182, v182, v138
	v_pk_mul_f32 v[182:183], v[182:183], v[138:139] op_sel:[0,1]
	v_pk_mul_f32 v[184:185], v[184:185], v[138:139] op_sel:[0,1]
	v_pk_fma_f32 v[182:183], v[228:229], v[182:183], v[232:233]
	v_pk_fma_f32 v[184:185], v[230:231], v[184:185], v[234:235]
.Lres_r1_skip20:
	v_pk_mul_f32 v[182:183], v[182:183], s[92:93] op_sel_hi:[1,0]
	v_pk_mul_f32 v[184:185], v[184:185], s[92:93] op_sel_hi:[1,0]
	v_pk_fma_f32 v[82:83], v[82:83], v[236:237], v[182:183]
	v_pk_fma_f32 v[84:85], v[84:85], v[238:239], v[184:185]
	global_store_dwordx4 v221, v[82:85], s[54:55] offset:512
	s_waitcnt vmcnt(24)
	s_cbranch_vccnz .Lres_r1_skip21
	v_sub_f32_e32 v189, v189, v140
	v_sub_f32_e32 v188, v188, v140
	v_sub_f32_e32 v187, v187, v140
	v_sub_f32_e32 v186, v186, v140
	v_pk_mul_f32 v[186:187], v[186:187], v[140:141] op_sel:[0,1]
	v_pk_mul_f32 v[188:189], v[188:189], v[140:141] op_sel:[0,1]
	v_pk_fma_f32 v[186:187], v[228:229], v[186:187], v[232:233]
	v_pk_fma_f32 v[188:189], v[230:231], v[188:189], v[234:235]
.Lres_r1_skip21:
	v_pk_mul_f32 v[186:187], v[186:187], s[92:93] op_sel_hi:[1,0]
	v_pk_mul_f32 v[188:189], v[188:189], s[92:93] op_sel_hi:[1,0]
	v_pk_fma_f32 v[86:87], v[86:87], v[236:237], v[186:187]
	v_pk_fma_f32 v[88:89], v[88:89], v[238:239], v[188:189]
	global_store_dwordx4 v222, v[86:89], s[54:55] offset:512
	s_waitcnt vmcnt(23)
	s_cbranch_vccnz .Lres_r1_skip22
	v_sub_f32_e32 v193, v193, v142
	v_sub_f32_e32 v192, v192, v142
	v_sub_f32_e32 v191, v191, v142
	v_sub_f32_e32 v190, v190, v142
	v_pk_mul_f32 v[190:191], v[190:191], v[142:143] op_sel:[0,1]
	v_pk_mul_f32 v[192:193], v[192:193], v[142:143] op_sel:[0,1]
	v_pk_fma_f32 v[190:191], v[228:229], v[190:191], v[232:233]
	v_pk_fma_f32 v[192:193], v[230:231], v[192:193], v[234:235]
.Lres_r1_skip22:
	v_pk_mul_f32 v[190:191], v[190:191], s[92:93] op_sel_hi:[1,0]
	v_pk_mul_f32 v[192:193], v[192:193], s[92:93] op_sel_hi:[1,0]
	v_pk_fma_f32 v[90:91], v[90:91], v[236:237], v[190:191]
	v_pk_fma_f32 v[92:93], v[92:93], v[238:239], v[192:193]
	global_store_dwordx4 v223, v[90:93], s[54:55] offset:512
	s_waitcnt vmcnt(22)
	s_cbranch_vccnz .Lres_r1_skip23
	v_sub_f32_e32 v197, v197, v144
	v_sub_f32_e32 v196, v196, v144
	v_sub_f32_e32 v195, v195, v144
	v_sub_f32_e32 v194, v194, v144
	v_pk_mul_f32 v[194:195], v[194:195], v[144:145] op_sel:[0,1]
	v_pk_mul_f32 v[196:197], v[196:197], v[144:145] op_sel:[0,1]
	v_pk_fma_f32 v[194:195], v[228:229], v[194:195], v[232:233]
	v_pk_fma_f32 v[196:197], v[230:231], v[196:197], v[234:235]
.Lres_r1_skip23:
	v_pk_mul_f32 v[194:195], v[194:195], s[92:93] op_sel_hi:[1,0]
	v_pk_mul_f32 v[196:197], v[196:197], s[92:93] op_sel_hi:[1,0]
	v_pk_fma_f32 v[102:103], v[102:103], v[236:237], v[194:195]
	v_pk_fma_f32 v[104:105], v[104:105], v[238:239], v[196:197]
	global_store_dwordx4 v224, v[102:105], s[54:55] offset:512
	s_waitcnt vmcnt(21)
	s_cbranch_vccnz .Lres_r1_skip24
	v_sub_f32_e32 v153, v153, v130
	v_sub_f32_e32 v152, v152, v130
	v_sub_f32_e32 v151, v151, v130
	v_sub_f32_e32 v150, v150, v130
	v_pk_mul_f32 v[150:151], v[150:151], v[130:131] op_sel:[0,1]
	v_pk_mul_f32 v[152:153], v[152:153], v[130:131] op_sel:[0,1]
	v_pk_fma_f32 v[150:151], v[240:241], v[150:151], v[244:245]
	v_pk_fma_f32 v[152:153], v[242:243], v[152:153], v[246:247]
;   __device__ __forceinline__ void operator()(f32x4 (&acc)[2][2][4][2], int pm, int pn, int wr_, int wc_, int fr_, int fq_, bf16_t* shm, int tid) const {
;     ...
;         for (int ai = 0; ai < 2; ++ai)
; #pragma unroll
;           for (int m = 0; m < 4; ++m) {
;             const int row = pm * 256 + ai * 128 + wr * 64 + m * 16 + fr;
;             const f32x4 v = acc[ai][bj][m][n];
;             f32x4* xp = (f32x4*)(X + (long)row * DM + col);
;             f32x4 xv = *(const f32x4*)(Xr + (long)row * DM + col);
;             if (stats) { const float mu = stats[2 * row], rs = stats[2 * row + 1]; xv = (xv - mu) * rs * lg + lb; }
;             xv = xv * ALPHA + gv * v; *xp = xv;
;             acc[ai][bj][m][n] = xv;
.Lres_r1_skip24:
	v_pk_mul_f32 v[150:151], v[150:151], s[92:93] op_sel_hi:[1,0]
	v_pk_mul_f32 v[152:153], v[152:153], s[92:93] op_sel_hi:[1,0]
	v_pk_fma_f32 v[98:99], v[98:99], v[198:199], v[150:151]
	v_pk_fma_f32 v[100:101], v[100:101], v[200:201], v[152:153]
	global_store_dwordx4 v217, v[98:101], s[54:55] offset:576
	s_waitcnt vmcnt(20)
	s_cbranch_vccnz .Lres_r1_skip25
	v_sub_f32_e32 v157, v157, v132
	v_sub_f32_e32 v156, v156, v132
	v_sub_f32_e32 v155, v155, v132
	v_sub_f32_e32 v154, v154, v132
	v_pk_mul_f32 v[154:155], v[154:155], v[132:133] op_sel:[0,1]
	v_pk_mul_f32 v[156:157], v[156:157], v[132:133] op_sel:[0,1]
	v_pk_fma_f32 v[154:155], v[240:241], v[154:155], v[244:245]
	v_pk_fma_f32 v[156:157], v[242:243], v[156:157], v[246:247]
.Lres_r1_skip25:
	v_pk_mul_f32 v[154:155], v[154:155], s[92:93] op_sel_hi:[1,0]
	v_pk_mul_f32 v[156:157], v[156:157], s[92:93] op_sel_hi:[1,0]
	v_pk_fma_f32 v[106:107], v[106:107], v[198:199], v[154:155]
	v_pk_fma_f32 v[108:109], v[108:109], v[200:201], v[156:157]
	global_store_dwordx4 v218, v[106:109], s[54:55] offset:576
	s_waitcnt vmcnt(19)
	s_cbranch_vccnz .Lres_r1_skip26
	v_sub_f32_e32 v161, v161, v134
	v_sub_f32_e32 v160, v160, v134
	v_sub_f32_e32 v159, v159, v134
	v_sub_f32_e32 v158, v158, v134
	v_pk_mul_f32 v[158:159], v[158:159], v[134:135] op_sel:[0,1]
	v_pk_mul_f32 v[160:161], v[160:161], v[134:135] op_sel:[0,1]
	v_pk_fma_f32 v[158:159], v[240:241], v[158:159], v[244:245]
	v_pk_fma_f32 v[160:161], v[242:243], v[160:161], v[246:247]
.Lres_r1_skip26:
	v_pk_mul_f32 v[158:159], v[158:159], s[92:93] op_sel_hi:[1,0]
	v_pk_mul_f32 v[160:161], v[160:161], s[92:93] op_sel_hi:[1,0]
	v_pk_fma_f32 v[110:111], v[110:111], v[198:199], v[158:159]
	v_pk_fma_f32 v[112:113], v[112:113], v[200:201], v[160:161]
	global_store_dwordx4 v219, v[110:113], s[54:55] offset:576
	s_waitcnt vmcnt(18)
	s_cbranch_vccnz .Lres_r1_skip27
	v_sub_f32_e32 v165, v165, v136
	v_sub_f32_e32 v164, v164, v136
	v_sub_f32_e32 v163, v163, v136
	v_sub_f32_e32 v162, v162, v136
	v_pk_mul_f32 v[162:163], v[162:163], v[136:137] op_sel:[0,1]
	v_pk_mul_f32 v[164:165], v[164:165], v[136:137] op_sel:[0,1]
	v_pk_fma_f32 v[162:163], v[240:241], v[162:163], v[244:245]
	v_pk_fma_f32 v[164:165], v[242:243], v[164:165], v[246:247]
.Lres_r1_skip27:
	v_pk_mul_f32 v[162:163], v[162:163], s[92:93] op_sel_hi:[1,0]
	v_pk_mul_f32 v[164:165], v[164:165], s[92:93] op_sel_hi:[1,0]
	v_pk_fma_f32 v[114:115], v[114:115], v[198:199], v[162:163]
	v_pk_fma_f32 v[116:117], v[116:117], v[200:201], v[164:165]
	global_store_dwordx4 v220, v[114:117], s[54:55] offset:576
	s_waitcnt vmcnt(14)
	s_cbranch_vccnz .Lres_r1_skip28
	v_sub_f32_e32 v169, v169, v138
	v_sub_f32_e32 v168, v168, v138
	v_sub_f32_e32 v167, v167, v138
	v_sub_f32_e32 v166, v166, v138
	v_pk_mul_f32 v[166:167], v[166:167], v[138:139] op_sel:[0,1]
	v_pk_mul_f32 v[168:169], v[168:169], v[138:139] op_sel:[0,1]
	v_pk_fma_f32 v[166:167], v[240:241], v[166:167], v[244:245]
	v_pk_fma_f32 v[168:169], v[242:243], v[168:169], v[246:247]
.Lres_r1_skip28:
	v_pk_mul_f32 v[166:167], v[166:167], s[92:93] op_sel_hi:[1,0]
	v_pk_mul_f32 v[168:169], v[168:169], s[92:93] op_sel_hi:[1,0]
	v_pk_fma_f32 v[122:123], v[122:123], v[198:199], v[166:167]
	v_pk_fma_f32 v[124:125], v[124:125], v[200:201], v[168:169]
	global_store_dwordx4 v221, v[122:125], s[54:55] offset:576
	s_waitcnt vmcnt(13)
	s_cbranch_vccnz .Lres_r1_skip29
	v_sub_f32_e32 v173, v173, v140
	v_sub_f32_e32 v172, v172, v140
	v_sub_f32_e32 v171, v171, v140
	v_sub_f32_e32 v170, v170, v140
	v_pk_mul_f32 v[170:171], v[170:171], v[140:141] op_sel:[0,1]
	v_pk_mul_f32 v[172:173], v[172:173], v[140:141] op_sel:[0,1]
	v_pk_fma_f32 v[170:171], v[240:241], v[170:171], v[244:245]
	v_pk_fma_f32 v[172:173], v[242:243], v[172:173], v[246:247]
;   __device__ __forceinline__ void operator()(f32x4 (&acc)[2][2][4][2], int pm, int pn, int wr_, int wc_, int fr_, int fq_, bf16_t* shm, int tid) const {
;     ...
;         for (int ai = 0; ai < 2; ++ai)
; #pragma unroll
;           for (int m = 0; m < 4; ++m) {
;             const int row = pm * 256 + ai * 128 + wr * 64 + m * 16 + fr;
;             const f32x4 v = acc[ai][bj][m][n];
;             f32x4* xp = (f32x4*)(X + (long)row * DM + col);
;             f32x4 xv = *(const f32x4*)(Xr + (long)row * DM + col);
;             if (stats) { const float mu = stats[2 * row], rs = stats[2 * row + 1]; xv = (xv - mu) * rs * lg + lb; }
;             xv = xv * ALPHA + gv * v; *xp = xv;
;             acc[ai][bj][m][n] = xv;
;             s1[ai * 4 + m] += (xv[0] + xv[1]) + (xv[2] + xv[3]);
;             s2[ai * 4 + m] += (xv[0] * xv[0] + xv[1] * xv[1]) + (xv[2] * xv[2] + xv[3] * xv[3]);
;           }
;       }
; #pragma unroll
;     for (int i = 0; i < 8; ++i) {
;       s1[i] += __shfl_xor(s1[i], 16); s1[i] += __shfl_xor(s1[i], 32);
;       s2[i] += __shfl_xor(s2[i], 16); s2[i] += __shfl_xor(s2[i], 32);
;       if (fq == 0) red[((i >> 2) * 128 + wr * 64 + (i & 3) * 16 + fr) * 4 + wc] = (f2_t){s1[i], s2[i]};
.Lres_r1_skip29:
	v_pk_mul_f32 v[170:171], v[170:171], s[92:93] op_sel_hi:[1,0]
	v_pk_mul_f32 v[172:173], v[172:173], s[92:93] op_sel_hi:[1,0]
	v_pk_fma_f32 v[126:127], v[126:127], v[198:199], v[170:171]
	v_pk_fma_f32 v[128:129], v[128:129], v[200:201], v[172:173]
	global_store_dwordx4 v222, v[126:129], s[54:55] offset:576
	s_waitcnt vmcnt(12)
	s_cbranch_vccnz .Lres_r1_skip30
	v_sub_f32_e32 v177, v177, v142
	v_sub_f32_e32 v176, v176, v142
	v_sub_f32_e32 v175, v175, v142
	v_sub_f32_e32 v174, v174, v142
	v_pk_mul_f32 v[174:175], v[174:175], v[142:143] op_sel:[0,1]
	v_pk_mul_f32 v[176:177], v[176:177], v[142:143] op_sel:[0,1]
	v_pk_fma_f32 v[174:175], v[240:241], v[174:175], v[244:245]
	v_pk_fma_f32 v[176:177], v[242:243], v[176:177], v[246:247]
.Lres_r1_skip30:
	v_pk_mul_f32 v[174:175], v[174:175], s[92:93] op_sel_hi:[1,0]
	v_pk_mul_f32 v[176:177], v[176:177], s[92:93] op_sel_hi:[1,0]
	v_pk_fma_f32 v[118:119], v[118:119], v[198:199], v[174:175]
	v_pk_fma_f32 v[120:121], v[120:121], v[200:201], v[176:177]
	global_store_dwordx4 v223, v[118:121], s[54:55] offset:576
	s_waitcnt vmcnt(11)
	s_cbranch_vccnz .Lres_r1_skip31
	v_sub_f32_e32 v181, v181, v144
	v_sub_f32_e32 v180, v180, v144
	v_sub_f32_e32 v179, v179, v144
	v_sub_f32_e32 v178, v178, v144
	v_pk_mul_f32 v[178:179], v[178:179], v[144:145] op_sel:[0,1]
	v_pk_mul_f32 v[180:181], v[180:181], v[144:145] op_sel:[0,1]
	v_pk_fma_f32 v[178:179], v[240:241], v[178:179], v[244:245]
	v_pk_fma_f32 v[180:181], v[242:243], v[180:181], v[246:247]
.Lres_r1_skip31:
	v_pk_mul_f32 v[178:179], v[178:179], s[92:93] op_sel_hi:[1,0]
	v_pk_mul_f32 v[180:181], v[180:181], s[92:93] op_sel_hi:[1,0]
	v_pk_fma_f32 v[94:95], v[94:95], v[198:199], v[178:179]
	v_pk_fma_f32 v[96:97], v[96:97], v[200:201], v[180:181]
	global_store_dwordx4 v224, v[94:97], s[54:55] offset:576
.LBB0_200:
	v_mov_b32_e32 v134, v4
	v_mov_b32_e32 v135, v2
	v_mov_b32_e32 v136, v5
	v_mov_b32_e32 v137, v2
	v_pk_add_f32 v[138:139], v[134:135], v[136:137]
	v_pk_mul_f32 v[134:135], v[134:135], v[136:137]
	v_pk_mul_f32 v[136:137], v[2:3], v[2:3]
	v_mov_b32_e32 v139, v135
	v_pk_add_f32 v[134:135], v[2:3], v[2:3] op_sel:[1,0]
	v_mul_f32_e32 v136, v4, v4
	v_mov_b32_e32 v135, v137
	v_pk_fma_f32 v[136:137], v[4:5], v[4:5], v[136:137] op_sel_hi:[1,1,0]
	v_pk_add_f32 v[134:135], v[134:135], v[138:139]
	v_mov_b32_e32 v136, v1
	v_pk_add_f32 v[134:135], v[134:135], v[136:137]
	v_mul_f32_e32 v137, v30, v30
	v_mul_f32_e32 v139, v31, v31
	v_mul_f32_e32 v141, v32, v32
	v_mul_f32_e32 v153, v33, v33
	v_mov_b32_e32 v136, v30
	v_mov_b32_e32 v138, v31
	v_mov_b32_e32 v140, v32
	v_mov_b32_e32 v152, v33
	v_pk_add_f32 v[136:137], v[136:137], v[138:139]
	v_pk_add_f32 v[138:139], v[140:141], v[152:153]
	v_mul_f32_e32 v141, v64, v64
	v_pk_add_f32 v[136:137], v[136:137], v[138:139]
	v_mul_f32_e32 v139, v63, v63
	v_pk_add_f32 v[134:135], v[134:135], v[136:137]
	v_mul_f32_e32 v137, v62, v62
	v_mul_f32_e32 v153, v65, v65
	v_mov_b32_e32 v136, v62
	v_mov_b32_e32 v138, v63
	v_mov_b32_e32 v140, v64
	v_mov_b32_e32 v152, v65
	v_pk_add_f32 v[136:137], v[136:137], v[138:139]
	v_pk_add_f32 v[138:139], v[140:141], v[152:153]
	v_mul_f32_e32 v141, v100, v100
	v_pk_add_f32 v[136:137], v[136:137], v[138:139]
	v_mul_f32_e32 v139, v99, v99
	v_pk_add_f32 v[134:135], v[134:135], v[136:137]
	v_mul_f32_e32 v137, v98, v98
	v_mul_f32_e32 v153, v101, v101
	v_mov_b32_e32 v136, v98
	v_mov_b32_e32 v138, v99
	v_mov_b32_e32 v140, v100
	v_mov_b32_e32 v152, v101
	v_pk_add_f32 v[136:137], v[136:137], v[138:139]
	v_pk_add_f32 v[138:139], v[140:141], v[152:153]
	v_readlane_b32 s6, v253, 26
	v_pk_add_f32 v[136:137], v[136:137], v[138:139]
	v_pk_add_f32 v[136:137], v[134:135], v[136:137]
	v_and_b32_e32 v131, 64, v226
	v_xor_b32_e32 v130, 16, v226
	v_add_u32_e32 v132, 64, v131
	v_cmp_lt_i32_e32 vcc, v130, v132
	v_xor_b32_e32 v133, 32, v226
	v_or_b32_e32 v154, v214, v149
	v_cndmask_b32_e32 v130, v226, v130, vcc
	v_lshlrev_b32_e32 v134, 2, v130
	ds_bpermute_b32 v130, v134, v136
	ds_bpermute_b32 v131, v134, v137
	v_cmp_lt_i32_e32 vcc, v133, v132
	s_waitcnt lgkmcnt(0)
	v_pk_add_f32 v[130:131], v[136:137], v[130:131]
	v_cndmask_b32_e32 v132, v226, v133, vcc
	v_lshlrev_b32_e32 v135, 2, v132
	ds_bpermute_b32 v132, v135, v130
	ds_bpermute_b32 v133, v135, v131
	v_lshl_add_u32 v136, v215, 3, s6
	v_cmp_eq_u32_e32 vcc, 0, v216
	v_lshl_add_u32 v137, v154, 5, v136
	s_and_saveexec_b64 s[6:7], vcc
	s_cbranch_execz .LBB0_202
	s_waitcnt lgkmcnt(0)
	v_pk_add_f32 v[130:131], v[130:131], v[132:133]
	ds_write_b64 v137, v[130:131]

;   __device__ __forceinline__ void operator()(f32x4 (&acc)[2][2][4][2], int pm, int pn, int wr_, int wc_, int fr_, int fq_, bf16_t* shm, int tid) const {
;     ...
; #pragma unroll
;     for (int bj = 0; bj < 2; ++bj)
; #pragma unroll
;       for (int n = 0; n < 2; ++n) {
;         asm volatile("" ::: "memory");
;         const int col = pn * 256 + bj * 128 + wc * 32 + n * 16 + fq * 4;
;         const f32x4 gg = *(const f32x4*)(ng + col), bb = *(const f32x4*)(nb + col);
;         f32x4 sh = {0.f, 0.f, 0.f, 0.f}, sc = {0.f, 0.f, 0.f, 0.f};
;         if (!outp) { sh = *(const f32x4*)(msh + bio + col); sc = *(const f32x4*)(msc + bio + col); }
.LBB0_232:
	s_or_b64 exec, exec, s[6:7]
	s_waitcnt lgkmcnt(0)
	s_barrier
	v_lshl_add_u64 v[158:159], s[88:89], 0, v[146:147]
	v_lshl_add_u64 v[160:161], s[66:67], 0, v[146:147]
	global_load_dwordx4 v[134:137], v[158:159], off
	global_load_dwordx4 v[138:141], v[160:161], off
	s_add_u32 s6, s77, s0
	s_addc_u32 s7, s90, s1
	s_add_u32 s0, s76, s0
	v_cndmask_b32_e64 v130, 0, 1, s[12:13]
	s_addc_u32 s1, s23, s1
	v_cmp_ne_u32_e64 s[10:11], 1, v130
	s_andn2_b64 vcc, exec, s[12:13]
	s_cbranch_vccz .LBB0_237
	v_mov_b32_e32 v162, 1.0
	v_mov_b32_e32 v130, 0
	v_mov_b32_e32 v131, v130
	v_mov_b32_e32 v132, v130
	v_mov_b32_e32 v133, v130
	v_mov_b32_e32 v163, v162
	v_mov_b32_e32 v164, v162
	v_mov_b32_e32 v165, v162
	s_branch .LBB0_238
.LBB0_237:
	v_lshl_add_u64 v[130:131], s[6:7], 0, v[146:147]
	global_load_dwordx4 v[142:145], v[130:131], off
	v_lshl_add_u64 v[130:131], s[0:1], 0, v[146:147]
	global_load_dwordx4 v[130:133], v[130:131], off
	s_waitcnt vmcnt(1)
	v_pk_add_f32 v[164:165], v[144:145], 1.0 op_sel_hi:[1,0]
	v_pk_add_f32 v[162:163], v[142:143], 1.0 op_sel_hi:[1,0]

;   __device__ __forceinline__ void operator()(f32x4 (&acc)[2][2][4][2], int pm, int pn, int wr_, int wc_, int fr_, int fq_, bf16_t* shm, int tid) const {
;     ...
;     const float* Xr = (!fdown && l == 0) ? (pm < 256 ? p.x : p.ctx - (long)NLAT * DM) : (const float*)X;
;     const long bio = (long)row_bi(pm * 256) * 6144;
;     f2_t* red = (f2_t*)((char*)shm + 128 * 1024);
;     f2_t* rst = (f2_t*)((char*)shm + 128 * 1024 + 8192);
;     float s1[8], s2[8];
; #pragma unroll
;     for (int i = 0; i < 8; ++i) { s1[i] = 0.f; s2[i] = 0.f; }
; #pragma unroll
;     for (int bj = 0; bj < 2; ++bj)
; #pragma unroll
;       for (int n = 0; n < 2; ++n) {
;         asm volatile("" ::: "memory");
;         const int col = pn * 256 + bj * 128 + wc * 32 + n * 16 + fq * 4;
;         f32x4 lg = {1.f, 1.f, 1.f, 1.f}, lb = {0.f, 0.f, 0.f, 0.f};
;         if (stats) { lg = *(const f32x4*)(lng + col); lb = *(const f32x4*)(lnb + col); }
;         const f32x4 gv = *(const f32x4*)(g + bio + col);
; #pragma unroll
;         for (int ai = 0; ai < 2; ++ai)
; #pragma unroll
;           for (int m = 0; m < 4; ++m) {
;             const int row = pm * 256 + ai * 128 + wr * 64 + m * 16 + fr;
;             const f32x4 v = acc[ai][bj][m][n];
;             f32x4* xp = (f32x4*)(X + (long)row * DM + col);
;             f32x4 xv = *(const f32x4*)(Xr + (long)row * DM + col);
;             if (stats) { const float mu = stats[2 * row], rs = stats[2 * row + 1]; xv = (xv - mu) * rs * lg + lb; }
;             xv = xv * ALPHA + gv * v; *xp = xv;
;             acc[ai][bj][m][n] = xv;
;             s1[ai * 4 + m] += (xv[0] + xv[1]) + (xv[2] + xv[3]);
;             s2[ai * 4 + m] += (xv[0] * xv[0] + xv[1] * xv[1]) + (xv[2] * xv[2] + xv[3] * xv[3]);
;           }
.LBB0_477:
	v_readlane_b32 s1, v250, 0
	s_nop 15
	s_nop 15
	v_mbcnt_lo_u32_b32 v138, -1, 0
	v_mbcnt_hi_u32_b32 v138, -1, v138
	s_lshl_b32 s0, s25, 8
	v_bfe_u32 v244, v138, 4, 2
	v_add_u32_e32 v148, s1, v138
	v_bfe_u32 v243, v148, 6, 2
	v_lshlrev_b32_e32 v0, 5, v243
	v_lshlrev_b32_e32 v130, 2, v244
	v_or3_b32 v0, v0, v130, s0
	v_cndmask_b32_e64 v130, 0, 1, s[66:67]
	v_lshlrev_b64 v[146:147], 2, v[0:1]
	v_cmp_ne_u32_e64 s[8:9], 1, v130
	s_andn2_b64 vcc, exec, s[66:67]
	v_lshl_add_u64 v[150:151], s[84:85], 0, v[146:147]
	v_lshl_add_u64 v[152:153], s[86:87], 0, v[146:147]
	s_cmpk_lt_i32 s4, 0x100
	v_readlane_b32 s44, v252, 49
	v_readlane_b32 s0, v251, 5
	v_readlane_b32 s45, v252, 50
	s_cselect_b32 s5, s44, s0
	v_readlane_b32 s0, v251, 6
	s_cselect_b32 s12, s45, s0
	s_and_b64 s[0:1], s[76:77], exec
	v_readlane_b32 s48, v252, 24
	v_readlane_b32 s49, v252, 25
	s_cselect_b32 s1, s12, s49
	s_cselect_b32 s0, s5, s48
	s_mov_b64 s[52:53], s[0:1]
	s_mov_b64 s[54:55], s[48:49]
	s_min_i32 s5, s82, 0x10000
	s_ashr_i32 s5, s5, 11
	s_mul_hi_i32 s7, s5, 0x1800
	s_mul_i32 s6, s5, 0x1800
	s_lshl_b64 s[6:7], s[6:7], 2
	v_and_b32_e32 v149, 15, v138
	v_ashrrev_i32_e32 v138, 2, v148
	v_and_b32_e32 v242, 0xffffffc0, v138
	v_or_b32_e32 v138, s82, v149
	v_add_u32_e32 v247, v242, v138
	s_add_u32 s50, s22, s6
	s_addc_u32 s51, s23, s7
	s_mov_b64 s[44:45], s[10:11]
	s_and_b64 vcc, exec, s[8:9]
	s_cselect_b32 s44, s54, s44
	s_cselect_b32 s45, s55, s45
	s_cselect_b32 s46, s50, s84
	s_cselect_b32 s47, s51, s85
	s_cselect_b32 s48, s50, s86
	s_cselect_b32 s49, s51, s87
	v_lshlrev_b32_e32 v246, 3, v247
	v_lshlrev_b32_e32 v218, 12, v247
	v_add_u32_e32 v218, v218, v146
	v_add_u32_e32 v219, 0x10000, v218
	v_add_u32_e32 v224, 0x20000, v218
	v_add_u32_e32 v225, 0x30000, v218
	v_add_u32_e32 v227, 0x80000, v218
	v_add_u32_e32 v232, 0x90000, v218
	v_add_u32_e32 v233, 0xa0000, v218
	v_add_u32_e32 v245, 0xb0000, v218
	global_load_dwordx2 v[130:131], v246, s[44:45]
	global_load_dwordx2 v[132:133], v246, s[44:45] offset:128
	global_load_dwordx2 v[134:135], v246, s[44:45] offset:256
	global_load_dwordx2 v[136:137], v246, s[44:45] offset:384
	global_load_dwordx2 v[138:139], v246, s[44:45] offset:1024
	global_load_dwordx2 v[140:141], v246, s[44:45] offset:1152
	global_load_dwordx2 v[142:143], v246, s[44:45] offset:1280
	global_load_dwordx2 v[144:145], v246, s[44:45] offset:1408
	global_load_dwordx4 v[198:201], v146, s[46:47]
	global_load_dwordx4 v[202:205], v146, s[48:49]
	global_load_dwordx4 v[206:209], v146, s[50:51]
	global_load_dwordx4 v[150:153], v218, s[52:53]
	global_load_dwordx4 v[154:157], v219, s[52:53]
	global_load_dwordx4 v[158:161], v224, s[52:53]
	global_load_dwordx4 v[162:165], v225, s[52:53]
	global_load_dwordx4 v[166:169], v227, s[52:53]
	global_load_dwordx4 v[170:173], v232, s[52:53]
	global_load_dwordx4 v[174:177], v233, s[52:53]
	global_load_dwordx4 v[178:181], v245, s[52:53]
	global_load_dwordx4 v[182:185], v218, s[52:53] offset:64
	global_load_dwordx4 v[186:189], v219, s[52:53] offset:64
	global_load_dwordx4 v[190:193], v224, s[52:53] offset:64
	global_load_dwordx4 v[194:197], v225, s[52:53] offset:64
	global_load_dwordx4 v[210:213], v146, s[46:47] offset:64
	global_load_dwordx4 v[214:217], v146, s[48:49] offset:64
	global_load_dwordx4 v[228:231], v146, s[50:51] offset:64
	s_waitcnt vmcnt(14)
	s_cbranch_vccnz .Lres_r2_skip0
	v_sub_f32_e32 v153, v153, v130
	v_sub_f32_e32 v152, v152, v130
	v_sub_f32_e32 v151, v151, v130
	v_sub_f32_e32 v150, v150, v130
	v_pk_mul_f32 v[150:151], v[150:151], v[130:131] op_sel:[0,1]
	v_pk_mul_f32 v[152:153], v[152:153], v[130:131] op_sel:[0,1]
	v_pk_fma_f32 v[150:151], v[198:199], v[150:151], v[202:203]
	v_pk_fma_f32 v[152:153], v[200:201], v[152:153], v[204:205]
.Lres_r2_skip0:
	v_pk_mul_f32 v[150:151], v[150:151], s[92:93] op_sel_hi:[1,0]
	v_pk_mul_f32 v[152:153], v[152:153], s[92:93] op_sel_hi:[1,0]
	v_pk_fma_f32 v[126:127], v[126:127], v[206:207], v[150:151]
	v_pk_fma_f32 v[128:129], v[128:129], v[208:209], v[152:153]
	global_store_dwordx4 v218, v[126:129], s[54:55]
	global_load_dwordx4 v[150:153], v227, s[52:53] offset:64
	s_waitcnt vmcnt(15)
	s_cbranch_vccnz .Lres_r2_skip1
	v_sub_f32_e32 v157, v157, v132
	v_sub_f32_e32 v156, v156, v132
	v_sub_f32_e32 v155, v155, v132
	v_sub_f32_e32 v154, v154, v132
	v_pk_mul_f32 v[154:155], v[154:155], v[132:133] op_sel:[0,1]
	v_pk_mul_f32 v[156:157], v[156:157], v[132:133] op_sel:[0,1]
	v_pk_fma_f32 v[154:155], v[198:199], v[154:155], v[202:203]
	v_pk_fma_f32 v[156:157], v[200:201], v[156:157], v[204:205]
.Lres_r2_skip1:
	v_pk_mul_f32 v[154:155], v[154:155], s[92:93] op_sel_hi:[1,0]
	v_pk_mul_f32 v[156:157], v[156:157], s[92:93] op_sel_hi:[1,0]
	v_pk_fma_f32 v[110:111], v[110:111], v[206:207], v[154:155]
	v_pk_fma_f32 v[112:113], v[112:113], v[208:209], v[156:157]
	global_store_dwordx4 v219, v[110:113], s[54:55]
	global_load_dwordx4 v[154:157], v232, s[52:53] offset:64
	s_waitcnt vmcnt(16)
	s_cbranch_vccnz .Lres_r2_skip2
	v_sub_f32_e32 v161, v161, v134
	v_sub_f32_e32 v160, v160, v134
	v_sub_f32_e32 v159, v159, v134
	v_sub_f32_e32 v158, v158, v134
	v_pk_mul_f32 v[158:159], v[158:159], v[134:135] op_sel:[0,1]
	v_pk_mul_f32 v[160:161], v[160:161], v[134:135] op_sel:[0,1]
	v_pk_fma_f32 v[158:159], v[198:199], v[158:159], v[202:203]
	v_pk_fma_f32 v[160:161], v[200:201], v[160:161], v[204:205]
;   __device__ __forceinline__ void operator()(f32x4 (&acc)[2][2][4][2], int pm, int pn, int wr_, int wc_, int fr_, int fq_, bf16_t* shm, int tid) const {
;     ...
;         for (int ai = 0; ai < 2; ++ai)
; #pragma unroll
;           for (int m = 0; m < 4; ++m) {
;             const int row = pm * 256 + ai * 128 + wr * 64 + m * 16 + fr;
;             const f32x4 v = acc[ai][bj][m][n];
;             f32x4* xp = (f32x4*)(X + (long)row * DM + col);
;             f32x4 xv = *(const f32x4*)(Xr + (long)row * DM + col);
;             if (stats) { const float mu = stats[2 * row], rs = stats[2 * row + 1]; xv = (xv - mu) * rs * lg + lb; }
;             xv = xv * ALPHA + gv * v; *xp = xv;
;             acc[ai][bj][m][n] = xv;
.Lres_r2_skip2:
	v_pk_mul_f32 v[158:159], v[158:159], s[92:93] op_sel_hi:[1,0]
	v_pk_mul_f32 v[160:161], v[160:161], s[92:93] op_sel_hi:[1,0]
	v_pk_fma_f32 v[94:95], v[94:95], v[206:207], v[158:159]
	v_pk_fma_f32 v[96:97], v[96:97], v[208:209], v[160:161]
	global_store_dwordx4 v224, v[94:97], s[54:55]
	global_load_dwordx4 v[158:161], v233, s[52:53] offset:64
	s_waitcnt vmcnt(17)
	s_cbranch_vccnz .Lres_r2_skip3
	v_sub_f32_e32 v165, v165, v136
	v_sub_f32_e32 v164, v164, v136
	v_sub_f32_e32 v163, v163, v136
	v_sub_f32_e32 v162, v162, v136
	v_pk_mul_f32 v[162:163], v[162:163], v[136:137] op_sel:[0,1]
	v_pk_mul_f32 v[164:165], v[164:165], v[136:137] op_sel:[0,1]
	v_pk_fma_f32 v[162:163], v[198:199], v[162:163], v[202:203]
	v_pk_fma_f32 v[164:165], v[200:201], v[164:165], v[204:205]
.Lres_r2_skip3:
	v_pk_mul_f32 v[162:163], v[162:163], s[92:93] op_sel_hi:[1,0]
	v_pk_mul_f32 v[164:165], v[164:165], s[92:93] op_sel_hi:[1,0]
	v_pk_fma_f32 v[2:3], v[2:3], v[206:207], v[162:163]
	v_pk_fma_f32 v[4:5], v[4:5], v[208:209], v[164:165]
	global_store_dwordx4 v225, v[2:5], s[54:55]
	global_load_dwordx4 v[162:165], v245, s[52:53] offset:64
	s_waitcnt vmcnt(18)
	s_cbranch_vccnz .Lres_r2_skip4
	v_sub_f32_e32 v169, v169, v138
	v_sub_f32_e32 v168, v168, v138
	v_sub_f32_e32 v167, v167, v138
	v_sub_f32_e32 v166, v166, v138
	v_pk_mul_f32 v[166:167], v[166:167], v[138:139] op_sel:[0,1]
	v_pk_mul_f32 v[168:169], v[168:169], v[138:139] op_sel:[0,1]
	v_pk_fma_f32 v[166:167], v[198:199], v[166:167], v[202:203]
	v_pk_fma_f32 v[168:169], v[200:201], v[168:169], v[204:205]
.Lres_r2_skip4:
	v_pk_mul_f32 v[166:167], v[166:167], s[92:93] op_sel_hi:[1,0]
	v_pk_mul_f32 v[168:169], v[168:169], s[92:93] op_sel_hi:[1,0]
	v_pk_fma_f32 v[6:7], v[6:7], v[206:207], v[166:167]
	v_pk_fma_f32 v[8:9], v[8:9], v[208:209], v[168:169]
	global_store_dwordx4 v227, v[6:9], s[54:55]
	global_load_dwordx4 v[166:169], v218, s[52:53] offset:512
	s_waitcnt vmcnt(19)
	s_cbranch_vccnz .Lres_r2_skip5
	v_sub_f32_e32 v173, v173, v140
	v_sub_f32_e32 v172, v172, v140
	v_sub_f32_e32 v171, v171, v140
	v_sub_f32_e32 v170, v170, v140
	v_pk_mul_f32 v[170:171], v[170:171], v[140:141] op_sel:[0,1]
	v_pk_mul_f32 v[172:173], v[172:173], v[140:141] op_sel:[0,1]
	v_pk_fma_f32 v[170:171], v[198:199], v[170:171], v[202:203]
	v_pk_fma_f32 v[172:173], v[200:201], v[172:173], v[204:205]
.Lres_r2_skip5:
	v_pk_mul_f32 v[170:171], v[170:171], s[92:93] op_sel_hi:[1,0]
	v_pk_mul_f32 v[172:173], v[172:173], s[92:93] op_sel_hi:[1,0]
	v_pk_fma_f32 v[14:15], v[14:15], v[206:207], v[170:171]
	v_pk_fma_f32 v[16:17], v[16:17], v[208:209], v[172:173]
	global_store_dwordx4 v232, v[14:17], s[54:55]
	global_load_dwordx4 v[170:173], v219, s[52:53] offset:512
	s_waitcnt vmcnt(20)
	s_cbranch_vccnz .Lres_r2_skip6
	v_sub_f32_e32 v177, v177, v142
	v_sub_f32_e32 v176, v176, v142
	v_sub_f32_e32 v175, v175, v142
	v_sub_f32_e32 v174, v174, v142
	v_pk_mul_f32 v[174:175], v[174:175], v[142:143] op_sel:[0,1]
	v_pk_mul_f32 v[176:177], v[176:177], v[142:143] op_sel:[0,1]
	v_pk_fma_f32 v[174:175], v[198:199], v[174:175], v[202:203]
	v_pk_fma_f32 v[176:177], v[200:201], v[176:177], v[204:205]
.Lres_r2_skip6:
	v_pk_mul_f32 v[174:175], v[174:175], s[92:93] op_sel_hi:[1,0]
	v_pk_mul_f32 v[176:177], v[176:177], s[92:93] op_sel_hi:[1,0]
	v_pk_fma_f32 v[30:31], v[30:31], v[206:207], v[174:175]
	v_pk_fma_f32 v[32:33], v[32:33], v[208:209], v[176:177]
	global_store_dwordx4 v233, v[30:33], s[54:55]
	global_load_dwordx4 v[174:177], v224, s[52:53] offset:512
	s_waitcnt vmcnt(21)
	s_cbranch_vccnz .Lres_r2_skip7
	v_sub_f32_e32 v181, v181, v144
	v_sub_f32_e32 v180, v180, v144
	v_sub_f32_e32 v179, v179, v144
	v_sub_f32_e32 v178, v178, v144
	v_pk_mul_f32 v[178:179], v[178:179], v[144:145] op_sel:[0,1]
	v_pk_mul_f32 v[180:181], v[180:181], v[144:145] op_sel:[0,1]
	v_pk_fma_f32 v[178:179], v[198:199], v[178:179], v[202:203]
	v_pk_fma_f32 v[180:181], v[200:201], v[180:181], v[204:205]
.Lres_r2_skip7:
	v_pk_mul_f32 v[178:179], v[178:179], s[92:93] op_sel_hi:[1,0]
	v_pk_mul_f32 v[180:181], v[180:181], s[92:93] op_sel_hi:[1,0]
	v_pk_fma_f32 v[54:55], v[54:55], v[206:207], v[178:179]
	v_pk_fma_f32 v[56:57], v[56:57], v[208:209], v[180:181]
	global_store_dwordx4 v245, v[54:57], s[54:55]
	global_load_dwordx4 v[178:181], v225, s[52:53] offset:512
	global_load_dwordx4 v[198:201], v146, s[46:47] offset:512
	global_load_dwordx4 v[202:205], v146, s[48:49] offset:512
	global_load_dwordx4 v[206:209], v146, s[50:51] offset:512
	s_waitcnt vmcnt(25)
	s_cbranch_vccnz .Lres_r2_skip8
	v_sub_f32_e32 v185, v185, v130
	v_sub_f32_e32 v184, v184, v130
	v_sub_f32_e32 v183, v183, v130
	v_sub_f32_e32 v182, v182, v130
	v_pk_mul_f32 v[182:183], v[182:183], v[130:131] op_sel:[0,1]
	v_pk_mul_f32 v[184:185], v[184:185], v[130:131] op_sel:[0,1]
	v_pk_fma_f32 v[182:183], v[210:211], v[182:183], v[214:215]
	v_pk_fma_f32 v[184:185], v[212:213], v[184:185], v[216:217]
.Lres_r2_skip8:
	v_pk_mul_f32 v[182:183], v[182:183], s[92:93] op_sel_hi:[1,0]
	v_pk_mul_f32 v[184:185], v[184:185], s[92:93] op_sel_hi:[1,0]
	v_pk_fma_f32 v[82:83], v[82:83], v[228:229], v[182:183]
	v_pk_fma_f32 v[84:85], v[84:85], v[230:231], v[184:185]
	global_store_dwordx4 v218, v[82:85], s[54:55] offset:64
	global_load_dwordx4 v[182:185], v227, s[52:53] offset:512
	s_waitcnt vmcnt(26)
	s_cbranch_vccnz .Lres_r2_skip9
	v_sub_f32_e32 v189, v189, v132
	v_sub_f32_e32 v188, v188, v132
	v_sub_f32_e32 v187, v187, v132
	v_sub_f32_e32 v186, v186, v132
	v_pk_mul_f32 v[186:187], v[186:187], v[132:133] op_sel:[0,1]
	v_pk_mul_f32 v[188:189], v[188:189], v[132:133] op_sel:[0,1]
	v_pk_fma_f32 v[186:187], v[210:211], v[186:187], v[214:215]
	v_pk_fma_f32 v[188:189], v[212:213], v[188:189], v[216:217]
;   __device__ __forceinline__ void operator()(f32x4 (&acc)[2][2][4][2], int pm, int pn, int wr_, int wc_, int fr_, int fq_, bf16_t* shm, int tid) const {
;     ...
;     for (int bj = 0; bj < 2; ++bj)
; #pragma unroll
;       for (int n = 0; n < 2; ++n) {
;         asm volatile("" ::: "memory");
;         const int col = pn * 256 + bj * 128 + wc * 32 + n * 16 + fq * 4;
;         f32x4 lg = {1.f, 1.f, 1.f, 1.f}, lb = {0.f, 0.f, 0.f, 0.f};
;         if (stats) { lg = *(const f32x4*)(lng + col); lb = *(const f32x4*)(lnb + col); }
;         const f32x4 gv = *(const f32x4*)(g + bio + col);
; #pragma unroll
;         for (int ai = 0; ai < 2; ++ai)
; #pragma unroll
;           for (int m = 0; m < 4; ++m) {
;             const int row = pm * 256 + ai * 128 + wr * 64 + m * 16 + fr;
;             const f32x4 v = acc[ai][bj][m][n];
;             f32x4* xp = (f32x4*)(X + (long)row * DM + col);
;             f32x4 xv = *(const f32x4*)(Xr + (long)row * DM + col);
;             if (stats) { const float mu = stats[2 * row], rs = stats[2 * row + 1]; xv = (xv - mu) * rs * lg + lb; }
;             xv = xv * ALPHA + gv * v; *xp = xv;
;             acc[ai][bj][m][n] = xv;
;             s1[ai * 4 + m] += (xv[0] + xv[1]) + (xv[2] + xv[3]);
;             s2[ai * 4 + m] += (xv[0] * xv[0] + xv[1] * xv[1]) + (xv[2] * xv[2] + xv[3] * xv[3]);
.Lres_r2_skip9:
	v_pk_mul_f32 v[186:187], v[186:187], s[92:93] op_sel_hi:[1,0]
	v_pk_mul_f32 v[188:189], v[188:189], s[92:93] op_sel_hi:[1,0]
	v_pk_fma_f32 v[86:87], v[86:87], v[228:229], v[186:187]
	v_pk_fma_f32 v[88:89], v[88:89], v[230:231], v[188:189]
	global_store_dwordx4 v219, v[86:89], s[54:55] offset:64
	global_load_dwordx4 v[186:189], v232, s[52:53] offset:512
	s_waitcnt vmcnt(27)
	s_cbranch_vccnz .Lres_r2_skip10
	v_sub_f32_e32 v193, v193, v134
	v_sub_f32_e32 v192, v192, v134
	v_sub_f32_e32 v191, v191, v134
	v_sub_f32_e32 v190, v190, v134
	v_pk_mul_f32 v[190:191], v[190:191], v[134:135] op_sel:[0,1]
	v_pk_mul_f32 v[192:193], v[192:193], v[134:135] op_sel:[0,1]
	v_pk_fma_f32 v[190:191], v[210:211], v[190:191], v[214:215]
	v_pk_fma_f32 v[192:193], v[212:213], v[192:193], v[216:217]
.Lres_r2_skip10:
	v_pk_mul_f32 v[190:191], v[190:191], s[92:93] op_sel_hi:[1,0]
	v_pk_mul_f32 v[192:193], v[192:193], s[92:93] op_sel_hi:[1,0]
	v_pk_fma_f32 v[78:79], v[78:79], v[228:229], v[190:191]
	v_pk_fma_f32 v[80:81], v[80:81], v[230:231], v[192:193]
	global_store_dwordx4 v224, v[78:81], s[54:55] offset:64
	global_load_dwordx4 v[190:193], v233, s[52:53] offset:512
	s_waitcnt vmcnt(28)
	s_cbranch_vccnz .Lres_r2_skip11
	v_sub_f32_e32 v197, v197, v136
	v_sub_f32_e32 v196, v196, v136
	v_sub_f32_e32 v195, v195, v136
	v_sub_f32_e32 v194, v194, v136
	v_pk_mul_f32 v[194:195], v[194:195], v[136:137] op_sel:[0,1]
	v_pk_mul_f32 v[196:197], v[196:197], v[136:137] op_sel:[0,1]
	v_pk_fma_f32 v[194:195], v[210:211], v[194:195], v[214:215]
	v_pk_fma_f32 v[196:197], v[212:213], v[196:197], v[216:217]
.Lres_r2_skip11:
	v_pk_mul_f32 v[194:195], v[194:195], s[92:93] op_sel_hi:[1,0]
	v_pk_mul_f32 v[196:197], v[196:197], s[92:93] op_sel_hi:[1,0]
	v_pk_fma_f32 v[10:11], v[10:11], v[228:229], v[194:195]
	v_pk_fma_f32 v[12:13], v[12:13], v[230:231], v[196:197]
	global_store_dwordx4 v225, v[10:13], s[54:55] offset:64
	global_load_dwordx4 v[194:197], v245, s[52:53] offset:512
	s_waitcnt vmcnt(25)
	s_cbranch_vccnz .Lres_r2_skip12
	v_sub_f32_e32 v153, v153, v138
	v_sub_f32_e32 v152, v152, v138
	v_sub_f32_e32 v151, v151, v138
	v_sub_f32_e32 v150, v150, v138
	v_pk_mul_f32 v[150:151], v[150:151], v[138:139] op_sel:[0,1]
	v_pk_mul_f32 v[152:153], v[152:153], v[138:139] op_sel:[0,1]
	v_pk_fma_f32 v[150:151], v[210:211], v[150:151], v[214:215]
	v_pk_fma_f32 v[152:153], v[212:213], v[152:153], v[216:217]
.Lres_r2_skip12:
	v_pk_mul_f32 v[150:151], v[150:151], s[92:93] op_sel_hi:[1,0]
	v_pk_mul_f32 v[152:153], v[152:153], s[92:93] op_sel_hi:[1,0]
	v_pk_fma_f32 v[18:19], v[18:19], v[228:229], v[150:151]
	v_pk_fma_f32 v[20:21], v[20:21], v[230:231], v[152:153]
	global_store_dwordx4 v227, v[18:21], s[54:55] offset:64
	global_load_dwordx4 v[150:153], v218, s[52:53] offset:576
	s_waitcnt vmcnt(25)
	s_cbranch_vccnz .Lres_r2_skip13
	v_sub_f32_e32 v157, v157, v140
	v_sub_f32_e32 v156, v156, v140
	v_sub_f32_e32 v155, v155, v140
	v_sub_f32_e32 v154, v154, v140
	v_pk_mul_f32 v[154:155], v[154:155], v[140:141] op_sel:[0,1]
	v_pk_mul_f32 v[156:157], v[156:157], v[140:141] op_sel:[0,1]
	v_pk_fma_f32 v[154:155], v[210:211], v[154:155], v[214:215]
	v_pk_fma_f32 v[156:157], v[212:213], v[156:157], v[216:217]
.Lres_r2_skip13:
	v_pk_mul_f32 v[154:155], v[154:155], s[92:93] op_sel_hi:[1,0]
	v_pk_mul_f32 v[156:157], v[156:157], s[92:93] op_sel_hi:[1,0]
	v_pk_fma_f32 v[26:27], v[26:27], v[228:229], v[154:155]
	v_pk_fma_f32 v[28:29], v[28:29], v[230:231], v[156:157]
	global_store_dwordx4 v232, v[26:29], s[54:55] offset:64
	global_load_dwordx4 v[154:157], v219, s[52:53] offset:576
	s_waitcnt vmcnt(25)
	s_cbranch_vccnz .Lres_r2_skip14
	v_sub_f32_e32 v161, v161, v142
	v_sub_f32_e32 v160, v160, v142
	v_sub_f32_e32 v159, v159, v142
	v_sub_f32_e32 v158, v158, v142
	v_pk_mul_f32 v[158:159], v[158:159], v[142:143] op_sel:[0,1]
	v_pk_mul_f32 v[160:161], v[160:161], v[142:143] op_sel:[0,1]
	v_pk_fma_f32 v[158:159], v[210:211], v[158:159], v[214:215]
	v_pk_fma_f32 v[160:161], v[212:213], v[160:161], v[216:217]
.Lres_r2_skip14:
	v_pk_mul_f32 v[158:159], v[158:159], s[92:93] op_sel_hi:[1,0]
	v_pk_mul_f32 v[160:161], v[160:161], s[92:93] op_sel_hi:[1,0]
	v_pk_fma_f32 v[46:47], v[46:47], v[228:229], v[158:159]
	v_pk_fma_f32 v[48:49], v[48:49], v[230:231], v[160:161]
	global_store_dwordx4 v233, v[46:49], s[54:55] offset:64
	global_load_dwordx4 v[158:161], v224, s[52:53] offset:576
	s_waitcnt vmcnt(25)
	s_cbranch_vccnz .Lres_r2_skip15
	v_sub_f32_e32 v165, v165, v144
	v_sub_f32_e32 v164, v164, v144
	v_sub_f32_e32 v163, v163, v144
	v_sub_f32_e32 v162, v162, v144
	v_pk_mul_f32 v[162:163], v[162:163], v[144:145] op_sel:[0,1]
	v_pk_mul_f32 v[164:165], v[164:165], v[144:145] op_sel:[0,1]
	v_pk_fma_f32 v[162:163], v[210:211], v[162:163], v[214:215]
	v_pk_fma_f32 v[164:165], v[212:213], v[164:165], v[216:217]
.Lres_r2_skip15:
	v_pk_mul_f32 v[162:163], v[162:163], s[92:93] op_sel_hi:[1,0]
	v_pk_mul_f32 v[164:165], v[164:165], s[92:93] op_sel_hi:[1,0]
	v_pk_fma_f32 v[66:67], v[66:67], v[228:229], v[162:163]
	v_pk_fma_f32 v[68:69], v[68:69], v[230:231], v[164:165]
	global_store_dwordx4 v245, v[66:69], s[54:55] offset:64
	global_load_dwordx4 v[162:165], v225, s[52:53] offset:576
	global_load_dwordx4 v[210:213], v146, s[46:47] offset:576
	global_load_dwordx4 v[214:217], v146, s[48:49] offset:576
	global_load_dwordx4 v[228:231], v146, s[50:51] offset:576
	s_waitcnt vmcnt(28)
	s_cbranch_vccnz .Lres_r2_skip16
	v_sub_f32_e32 v169, v169, v130
	v_sub_f32_e32 v168, v168, v130
	v_sub_f32_e32 v167, v167, v130
	v_sub_f32_e32 v166, v166, v130
	v_pk_mul_f32 v[166:167], v[166:167], v[130:131] op_sel:[0,1]
	v_pk_mul_f32 v[168:169], v[168:169], v[130:131] op_sel:[0,1]
	v_pk_fma_f32 v[166:167], v[198:199], v[166:167], v[202:203]
	v_pk_fma_f32 v[168:169], v[200:201], v[168:169], v[204:205]
;   __device__ __forceinline__ void operator()(f32x4 (&acc)[2][2][4][2], int pm, int pn, int wr_, int wc_, int fr_, int fq_, bf16_t* shm, int tid) const {
;     ...
;     for (int bj = 0; bj < 2; ++bj)
; #pragma unroll
;       for (int n = 0; n < 2; ++n) {
;         asm volatile("" ::: "memory");
;         const int col = pn * 256 + bj * 128 + wc * 32 + n * 16 + fq * 4;
;         f32x4 lg = {1.f, 1.f, 1.f, 1.f}, lb = {0.f, 0.f, 0.f, 0.f};
;         if (stats) { lg = *(const f32x4*)(lng + col); lb = *(const f32x4*)(lnb + col); }
;         const f32x4 gv = *(const f32x4*)(g + bio + col);
; #pragma unroll
;         for (int ai = 0; ai < 2; ++ai)
; #pragma unroll
;           for (int m = 0; m < 4; ++m) {
;             const int row = pm * 256 + ai * 128 + wr * 64 + m * 16 + fr;
;             const f32x4 v = acc[ai][bj][m][n];
;             f32x4* xp = (f32x4*)(X + (long)row * DM + col);
;             f32x4 xv = *(const f32x4*)(Xr + (long)row * DM + col);
;             if (stats) { const float mu = stats[2 * row], rs = stats[2 * row + 1]; xv = (xv - mu) * rs * lg + lb; }
;             xv = xv * ALPHA + gv * v; *xp = xv;
;             acc[ai][bj][m][n] = xv;
;             s1[ai * 4 + m] += (xv[0] + xv[1]) + (xv[2] + xv[3]);
;             s2[ai * 4 + m] += (xv[0] * xv[0] + xv[1] * xv[1]) + (xv[2] * xv[2] + xv[3] * xv[3]);
.Lres_r2_skip16:
	v_pk_mul_f32 v[166:167], v[166:167], s[92:93] op_sel_hi:[1,0]
	v_pk_mul_f32 v[168:169], v[168:169], s[92:93] op_sel_hi:[1,0]
	v_pk_fma_f32 v[98:99], v[98:99], v[206:207], v[166:167]
	v_pk_fma_f32 v[100:101], v[100:101], v[208:209], v[168:169]
	global_store_dwordx4 v218, v[98:101], s[54:55] offset:512
	global_load_dwordx4 v[166:169], v227, s[52:53] offset:576
	s_waitcnt vmcnt(28)
	s_cbranch_vccnz .Lres_r2_skip17
	v_sub_f32_e32 v173, v173, v132
	v_sub_f32_e32 v172, v172, v132
	v_sub_f32_e32 v171, v171, v132
	v_sub_f32_e32 v170, v170, v132
	v_pk_mul_f32 v[170:171], v[170:171], v[132:133] op_sel:[0,1]
	v_pk_mul_f32 v[172:173], v[172:173], v[132:133] op_sel:[0,1]
	v_pk_fma_f32 v[170:171], v[198:199], v[170:171], v[202:203]
	v_pk_fma_f32 v[172:173], v[200:201], v[172:173], v[204:205]
.Lres_r2_skip17:
	v_pk_mul_f32 v[170:171], v[170:171], s[92:93] op_sel_hi:[1,0]
	v_pk_mul_f32 v[172:173], v[172:173], s[92:93] op_sel_hi:[1,0]
	v_pk_fma_f32 v[102:103], v[102:103], v[206:207], v[170:171]
	v_pk_fma_f32 v[104:105], v[104:105], v[208:209], v[172:173]
	global_store_dwordx4 v219, v[102:105], s[54:55] offset:512
	global_load_dwordx4 v[170:173], v232, s[52:53] offset:576
	s_waitcnt vmcnt(28)
	s_cbranch_vccnz .Lres_r2_skip18
	v_sub_f32_e32 v177, v177, v134
	v_sub_f32_e32 v176, v176, v134
	v_sub_f32_e32 v175, v175, v134
	v_sub_f32_e32 v174, v174, v134
	v_pk_mul_f32 v[174:175], v[174:175], v[134:135] op_sel:[0,1]
	v_pk_mul_f32 v[176:177], v[176:177], v[134:135] op_sel:[0,1]
	v_pk_fma_f32 v[174:175], v[198:199], v[174:175], v[202:203]
	v_pk_fma_f32 v[176:177], v[200:201], v[176:177], v[204:205]
.Lres_r2_skip18:
	v_pk_mul_f32 v[174:175], v[174:175], s[92:93] op_sel_hi:[1,0]
	v_pk_mul_f32 v[176:177], v[176:177], s[92:93] op_sel_hi:[1,0]
	v_pk_fma_f32 v[90:91], v[90:91], v[206:207], v[174:175]
	v_pk_fma_f32 v[92:93], v[92:93], v[208:209], v[176:177]
	global_store_dwordx4 v224, v[90:93], s[54:55] offset:512
	global_load_dwordx4 v[174:177], v233, s[52:53] offset:576
	s_waitcnt vmcnt(28)
	s_cbranch_vccnz .Lres_r2_skip19
	v_sub_f32_e32 v181, v181, v136
	v_sub_f32_e32 v180, v180, v136
	v_sub_f32_e32 v179, v179, v136
	v_sub_f32_e32 v178, v178, v136
	v_pk_mul_f32 v[178:179], v[178:179], v[136:137] op_sel:[0,1]
	v_pk_mul_f32 v[180:181], v[180:181], v[136:137] op_sel:[0,1]
	v_pk_fma_f32 v[178:179], v[198:199], v[178:179], v[202:203]
	v_pk_fma_f32 v[180:181], v[200:201], v[180:181], v[204:205]
.Lres_r2_skip19:
	v_pk_mul_f32 v[178:179], v[178:179], s[92:93] op_sel_hi:[1,0]
	v_pk_mul_f32 v[180:181], v[180:181], s[92:93] op_sel_hi:[1,0]
	v_pk_fma_f32 v[22:23], v[22:23], v[206:207], v[178:179]
	v_pk_fma_f32 v[24:25], v[24:25], v[208:209], v[180:181]
	global_store_dwordx4 v225, v[22:25], s[54:55] offset:512
	global_load_dwordx4 v[178:181], v245, s[52:53] offset:576
	s_waitcnt vmcnt(25)
	s_cbranch_vccnz .Lres_r2_skip20
	v_sub_f32_e32 v185, v185, v138
	v_sub_f32_e32 v184, v184, v138
	v_sub_f32_e32 v183, v183, v138
	v_sub_f32_e32 v182, v182, v138
	v_pk_mul_f32 v[182:183], v[182:183], v[138:139] op_sel:[0,1]
	v_pk_mul_f32 v[184:185], v[184:185], v[138:139] op_sel:[0,1]
	v_pk_fma_f32 v[182:183], v[198:199], v[182:183], v[202:203]
	v_pk_fma_f32 v[184:185], v[200:201], v[184:185], v[204:205]
.Lres_r2_skip20:
	v_pk_mul_f32 v[182:183], v[182:183], s[92:93] op_sel_hi:[1,0]
	v_pk_mul_f32 v[184:185], v[184:185], s[92:93] op_sel_hi:[1,0]
	v_pk_fma_f32 v[34:35], v[34:35], v[206:207], v[182:183]
	v_pk_fma_f32 v[36:37], v[36:37], v[208:209], v[184:185]
	global_store_dwordx4 v227, v[34:37], s[54:55] offset:512
	s_waitcnt vmcnt(24)
	s_cbranch_vccnz .Lres_r2_skip21
	v_sub_f32_e32 v189, v189, v140
	v_sub_f32_e32 v188, v188, v140
	v_sub_f32_e32 v187, v187, v140
	v_sub_f32_e32 v186, v186, v140
	v_pk_mul_f32 v[186:187], v[186:187], v[140:141] op_sel:[0,1]
	v_pk_mul_f32 v[188:189], v[188:189], v[140:141] op_sel:[0,1]
	v_pk_fma_f32 v[186:187], v[198:199], v[186:187], v[202:203]
	v_pk_fma_f32 v[188:189], v[200:201], v[188:189], v[204:205]
.Lres_r2_skip21:
	v_pk_mul_f32 v[186:187], v[186:187], s[92:93] op_sel_hi:[1,0]
	v_pk_mul_f32 v[188:189], v[188:189], s[92:93] op_sel_hi:[1,0]
	v_pk_fma_f32 v[42:43], v[42:43], v[206:207], v[186:187]
	v_pk_fma_f32 v[44:45], v[44:45], v[208:209], v[188:189]
	global_store_dwordx4 v232, v[42:45], s[54:55] offset:512
	s_waitcnt vmcnt(23)
	s_cbranch_vccnz .Lres_r2_skip22
	v_sub_f32_e32 v193, v193, v142
	v_sub_f32_e32 v192, v192, v142
	v_sub_f32_e32 v191, v191, v142
	v_sub_f32_e32 v190, v190, v142
	v_pk_mul_f32 v[190:191], v[190:191], v[142:143] op_sel:[0,1]
	v_pk_mul_f32 v[192:193], v[192:193], v[142:143] op_sel:[0,1]
	v_pk_fma_f32 v[190:191], v[198:199], v[190:191], v[202:203]
	v_pk_fma_f32 v[192:193], v[200:201], v[192:193], v[204:205]
.Lres_r2_skip22:
	v_pk_mul_f32 v[190:191], v[190:191], s[92:93] op_sel_hi:[1,0]
	v_pk_mul_f32 v[192:193], v[192:193], s[92:93] op_sel_hi:[1,0]
	v_pk_fma_f32 v[62:63], v[62:63], v[206:207], v[190:191]
	v_pk_fma_f32 v[64:65], v[64:65], v[208:209], v[192:193]
	global_store_dwordx4 v233, v[62:65], s[54:55] offset:512
	s_waitcnt vmcnt(22)
	s_cbranch_vccnz .Lres_r2_skip23
	v_sub_f32_e32 v197, v197, v144
	v_sub_f32_e32 v196, v196, v144
	v_sub_f32_e32 v195, v195, v144
	v_sub_f32_e32 v194, v194, v144
	v_pk_mul_f32 v[194:195], v[194:195], v[144:145] op_sel:[0,1]
	v_pk_mul_f32 v[196:197], v[196:197], v[144:145] op_sel:[0,1]
	v_pk_fma_f32 v[194:195], v[198:199], v[194:195], v[202:203]
	v_pk_fma_f32 v[196:197], v[200:201], v[196:197], v[204:205]
;   __device__ __forceinline__ void operator()(f32x4 (&acc)[2][2][4][2], int pm, int pn, int wr_, int wc_, int fr_, int fq_, bf16_t* shm, int tid) const {
;     ...
;     for (int bj = 0; bj < 2; ++bj)
; #pragma unroll
;       for (int n = 0; n < 2; ++n) {
;         asm volatile("" ::: "memory");
;         const int col = pn * 256 + bj * 128 + wc * 32 + n * 16 + fq * 4;
;         f32x4 lg = {1.f, 1.f, 1.f, 1.f}, lb = {0.f, 0.f, 0.f, 0.f};
;         if (stats) { lg = *(const f32x4*)(lng + col); lb = *(const f32x4*)(lnb + col); }
;         const f32x4 gv = *(const f32x4*)(g + bio + col);
; #pragma unroll
;         for (int ai = 0; ai < 2; ++ai)
; #pragma unroll
;           for (int m = 0; m < 4; ++m) {
;             const int row = pm * 256 + ai * 128 + wr * 64 + m * 16 + fr;
;             const f32x4 v = acc[ai][bj][m][n];
;             f32x4* xp = (f32x4*)(X + (long)row * DM + col);
;             f32x4 xv = *(const f32x4*)(Xr + (long)row * DM + col);
;             if (stats) { const float mu = stats[2 * row], rs = stats[2 * row + 1]; xv = (xv - mu) * rs * lg + lb; }
;             xv = xv * ALPHA + gv * v; *xp = xv;
;             acc[ai][bj][m][n] = xv;
;             s1[ai * 4 + m] += (xv[0] + xv[1]) + (xv[2] + xv[3]);
;             s2[ai * 4 + m] += (xv[0] * xv[0] + xv[1] * xv[1]) + (xv[2] * xv[2] + xv[3] * xv[3]);
.Lres_r2_skip23:
	v_pk_mul_f32 v[194:195], v[194:195], s[92:93] op_sel_hi:[1,0]
	v_pk_mul_f32 v[196:197], v[196:197], s[92:93] op_sel_hi:[1,0]
	v_pk_fma_f32 v[74:75], v[74:75], v[206:207], v[194:195]
	v_pk_fma_f32 v[76:77], v[76:77], v[208:209], v[196:197]
	global_store_dwordx4 v245, v[74:77], s[54:55] offset:512
	s_waitcnt vmcnt(21)
	s_cbranch_vccnz .Lres_r2_skip24
	v_sub_f32_e32 v153, v153, v130
	v_sub_f32_e32 v152, v152, v130
	v_sub_f32_e32 v151, v151, v130
	v_sub_f32_e32 v150, v150, v130
	v_pk_mul_f32 v[150:151], v[150:151], v[130:131] op_sel:[0,1]
	v_pk_mul_f32 v[152:153], v[152:153], v[130:131] op_sel:[0,1]
	v_pk_fma_f32 v[150:151], v[210:211], v[150:151], v[214:215]
	v_pk_fma_f32 v[152:153], v[212:213], v[152:153], v[216:217]
.Lres_r2_skip24:
	v_pk_mul_f32 v[150:151], v[150:151], s[92:93] op_sel_hi:[1,0]
	v_pk_mul_f32 v[152:153], v[152:153], s[92:93] op_sel_hi:[1,0]
	v_pk_fma_f32 v[114:115], v[114:115], v[228:229], v[150:151]
	v_pk_fma_f32 v[116:117], v[116:117], v[230:231], v[152:153]
	global_store_dwordx4 v218, v[114:117], s[54:55] offset:576
	s_waitcnt vmcnt(20)
	s_cbranch_vccnz .Lres_r2_skip25
	v_sub_f32_e32 v157, v157, v132
	v_sub_f32_e32 v156, v156, v132
	v_sub_f32_e32 v155, v155, v132
	v_sub_f32_e32 v154, v154, v132
	v_pk_mul_f32 v[154:155], v[154:155], v[132:133] op_sel:[0,1]
	v_pk_mul_f32 v[156:157], v[156:157], v[132:133] op_sel:[0,1]
	v_pk_fma_f32 v[154:155], v[210:211], v[154:155], v[214:215]
	v_pk_fma_f32 v[156:157], v[212:213], v[156:157], v[216:217]
.Lres_r2_skip25:
	v_pk_mul_f32 v[154:155], v[154:155], s[92:93] op_sel_hi:[1,0]
	v_pk_mul_f32 v[156:157], v[156:157], s[92:93] op_sel_hi:[1,0]
	v_pk_fma_f32 v[118:119], v[118:119], v[228:229], v[154:155]
	v_pk_fma_f32 v[120:121], v[120:121], v[230:231], v[156:157]
	global_store_dwordx4 v219, v[118:121], s[54:55] offset:576
	s_waitcnt vmcnt(19)
	s_cbranch_vccnz .Lres_r2_skip26
	v_sub_f32_e32 v161, v161, v134
	v_sub_f32_e32 v160, v160, v134
	v_sub_f32_e32 v159, v159, v134
	v_sub_f32_e32 v158, v158, v134
	v_pk_mul_f32 v[158:159], v[158:159], v[134:135] op_sel:[0,1]
	v_pk_mul_f32 v[160:161], v[160:161], v[134:135] op_sel:[0,1]
	v_pk_fma_f32 v[158:159], v[210:211], v[158:159], v[214:215]
	v_pk_fma_f32 v[160:161], v[212:213], v[160:161], v[216:217]
.Lres_r2_skip26:
	v_pk_mul_f32 v[158:159], v[158:159], s[92:93] op_sel_hi:[1,0]
	v_pk_mul_f32 v[160:161], v[160:161], s[92:93] op_sel_hi:[1,0]
	v_pk_fma_f32 v[106:107], v[106:107], v[228:229], v[158:159]
	v_pk_fma_f32 v[108:109], v[108:109], v[230:231], v[160:161]
	global_store_dwordx4 v224, v[106:109], s[54:55] offset:576
	s_waitcnt vmcnt(18)
	s_cbranch_vccnz .Lres_r2_skip27
	v_sub_f32_e32 v165, v165, v136
	v_sub_f32_e32 v164, v164, v136
	v_sub_f32_e32 v163, v163, v136
	v_sub_f32_e32 v162, v162, v136
	v_pk_mul_f32 v[162:163], v[162:163], v[136:137] op_sel:[0,1]
	v_pk_mul_f32 v[164:165], v[164:165], v[136:137] op_sel:[0,1]
	v_pk_fma_f32 v[162:163], v[210:211], v[162:163], v[214:215]
	v_pk_fma_f32 v[164:165], v[212:213], v[164:165], v[216:217]
.Lres_r2_skip27:
	v_pk_mul_f32 v[162:163], v[162:163], s[92:93] op_sel_hi:[1,0]
	v_pk_mul_f32 v[164:165], v[164:165], s[92:93] op_sel_hi:[1,0]
	v_pk_fma_f32 v[38:39], v[38:39], v[228:229], v[162:163]
	v_pk_fma_f32 v[40:41], v[40:41], v[230:231], v[164:165]
	global_store_dwordx4 v225, v[38:41], s[54:55] offset:576
	s_waitcnt vmcnt(14)
	s_cbranch_vccnz .Lres_r2_skip28
	v_sub_f32_e32 v169, v169, v138
	v_sub_f32_e32 v168, v168, v138
	v_sub_f32_e32 v167, v167, v138
	v_sub_f32_e32 v166, v166, v138
	v_pk_mul_f32 v[166:167], v[166:167], v[138:139] op_sel:[0,1]
	v_pk_mul_f32 v[168:169], v[168:169], v[138:139] op_sel:[0,1]
	v_pk_fma_f32 v[166:167], v[210:211], v[166:167], v[214:215]
	v_pk_fma_f32 v[168:169], v[212:213], v[168:169], v[216:217]
.Lres_r2_skip28:
	v_pk_mul_f32 v[166:167], v[166:167], s[92:93] op_sel_hi:[1,0]
	v_pk_mul_f32 v[168:169], v[168:169], s[92:93] op_sel_hi:[1,0]
	v_pk_fma_f32 v[50:51], v[50:51], v[228:229], v[166:167]
	v_pk_fma_f32 v[52:53], v[52:53], v[230:231], v[168:169]
	global_store_dwordx4 v227, v[50:53], s[54:55] offset:576
	s_waitcnt vmcnt(13)
	s_cbranch_vccnz .Lres_r2_skip29
	v_sub_f32_e32 v173, v173, v140
	v_sub_f32_e32 v172, v172, v140
	v_sub_f32_e32 v171, v171, v140
	v_sub_f32_e32 v170, v170, v140
	v_pk_mul_f32 v[170:171], v[170:171], v[140:141] op_sel:[0,1]
	v_pk_mul_f32 v[172:173], v[172:173], v[140:141] op_sel:[0,1]
	v_pk_fma_f32 v[170:171], v[210:211], v[170:171], v[214:215]
	v_pk_fma_f32 v[172:173], v[212:213], v[172:173], v[216:217]
;   __device__ __forceinline__ void operator()(f32x4 (&acc)[2][2][4][2], int pm, int pn, int wr_, int wc_, int fr_, int fq_, bf16_t* shm, int tid) const {
;     ...
; #pragma unroll
;           for (int m = 0; m < 4; ++m) {
;             const int row = pm * 256 + ai * 128 + wr * 64 + m * 16 + fr;
;             const f32x4 v = acc[ai][bj][m][n];
;             f32x4* xp = (f32x4*)(X + (long)row * DM + col);
;             f32x4 xv = *(const f32x4*)(Xr + (long)row * DM + col);
;             if (stats) { const float mu = stats[2 * row], rs = stats[2 * row + 1]; xv = (xv - mu) * rs * lg + lb; }
;             xv = xv * ALPHA + gv * v; *xp = xv;
;             acc[ai][bj][m][n] = xv;
;             s1[ai * 4 + m] += (xv[0] + xv[1]) + (xv[2] + xv[3]);
;             s2[ai * 4 + m] += (xv[0] * xv[0] + xv[1] * xv[1]) + (xv[2] * xv[2] + xv[3] * xv[3]);
;           }
;       }
; #pragma unroll
;     for (int i = 0; i < 8; ++i) {
;       s1[i] += __shfl_xor(s1[i], 16); s1[i] += __shfl_xor(s1[i], 32);
;       s2[i] += __shfl_xor(s2[i], 16); s2[i] += __shfl_xor(s2[i], 32);
;       if (fq == 0) red[((i >> 2) * 128 + wr * 64 + (i & 3) * 16 + fr) * 4 + wc] = (f2_t){s1[i], s2[i]};
.Lres_r2_skip29:
	v_pk_mul_f32 v[170:171], v[170:171], s[92:93] op_sel_hi:[1,0]
	v_pk_mul_f32 v[172:173], v[172:173], s[92:93] op_sel_hi:[1,0]
	v_pk_fma_f32 v[58:59], v[58:59], v[228:229], v[170:171]
	v_pk_fma_f32 v[60:61], v[60:61], v[230:231], v[172:173]
	global_store_dwordx4 v232, v[58:61], s[54:55] offset:576
	s_waitcnt vmcnt(12)
	s_cbranch_vccnz .Lres_r2_skip30
	v_sub_f32_e32 v177, v177, v142
	v_sub_f32_e32 v176, v176, v142
	v_sub_f32_e32 v175, v175, v142
	v_sub_f32_e32 v174, v174, v142
	v_pk_mul_f32 v[174:175], v[174:175], v[142:143] op_sel:[0,1]
	v_pk_mul_f32 v[176:177], v[176:177], v[142:143] op_sel:[0,1]
	v_pk_fma_f32 v[174:175], v[210:211], v[174:175], v[214:215]
	v_pk_fma_f32 v[176:177], v[212:213], v[176:177], v[216:217]
.Lres_r2_skip30:
	v_pk_mul_f32 v[174:175], v[174:175], s[92:93] op_sel_hi:[1,0]
	v_pk_mul_f32 v[176:177], v[176:177], s[92:93] op_sel_hi:[1,0]
	v_pk_fma_f32 v[70:71], v[70:71], v[228:229], v[174:175]
	v_pk_fma_f32 v[72:73], v[72:73], v[230:231], v[176:177]
	global_store_dwordx4 v233, v[70:73], s[54:55] offset:576
	s_waitcnt vmcnt(11)
	s_cbranch_vccnz .Lres_r2_skip31
	v_sub_f32_e32 v181, v181, v144
	v_sub_f32_e32 v180, v180, v144
	v_sub_f32_e32 v179, v179, v144
	v_sub_f32_e32 v178, v178, v144
	v_pk_mul_f32 v[178:179], v[178:179], v[144:145] op_sel:[0,1]
	v_pk_mul_f32 v[180:181], v[180:181], v[144:145] op_sel:[0,1]
	v_pk_fma_f32 v[178:179], v[210:211], v[178:179], v[214:215]
	v_pk_fma_f32 v[180:181], v[212:213], v[180:181], v[216:217]
.Lres_r2_skip31:
	v_pk_mul_f32 v[178:179], v[178:179], s[92:93] op_sel_hi:[1,0]
	v_pk_mul_f32 v[180:181], v[180:181], s[92:93] op_sel_hi:[1,0]
	v_pk_fma_f32 v[122:123], v[122:123], v[228:229], v[178:179]
	v_pk_fma_f32 v[124:125], v[124:125], v[230:231], v[180:181]
	global_store_dwordx4 v245, v[122:125], s[54:55] offset:576
.LBB0_547:
	v_mov_b32_e32 v134, v128
	v_mov_b32_e32 v135, v126
	v_mov_b32_e32 v136, v129
	v_mov_b32_e32 v137, v126
	v_pk_add_f32 v[138:139], v[134:135], v[136:137]
	v_pk_mul_f32 v[134:135], v[134:135], v[136:137]
	v_pk_mul_f32 v[136:137], v[126:127], v[126:127]
	v_mov_b32_e32 v139, v135
	v_pk_add_f32 v[134:135], v[126:127], v[126:127] op_sel:[1,0]
	v_mul_f32_e32 v136, v128, v128
	v_mov_b32_e32 v135, v137
	v_pk_fma_f32 v[136:137], v[128:129], v[128:129], v[136:137] op_sel_hi:[1,1,0]
	v_pk_add_f32 v[134:135], v[134:135], v[138:139]
	v_mov_b32_e32 v136, v1
	v_pk_add_f32 v[134:135], v[134:135], v[136:137]
	v_mul_f32_e32 v137, v82, v82
	v_mul_f32_e32 v139, v83, v83
	v_mul_f32_e32 v141, v84, v84
	v_mul_f32_e32 v151, v85, v85
	v_mov_b32_e32 v136, v82
	v_mov_b32_e32 v138, v83
	v_mov_b32_e32 v140, v84
	v_mov_b32_e32 v150, v85
	v_pk_add_f32 v[136:137], v[136:137], v[138:139]
	v_pk_add_f32 v[138:139], v[140:141], v[150:151]
	v_mul_f32_e32 v141, v100, v100
	v_pk_add_f32 v[136:137], v[136:137], v[138:139]
	v_mul_f32_e32 v139, v99, v99
	v_pk_add_f32 v[134:135], v[134:135], v[136:137]
	v_mul_f32_e32 v137, v98, v98
	v_mul_f32_e32 v151, v101, v101
	v_mov_b32_e32 v136, v98
	v_mov_b32_e32 v138, v99
	v_mov_b32_e32 v140, v100
	v_mov_b32_e32 v150, v101
	v_pk_add_f32 v[136:137], v[136:137], v[138:139]
	v_pk_add_f32 v[138:139], v[140:141], v[150:151]
	v_mul_f32_e32 v141, v116, v116
	v_pk_add_f32 v[136:137], v[136:137], v[138:139]
	v_mul_f32_e32 v139, v115, v115
	v_pk_add_f32 v[134:135], v[134:135], v[136:137]
	v_mul_f32_e32 v137, v114, v114
	v_mul_f32_e32 v151, v117, v117
	v_mov_b32_e32 v136, v114
	v_mov_b32_e32 v138, v115
	v_mov_b32_e32 v140, v116
	v_mov_b32_e32 v150, v117
	v_pk_add_f32 v[136:137], v[136:137], v[138:139]
	v_pk_add_f32 v[138:139], v[140:141], v[150:151]
	v_readlane_b32 s0, v253, 26
	v_pk_add_f32 v[136:137], v[136:137], v[138:139]
	v_pk_add_f32 v[136:137], v[134:135], v[136:137]
	v_and_b32_e32 v131, 64, v226
	v_xor_b32_e32 v130, 16, v226
	v_add_u32_e32 v132, 64, v131
	v_cmp_lt_i32_e32 vcc, v130, v132
	v_xor_b32_e32 v133, 32, v226
	v_cndmask_b32_e32 v130, v226, v130, vcc
	v_lshlrev_b32_e32 v134, 2, v130
	ds_bpermute_b32 v130, v134, v136
	ds_bpermute_b32 v131, v134, v137
	v_cmp_lt_i32_e32 vcc, v133, v132
	v_or_b32_e32 v160, v242, v149
	s_waitcnt lgkmcnt(0)
	v_pk_add_f32 v[130:131], v[136:137], v[130:131]
	v_cndmask_b32_e32 v132, v226, v133, vcc
	v_lshlrev_b32_e32 v135, 2, v132
	ds_bpermute_b32 v132, v135, v130
	ds_bpermute_b32 v133, v135, v131
	v_lshl_add_u32 v136, v243, 3, s0
	v_cmp_eq_u32_e32 vcc, 0, v244
	v_lshl_add_u32 v137, v160, 5, v136
	s_and_saveexec_b64 s[0:1], vcc
	s_cbranch_execz .LBB0_549
	s_waitcnt lgkmcnt(0)
	v_pk_add_f32 v[130:131], v[130:131], v[132:133]
	ds_write_b64 v137, v[130:131]

; __device__ __forceinline__ unsigned pk2(float lo, float hi) { const f2_t v = {lo, hi}; return __builtin_bit_cast(unsigned, __builtin_convertvector(v, bf2_t)); }
;   __device__ __forceinline__ void operator()(f32x4 (&acc)[2][2][4][2], int pm, int pn, int wr_, int wc_, int fr_, int fq_, bf16_t* shm, int tid) const {
;     ...
; #pragma unroll
;     for (int bj = 0; bj < 2; ++bj)
; #pragma unroll
;       for (int n = 0; n < 2; ++n) {
;         asm volatile("" ::: "memory");
;         const int col = pn * 256 + bj * 128 + wc * 32 + n * 16 + fq * 4;
;         const f32x4 gg = *(const f32x4*)(ng + col), bb = *(const f32x4*)(nb + col);
;         f32x4 sh = {0.f, 0.f, 0.f, 0.f}, sc = {0.f, 0.f, 0.f, 0.f};
;         if (!outp) { sh = *(const f32x4*)(msh + bio + col); sc = *(const f32x4*)(msc + bio + col); }
; #pragma unroll
;         for (int ai = 0; ai < 2; ++ai)
; #pragma unroll
;           for (int m = 0; m < 4; ++m) {
;             const int rl = ai * 128 + wr * 64 + m * 16 + fr, row = pm * 256 + rl;
;             const f2_t st = rst[rl];
;             f32x4 y = (acc[ai][bj][m][n] - st[0]) * st[1] * gg + bb;
;             if (outp) { *(f32x4*)(outp + (long)row * DM + col) = y; }
;             else {
;               y = y * (sc + 1.f) + sh;
;               u32x2 w; w.x = pk2(y[0], y[1]); w.y = pk2(y[2], y[3]);
;               *(u32x2*)(H + (long)row * DM + col) = w;
;               if (HA && (rl == 0 || rl == 255)) *(u32x2*)(HA + (long)(pm * 2 + (rl == 255)) * DM + col) = w;
;             }
;           }
.LBB0_609:
	s_or_b64 exec, exec, s[0:1]
	ds_read2_b64 v[18:21], v0 offset0:144 offset1:160
	s_waitcnt lgkmcnt(0)
	v_sub_f32_e32 v23, v59, v18
	v_sub_f32_e32 v22, v58, v18
	v_sub_f32_e32 v25, v61, v18
	v_sub_f32_e32 v24, v60, v18
	v_pk_mul_f32 v[24:25], v[18:19], v[24:25] op_sel:[1,0]
	v_pk_mul_f32 v[18:19], v[18:19], v[22:23] op_sel:[1,0]
	v_pk_fma_f32 v[22:23], v[4:5], v[24:25], v[12:13]
	v_pk_fma_f32 v[18:19], v[2:3], v[18:19], v[10:11]
	v_pk_fma_f32 v[22:23], v[14:15], v[22:23], v[8:9]
	v_pk_fma_f32 v[18:19], v[16:17], v[18:19], v[6:7]
	s_nop 0
	v_cvt_pk_bf16_f32 v18, v18, v19
	v_cvt_pk_bf16_f32 v19, v22, v23
	v_sub_f32_e32 v23, v73, v20
	v_sub_f32_e32 v22, v72, v20
	global_store_dwordx2 v[128:129], v[18:19], off offset:288
	v_sub_f32_e32 v19, v71, v20
	v_sub_f32_e32 v18, v70, v20
	v_pk_mul_f32 v[22:23], v[20:21], v[22:23] op_sel:[1,0]
	v_pk_mul_f32 v[18:19], v[20:21], v[18:19] op_sel:[1,0]
	v_pk_fma_f32 v[20:21], v[4:5], v[22:23], v[12:13]
	ds_read_b64 v[22:23], v0 offset:1408
	v_pk_fma_f32 v[18:19], v[2:3], v[18:19], v[10:11]
	v_pk_fma_f32 v[20:21], v[14:15], v[20:21], v[8:9]
	v_pk_fma_f32 v[18:19], v[16:17], v[18:19], v[6:7]
	s_nop 0
	v_cvt_pk_bf16_f32 v18, v18, v19
	v_cvt_pk_bf16_f32 v19, v20, v21
	global_store_dwordx2 v[30:31], v[18:19], off offset:288
	s_waitcnt lgkmcnt(0)
	v_sub_f32_e32 v19, v123, v22
	v_sub_f32_e32 v18, v122, v22
	v_sub_f32_e32 v21, v125, v22
	v_sub_f32_e32 v20, v124, v22
	v_pk_mul_f32 v[20:21], v[22:23], v[20:21] op_sel:[1,0]
	v_pk_mul_f32 v[18:19], v[22:23], v[18:19] op_sel:[1,0]
	v_pk_fma_f32 v[4:5], v[4:5], v[20:21], v[12:13]
	v_pk_fma_f32 v[2:3], v[2:3], v[18:19], v[10:11]
	v_pk_fma_f32 v[4:5], v[14:15], v[4:5], v[8:9]
	v_pk_fma_f32 v[2:3], v[16:17], v[2:3], v[6:7]
	s_nop 0
	v_cvt_pk_bf16_f32 v2, v2, v3
	v_cvt_pk_bf16_f32 v3, v4, v5
	global_store_dwordx2 v[32:33], v[2:3], off offset:288
	s_and_saveexec_b64 s[0:1], vcc
	s_cbranch_execz .LBB0_468
	s_or_b32 s4, s4, 1
	s_ashr_i32 s5, s4, 31
	s_lshl_b64 s[4:5], s[4:5], 11
	v_lshl_add_u64 v[4:5], v[142:143], 0, s[4:5]
	global_store_dwordx2 v[4:5], v[2:3], off offset:288
	s_branch .LBB0_468
.LBB0_614:
	s_mov_b64 s[0:1], 0
	s_barrier

; __device__ __forceinline__ unsigned pk2(float lo, float hi) { const f2_t v = {lo, hi}; return __builtin_bit_cast(unsigned, __builtin_convertvector(v, bf2_t)); }
; #define EPI_LOOP for (int ai = 0; ai < 2; ++ai) for (int bj = 0; bj < 2; ++bj) for (int m = 0; m < 4; ++m) for (int n = 0; n < 2; ++n)
;   __device__ __forceinline__ void operator()(const f32x4 (&acc)[2][2][4][2], int pm, int pn, int wr, int wc, int fr, int fq, bf16_t* shm, int tid) const {
; #pragma unroll
;     EPI_LOOP { EPI_RC
;       const float s = rstd[2 * row] * (0.10206207261596577f * 1.4426950408889634f);
;       u32x2 w; w.x = pk2(v[0] * s, v[1] * s); w.y = pk2(v[2] * s, v[3] * s); *(u32x2*)(Q + (long)row * 768 + col) = w; }
;   }
.LBB0_682:
	v_add_u32_e32 v144, s23, v248
	v_lshlrev_b32_e32 v130, 1, v144
	v_readlane_b32 s40, v253, 7
	v_ashrrev_i32_e32 v131, 31, v130
	v_readlane_b32 s52, v253, 19
	v_readlane_b32 s53, v253, 20
	s_nop 15
	s_nop 15
	v_mbcnt_lo_u32_b32 v0, -1, 0
	v_mbcnt_hi_u32_b32 v0, -1, v0
	v_readlane_b32 s41, v253, 8
	v_or_b32_e32 v132, s12, v249
	v_lshl_add_u64 v[140:141], v[130:131], 2, s[52:53]
	v_mov_b64_e32 v[130:131], s[40:41]
	s_movk_i32 s12, 0x600
	v_ashrrev_i32_e32 v133, 31, v132
	v_mad_i64_i32 v[142:143], s[10:11], v144, s12, v[130:131]
	v_lshlrev_b64 v[132:133], 1, v[132:133]
	v_lshl_add_u64 v[142:143], v[142:143], 0, v[132:133]
	s_andn2_b64 vcc, exec, s[8:9]
	global_load_dword v150, v[140:141], off
	global_load_dword v151, v[140:141], off offset:128
	global_load_dword v152, v[140:141], off offset:256
	global_load_dword v153, v[140:141], off offset:384
	global_load_dword v154, v[140:141], off offset:1024
	global_load_dword v155, v[140:141], off offset:1152
	global_load_dword v156, v[140:141], off offset:1280
	global_load_dword v157, v[140:141], off offset:1408
	s_mov_b32 s43, 0
	s_mov_b32 s42, 0x6000
	v_lshl_add_u64 v[160:161], v[142:143], 0, s[42:43]
	s_mov_b32 s42, 0xc000
	v_lshl_add_u64 v[162:163], v[142:143], 0, s[42:43]
	s_mov_b32 s42, 0x12000
	v_lshl_add_u64 v[164:165], v[142:143], 0, s[42:43]
	s_mov_b32 s42, 0x30000
	v_lshl_add_u64 v[166:167], v[142:143], 0, s[42:43]
	s_mov_b32 s42, 0x36000
	v_lshl_add_u64 v[168:169], v[142:143], 0, s[42:43]
	s_mov_b32 s42, 0x3c000
	v_lshl_add_u64 v[170:171], v[142:143], 0, s[42:43]
	s_mov_b32 s42, 0x42000
	v_lshl_add_u64 v[172:173], v[142:143], 0, s[42:43]
	s_waitcnt vmcnt(0)
	v_mul_f32_e32 v150, 0x3e16c740, v150
	v_mul_f32_e32 v151, 0x3e16c740, v151
	v_mul_f32_e32 v152, 0x3e16c740, v152
	v_mul_f32_e32 v153, 0x3e16c740, v153
	v_mul_f32_e32 v154, 0x3e16c740, v154
	v_mul_f32_e32 v155, 0x3e16c740, v155
	v_mul_f32_e32 v156, 0x3e16c740, v156
	v_mul_f32_e32 v157, 0x3e16c740, v157
	v_pk_mul_f32 v[126:127], v[126:127], v[150:151] op_sel_hi:[1,0]
	v_pk_mul_f32 v[128:129], v[128:129], v[150:151] op_sel_hi:[1,0]
	s_nop 0
	v_cvt_pk_bf16_f32 v126, v126, v127
	v_cvt_pk_bf16_f32 v127, v128, v129
	global_store_dwordx2 v[142:143], v[126:127], off
	v_pk_mul_f32 v[122:123], v[122:123], v[150:151] op_sel_hi:[1,0]
	v_pk_mul_f32 v[124:125], v[124:125], v[150:151] op_sel_hi:[1,0]
	s_nop 0
	v_cvt_pk_bf16_f32 v122, v122, v123
	v_cvt_pk_bf16_f32 v123, v124, v125
	global_store_dwordx2 v[142:143], v[122:123], off offset:32
	v_pk_mul_f32 v[118:119], v[118:119], v[150:151] op_sel:[0,1]
	v_pk_mul_f32 v[120:121], v[120:121], v[150:151] op_sel:[0,1]
	s_nop 0
	v_cvt_pk_bf16_f32 v118, v118, v119
	v_cvt_pk_bf16_f32 v119, v120, v121
	global_store_dwordx2 v[160:161], v[118:119], off
	v_pk_mul_f32 v[114:115], v[114:115], v[150:151] op_sel:[0,1]
	v_pk_mul_f32 v[116:117], v[116:117], v[150:151] op_sel:[0,1]
	s_nop 0
	v_cvt_pk_bf16_f32 v114, v114, v115
	v_cvt_pk_bf16_f32 v115, v116, v117
	global_store_dwordx2 v[160:161], v[114:115], off offset:32
	v_pk_mul_f32 v[110:111], v[110:111], v[152:153] op_sel_hi:[1,0]
	v_pk_mul_f32 v[112:113], v[112:113], v[152:153] op_sel_hi:[1,0]
	s_nop 0
	v_cvt_pk_bf16_f32 v110, v110, v111
	v_cvt_pk_bf16_f32 v111, v112, v113
	global_store_dwordx2 v[162:163], v[110:111], off
	v_pk_mul_f32 v[106:107], v[106:107], v[152:153] op_sel_hi:[1,0]
	v_pk_mul_f32 v[108:109], v[108:109], v[152:153] op_sel_hi:[1,0]
	s_nop 0
	v_cvt_pk_bf16_f32 v106, v106, v107
	v_cvt_pk_bf16_f32 v107, v108, v109
	global_store_dwordx2 v[162:163], v[106:107], off offset:32
	v_pk_mul_f32 v[102:103], v[102:103], v[152:153] op_sel:[0,1]
	v_pk_mul_f32 v[104:105], v[104:105], v[152:153] op_sel:[0,1]
	s_nop 0
	v_cvt_pk_bf16_f32 v102, v102, v103
	v_cvt_pk_bf16_f32 v103, v104, v105
	global_store_dwordx2 v[164:165], v[102:103], off
	v_pk_mul_f32 v[98:99], v[98:99], v[152:153] op_sel:[0,1]
	v_pk_mul_f32 v[100:101], v[100:101], v[152:153] op_sel:[0,1]
	s_nop 0
	v_cvt_pk_bf16_f32 v98, v98, v99
	v_cvt_pk_bf16_f32 v99, v100, v101
	global_store_dwordx2 v[164:165], v[98:99], off offset:32
	v_pk_mul_f32 v[94:95], v[94:95], v[150:151] op_sel_hi:[1,0]
	v_pk_mul_f32 v[96:97], v[96:97], v[150:151] op_sel_hi:[1,0]
	s_nop 0
	v_cvt_pk_bf16_f32 v94, v94, v95
	v_cvt_pk_bf16_f32 v95, v96, v97
	global_store_dwordx2 v[142:143], v[94:95], off offset:256
	v_pk_mul_f32 v[90:91], v[90:91], v[150:151] op_sel_hi:[1,0]
	v_pk_mul_f32 v[92:93], v[92:93], v[150:151] op_sel_hi:[1,0]
	s_nop 0
	v_cvt_pk_bf16_f32 v90, v90, v91
	v_cvt_pk_bf16_f32 v91, v92, v93
	global_store_dwordx2 v[142:143], v[90:91], off offset:288
	v_pk_mul_f32 v[86:87], v[86:87], v[150:151] op_sel:[0,1]
	v_pk_mul_f32 v[88:89], v[88:89], v[150:151] op_sel:[0,1]
	s_nop 0
	v_cvt_pk_bf16_f32 v86, v86, v87
	v_cvt_pk_bf16_f32 v87, v88, v89
	global_store_dwordx2 v[160:161], v[86:87], off offset:256
	v_pk_mul_f32 v[82:83], v[82:83], v[150:151] op_sel:[0,1]
	v_pk_mul_f32 v[84:85], v[84:85], v[150:151] op_sel:[0,1]
	s_nop 0
	v_cvt_pk_bf16_f32 v82, v82, v83
	v_cvt_pk_bf16_f32 v83, v84, v85
	global_store_dwordx2 v[160:161], v[82:83], off offset:288
; __device__ __forceinline__ unsigned pk2(float lo, float hi) { const f2_t v = {lo, hi}; return __builtin_bit_cast(unsigned, __builtin_convertvector(v, bf2_t)); }
; #define EPI_LOOP for (int ai = 0; ai < 2; ++ai) for (int bj = 0; bj < 2; ++bj) for (int m = 0; m < 4; ++m) for (int n = 0; n < 2; ++n)
;   __device__ __forceinline__ void operator()(const f32x4 (&acc)[2][2][4][2], int pm, int pn, int wr, int wc, int fr, int fq, bf16_t* shm, int tid) const {
; #pragma unroll
;     EPI_LOOP { EPI_RC
;       const float s = rstd[2 * row] * (0.10206207261596577f * 1.4426950408889634f);
;       u32x2 w; w.x = pk2(v[0] * s, v[1] * s); w.y = pk2(v[2] * s, v[3] * s); *(u32x2*)(Q + (long)row * 768 + col) = w; }
;   }
	v_pk_mul_f32 v[78:79], v[78:79], v[152:153] op_sel_hi:[1,0]
	v_pk_mul_f32 v[80:81], v[80:81], v[152:153] op_sel_hi:[1,0]
	s_nop 0
	v_cvt_pk_bf16_f32 v78, v78, v79
	v_cvt_pk_bf16_f32 v79, v80, v81
	global_store_dwordx2 v[162:163], v[78:79], off offset:256
	v_pk_mul_f32 v[74:75], v[74:75], v[152:153] op_sel_hi:[1,0]
	v_pk_mul_f32 v[76:77], v[76:77], v[152:153] op_sel_hi:[1,0]
	s_nop 0
	v_cvt_pk_bf16_f32 v74, v74, v75
	v_cvt_pk_bf16_f32 v75, v76, v77
	global_store_dwordx2 v[162:163], v[74:75], off offset:288
	v_pk_mul_f32 v[70:71], v[70:71], v[152:153] op_sel:[0,1]
	v_pk_mul_f32 v[72:73], v[72:73], v[152:153] op_sel:[0,1]
	s_nop 0
	v_cvt_pk_bf16_f32 v70, v70, v71
	v_cvt_pk_bf16_f32 v71, v72, v73
	global_store_dwordx2 v[164:165], v[70:71], off offset:256
	v_pk_mul_f32 v[66:67], v[66:67], v[152:153] op_sel:[0,1]
	v_pk_mul_f32 v[68:69], v[68:69], v[152:153] op_sel:[0,1]
	s_nop 0
	v_cvt_pk_bf16_f32 v66, v66, v67
	v_cvt_pk_bf16_f32 v67, v68, v69
	global_store_dwordx2 v[164:165], v[66:67], off offset:288
	v_pk_mul_f32 v[62:63], v[62:63], v[154:155] op_sel_hi:[1,0]
	v_pk_mul_f32 v[64:65], v[64:65], v[154:155] op_sel_hi:[1,0]
	s_nop 0
	v_cvt_pk_bf16_f32 v62, v62, v63
	v_cvt_pk_bf16_f32 v63, v64, v65
	global_store_dwordx2 v[166:167], v[62:63], off
	v_pk_mul_f32 v[58:59], v[58:59], v[154:155] op_sel_hi:[1,0]
	v_pk_mul_f32 v[60:61], v[60:61], v[154:155] op_sel_hi:[1,0]
	s_nop 0
	v_cvt_pk_bf16_f32 v58, v58, v59
	v_cvt_pk_bf16_f32 v59, v60, v61
	global_store_dwordx2 v[166:167], v[58:59], off offset:32
	v_pk_mul_f32 v[54:55], v[54:55], v[154:155] op_sel:[0,1]
	v_pk_mul_f32 v[56:57], v[56:57], v[154:155] op_sel:[0,1]
	s_nop 0
	v_cvt_pk_bf16_f32 v54, v54, v55
	v_cvt_pk_bf16_f32 v55, v56, v57
	global_store_dwordx2 v[168:169], v[54:55], off
	v_pk_mul_f32 v[50:51], v[50:51], v[154:155] op_sel:[0,1]
	v_pk_mul_f32 v[52:53], v[52:53], v[154:155] op_sel:[0,1]
	s_nop 0
	v_cvt_pk_bf16_f32 v50, v50, v51
	v_cvt_pk_bf16_f32 v51, v52, v53
	global_store_dwordx2 v[168:169], v[50:51], off offset:32
	v_pk_mul_f32 v[46:47], v[46:47], v[156:157] op_sel_hi:[1,0]
	v_pk_mul_f32 v[48:49], v[48:49], v[156:157] op_sel_hi:[1,0]
	s_nop 0
	v_cvt_pk_bf16_f32 v46, v46, v47
	v_cvt_pk_bf16_f32 v47, v48, v49
	global_store_dwordx2 v[170:171], v[46:47], off
	v_pk_mul_f32 v[42:43], v[42:43], v[156:157] op_sel_hi:[1,0]
	v_pk_mul_f32 v[44:45], v[44:45], v[156:157] op_sel_hi:[1,0]
	s_nop 0
	v_cvt_pk_bf16_f32 v42, v42, v43
	v_cvt_pk_bf16_f32 v43, v44, v45
	global_store_dwordx2 v[170:171], v[42:43], off offset:32
	v_pk_mul_f32 v[38:39], v[38:39], v[156:157] op_sel:[0,1]
	v_pk_mul_f32 v[40:41], v[40:41], v[156:157] op_sel:[0,1]
	s_nop 0
	v_cvt_pk_bf16_f32 v38, v38, v39
	v_cvt_pk_bf16_f32 v39, v40, v41
	global_store_dwordx2 v[172:173], v[38:39], off
	v_pk_mul_f32 v[34:35], v[34:35], v[156:157] op_sel:[0,1]
	v_pk_mul_f32 v[36:37], v[36:37], v[156:157] op_sel:[0,1]
	s_nop 0
	v_cvt_pk_bf16_f32 v34, v34, v35
	v_cvt_pk_bf16_f32 v35, v36, v37
	global_store_dwordx2 v[172:173], v[34:35], off offset:32
	v_pk_mul_f32 v[30:31], v[30:31], v[154:155] op_sel_hi:[1,0]
	v_pk_mul_f32 v[32:33], v[32:33], v[154:155] op_sel_hi:[1,0]
	s_nop 0
	v_cvt_pk_bf16_f32 v30, v30, v31
	v_cvt_pk_bf16_f32 v31, v32, v33
	global_store_dwordx2 v[166:167], v[30:31], off offset:256
	v_pk_mul_f32 v[26:27], v[26:27], v[154:155] op_sel_hi:[1,0]
	v_pk_mul_f32 v[28:29], v[28:29], v[154:155] op_sel_hi:[1,0]
	s_nop 0
	v_cvt_pk_bf16_f32 v26, v26, v27
	v_cvt_pk_bf16_f32 v27, v28, v29
	global_store_dwordx2 v[166:167], v[26:27], off offset:288
	v_pk_mul_f32 v[22:23], v[22:23], v[154:155] op_sel:[0,1]
	v_pk_mul_f32 v[24:25], v[24:25], v[154:155] op_sel:[0,1]
	s_nop 0
	v_cvt_pk_bf16_f32 v22, v22, v23
	v_cvt_pk_bf16_f32 v23, v24, v25
	global_store_dwordx2 v[168:169], v[22:23], off offset:256
	v_pk_mul_f32 v[18:19], v[18:19], v[154:155] op_sel:[0,1]
	v_pk_mul_f32 v[20:21], v[20:21], v[154:155] op_sel:[0,1]
	s_nop 0
	v_cvt_pk_bf16_f32 v18, v18, v19
	v_cvt_pk_bf16_f32 v19, v20, v21
	global_store_dwordx2 v[168:169], v[18:19], off offset:288
	v_pk_mul_f32 v[14:15], v[14:15], v[156:157] op_sel_hi:[1,0]
	v_pk_mul_f32 v[16:17], v[16:17], v[156:157] op_sel_hi:[1,0]
	s_nop 0
	v_cvt_pk_bf16_f32 v14, v14, v15
	v_cvt_pk_bf16_f32 v15, v16, v17
	global_store_dwordx2 v[170:171], v[14:15], off offset:256
	v_pk_mul_f32 v[10:11], v[10:11], v[156:157] op_sel_hi:[1,0]
	v_pk_mul_f32 v[12:13], v[12:13], v[156:157] op_sel_hi:[1,0]
	s_nop 0
	v_cvt_pk_bf16_f32 v10, v10, v11
	v_cvt_pk_bf16_f32 v11, v12, v13
	global_store_dwordx2 v[170:171], v[10:11], off offset:288
	v_pk_mul_f32 v[6:7], v[6:7], v[156:157] op_sel:[0,1]
	v_pk_mul_f32 v[8:9], v[8:9], v[156:157] op_sel:[0,1]
	s_nop 0
	v_cvt_pk_bf16_f32 v6, v6, v7
	v_cvt_pk_bf16_f32 v7, v8, v9
	global_store_dwordx2 v[172:173], v[6:7], off offset:256
	v_pk_mul_f32 v[2:3], v[2:3], v[156:157] op_sel:[0,1]
	v_pk_mul_f32 v[4:5], v[4:5], v[156:157] op_sel:[0,1]
	s_nop 0
	v_cvt_pk_bf16_f32 v2, v2, v3
	v_cvt_pk_bf16_f32 v3, v4, v5
	global_store_dwordx2 v[172:173], v[2:3], off offset:288
	s_waitcnt vmcnt(0)
	s_cbranch_vccz .LBB0_691

; __device__ __forceinline__ unsigned pk2(float lo, float hi) { const f2_t v = {lo, hi}; return __builtin_bit_cast(unsigned, __builtin_convertvector(v, bf2_t)); }
; #define EPI_LOOP for (int ai = 0; ai < 2; ++ai) for (int bj = 0; bj < 2; ++bj) for (int m = 0; m < 4; ++m) for (int n = 0; n < 2; ++n)
;   __device__ __forceinline__ void operator()(const f32x4 (&acc)[2][2][4][2], int pm, int pn, int wr_, int wc_, int fr_, int fq_, bf16_t* shm, int tid) const {
;     const int wr = tid >> 8, wc = (tid >> 6) & 3, fr = tid & 15, fq = (tid >> 4) & 3;
; #pragma unroll
;     EPI_LOOP { EPI_RC
;       const float s = rstd[2 * row + 1];
;       int b, key; if (row < NLAT) { b = row >> 11; key = row & 2047; } else { b = (row - NLAT) >> 8; key = 2048 + ((row - NLAT) & 255); }
;       const int h = col >> 6, d = col & 63;
;       u32x2 w; w.x = pk2(v[0] * s, v[1] * s); w.y = pk2(v[2] * s, v[3] * s);
;       *(u32x2*)(Kn + (((long)(b * 8 + h) * 2304 + key) << 6) + d) = w; }
;   }
.LBB0_693:
	v_readlane_b32 s10, v250, 0
	s_nop 15
	s_nop 15
	v_mbcnt_lo_u32_b32 v0, -1, 0
	v_mbcnt_hi_u32_b32 v0, -1, v0
	v_readlane_b32 s16, v253, 7
	v_and_b32_e32 v146, 15, v0
	v_add_u32_e32 v139, s10, v0
	v_ashrrev_i32_e32 v130, 2, v139
	v_and_b32_e32 v130, 0xffffffc0, v130
	v_add_u32_e32 v147, s14, v130
	v_or_b32_e32 v148, v147, v146
	v_lshlrev_b32_e32 v130, 1, v148
	v_ashrrev_i32_e32 v131, 31, v130
	v_readlane_b32 s28, v253, 19
	v_readlane_b32 s29, v253, 20
	v_lshrrev_b32_e32 v0, 2, v0
	v_and_b32_e32 v0, 12, v0
	v_lshl_add_u64 v[132:133], v[130:131], 2, s[28:29]
	v_lshrrev_b32_e32 v130, 1, v139
	s_lshl_b32 s10, s13, 8
	v_and_or_b32 v0, v130, 32, v0
	v_and_or_b32 v139, v130, 64, s10
	v_lshlrev_b32_e32 v130, 1, v0
	v_add_u32_e32 v0, 0xffff0000, v147
	s_movk_i32 s15, 0xcf
	v_lshrrev_b32_e32 v145, 6, v139
	v_ashrrev_i32_e32 v139, 11, v147
	v_bitop3_b32 v140, v147, s15, v146 bitop3:0xc8
	v_lshrrev_b32_e32 v149, 8, v0
	v_cmp_gt_i32_e32 vcc, s63, v148
	s_movk_i32 s16, 0x7cf
	v_or_b32_e32 v0, 0x800, v140
	v_cndmask_b32_e32 v140, v149, v139, vcc
	v_bitop3_b32 v141, v147, s16, v146 bitop3:0xc8
	v_lshlrev_b32_e32 v150, 3, v140
	v_cndmask_b32_e32 v0, v0, v141, vcc
	v_add_u32_e32 v140, v150, v145
	s_movk_i32 s13, 0x900
	v_mad_i64_i32 v[140:141], s[10:11], v140, s13, v[0:1]
	v_readlane_b32 s18, v253, 9
	v_readlane_b32 s19, v253, 10
	v_lshlrev_b64 v[140:141], 7, v[140:141]
	v_mov_b32_e32 v131, v1
	v_lshl_add_u64 v[140:141], s[18:19], 0, v[140:141]
	v_lshl_add_u64 v[140:141], v[140:141], 0, v[130:131]
	global_load_dword v150, v[132:133], off offset:4
	global_load_dword v151, v[132:133], off offset:132
	global_load_dword v152, v[132:133], off offset:260
	global_load_dword v153, v[132:133], off offset:388
	global_load_dword v154, v[132:133], off offset:1028
	global_load_dword v155, v[132:133], off offset:1156
	global_load_dword v156, v[132:133], off offset:1284
	global_load_dword v157, v[132:133], off offset:1412
	s_mov_b32 s45, 0
	s_mov_b32 s44, 0x800
	v_lshl_add_u64 v[160:161], v[140:141], 0, s[44:45]
	s_mov_b32 s44, 0x1000
	v_lshl_add_u64 v[162:163], v[140:141], 0, s[44:45]
	s_mov_b32 s44, 0x1800
	v_lshl_add_u64 v[164:165], v[140:141], 0, s[44:45]
	s_mov_b32 s44, 0x4000
	v_lshl_add_u64 v[166:167], v[140:141], 0, s[44:45]
	s_mov_b32 s44, 0x4800
	v_lshl_add_u64 v[168:169], v[140:141], 0, s[44:45]
	s_mov_b32 s44, 0x5000
	v_lshl_add_u64 v[170:171], v[140:141], 0, s[44:45]
	s_mov_b32 s44, 0x5800
	v_lshl_add_u64 v[172:173], v[140:141], 0, s[44:45]
	s_mov_b32 s44, 0x90000
	v_lshl_add_u64 v[174:175], v[140:141], 0, s[44:45]
	v_lshl_add_u64 v[176:177], v[160:161], 0, s[44:45]
	v_lshl_add_u64 v[178:179], v[162:163], 0, s[44:45]
	v_lshl_add_u64 v[180:181], v[164:165], 0, s[44:45]
	v_lshl_add_u64 v[182:183], v[166:167], 0, s[44:45]
	v_lshl_add_u64 v[184:185], v[168:169], 0, s[44:45]
	v_lshl_add_u64 v[186:187], v[170:171], 0, s[44:45]
	v_lshl_add_u64 v[188:189], v[172:173], 0, s[44:45]
	s_waitcnt vmcnt(0)
	v_pk_mul_f32 v[126:127], v[126:127], v[150:151] op_sel_hi:[1,0]
	v_pk_mul_f32 v[128:129], v[128:129], v[150:151] op_sel_hi:[1,0]
	s_nop 0
	v_cvt_pk_bf16_f32 v126, v126, v127
	v_cvt_pk_bf16_f32 v127, v128, v129
	global_store_dwordx2 v[140:141], v[126:127], off
	v_pk_mul_f32 v[122:123], v[122:123], v[150:151] op_sel_hi:[1,0]
	v_pk_mul_f32 v[124:125], v[124:125], v[150:151] op_sel_hi:[1,0]
	s_nop 0
	v_cvt_pk_bf16_f32 v122, v122, v123
	v_cvt_pk_bf16_f32 v123, v124, v125
	global_store_dwordx2 v[140:141], v[122:123], off offset:32
	v_pk_mul_f32 v[118:119], v[118:119], v[150:151] op_sel:[0,1]
	v_pk_mul_f32 v[120:121], v[120:121], v[150:151] op_sel:[0,1]
	s_nop 0
	v_cvt_pk_bf16_f32 v118, v118, v119
	v_cvt_pk_bf16_f32 v119, v120, v121
	global_store_dwordx2 v[160:161], v[118:119], off
	v_pk_mul_f32 v[114:115], v[114:115], v[150:151] op_sel:[0,1]
	v_pk_mul_f32 v[116:117], v[116:117], v[150:151] op_sel:[0,1]
	s_nop 0
	v_cvt_pk_bf16_f32 v114, v114, v115
	v_cvt_pk_bf16_f32 v115, v116, v117
	global_store_dwordx2 v[160:161], v[114:115], off offset:32
	v_pk_mul_f32 v[110:111], v[110:111], v[152:153] op_sel_hi:[1,0]
	v_pk_mul_f32 v[112:113], v[112:113], v[152:153] op_sel_hi:[1,0]
	s_nop 0
	v_cvt_pk_bf16_f32 v110, v110, v111
	v_cvt_pk_bf16_f32 v111, v112, v113
	global_store_dwordx2 v[162:163], v[110:111], off
	v_pk_mul_f32 v[106:107], v[106:107], v[152:153] op_sel_hi:[1,0]
	v_pk_mul_f32 v[108:109], v[108:109], v[152:153] op_sel_hi:[1,0]
	s_nop 0
	v_cvt_pk_bf16_f32 v106, v106, v107
	v_cvt_pk_bf16_f32 v107, v108, v109
	global_store_dwordx2 v[162:163], v[106:107], off offset:32
	v_pk_mul_f32 v[102:103], v[102:103], v[152:153] op_sel:[0,1]
	v_pk_mul_f32 v[104:105], v[104:105], v[152:153] op_sel:[0,1]
	s_nop 0
	v_cvt_pk_bf16_f32 v102, v102, v103
	v_cvt_pk_bf16_f32 v103, v104, v105
	global_store_dwordx2 v[164:165], v[102:103], off
	v_pk_mul_f32 v[98:99], v[98:99], v[152:153] op_sel:[0,1]
	v_pk_mul_f32 v[100:101], v[100:101], v[152:153] op_sel:[0,1]
	s_nop 0
	v_cvt_pk_bf16_f32 v98, v98, v99
	v_cvt_pk_bf16_f32 v99, v100, v101
	global_store_dwordx2 v[164:165], v[98:99], off offset:32
	v_pk_mul_f32 v[94:95], v[94:95], v[150:151] op_sel_hi:[1,0]
	v_pk_mul_f32 v[96:97], v[96:97], v[150:151] op_sel_hi:[1,0]
	s_nop 0
	v_cvt_pk_bf16_f32 v94, v94, v95
	v_cvt_pk_bf16_f32 v95, v96, v97
	global_store_dwordx2 v[174:175], v[94:95], off
	v_pk_mul_f32 v[90:91], v[90:91], v[150:151] op_sel_hi:[1,0]
	v_pk_mul_f32 v[92:93], v[92:93], v[150:151] op_sel_hi:[1,0]
	s_nop 0
	v_cvt_pk_bf16_f32 v90, v90, v91
	v_cvt_pk_bf16_f32 v91, v92, v93
	global_store_dwordx2 v[174:175], v[90:91], off offset:32
; __device__ __forceinline__ unsigned pk2(float lo, float hi) { const f2_t v = {lo, hi}; return __builtin_bit_cast(unsigned, __builtin_convertvector(v, bf2_t)); }
; #define EPI_LOOP for (int ai = 0; ai < 2; ++ai) for (int bj = 0; bj < 2; ++bj) for (int m = 0; m < 4; ++m) for (int n = 0; n < 2; ++n)
;   __device__ __forceinline__ void operator()(const f32x4 (&acc)[2][2][4][2], int pm, int pn, int wr_, int wc_, int fr_, int fq_, bf16_t* shm, int tid) const {
;     const int wr = tid >> 8, wc = (tid >> 6) & 3, fr = tid & 15, fq = (tid >> 4) & 3;
; #pragma unroll
;     EPI_LOOP { EPI_RC
;       const float s = rstd[2 * row + 1];
;       int b, key; if (row < NLAT) { b = row >> 11; key = row & 2047; } else { b = (row - NLAT) >> 8; key = 2048 + ((row - NLAT) & 255); }
;       const int h = col >> 6, d = col & 63;
;       u32x2 w; w.x = pk2(v[0] * s, v[1] * s); w.y = pk2(v[2] * s, v[3] * s);
;       *(u32x2*)(Kn + (((long)(b * 8 + h) * 2304 + key) << 6) + d) = w; }
;   }
	v_pk_mul_f32 v[86:87], v[86:87], v[150:151] op_sel:[0,1]
	v_pk_mul_f32 v[88:89], v[88:89], v[150:151] op_sel:[0,1]
	s_nop 0
	v_cvt_pk_bf16_f32 v86, v86, v87
	v_cvt_pk_bf16_f32 v87, v88, v89
	global_store_dwordx2 v[176:177], v[86:87], off
	v_pk_mul_f32 v[82:83], v[82:83], v[150:151] op_sel:[0,1]
	v_pk_mul_f32 v[84:85], v[84:85], v[150:151] op_sel:[0,1]
	s_nop 0
	v_cvt_pk_bf16_f32 v82, v82, v83
	v_cvt_pk_bf16_f32 v83, v84, v85
	global_store_dwordx2 v[176:177], v[82:83], off offset:32
	v_pk_mul_f32 v[78:79], v[78:79], v[152:153] op_sel_hi:[1,0]
	v_pk_mul_f32 v[80:81], v[80:81], v[152:153] op_sel_hi:[1,0]
	s_nop 0
	v_cvt_pk_bf16_f32 v78, v78, v79
	v_cvt_pk_bf16_f32 v79, v80, v81
	global_store_dwordx2 v[178:179], v[78:79], off
	v_pk_mul_f32 v[74:75], v[74:75], v[152:153] op_sel_hi:[1,0]
	v_pk_mul_f32 v[76:77], v[76:77], v[152:153] op_sel_hi:[1,0]
	s_nop 0
	v_cvt_pk_bf16_f32 v74, v74, v75
	v_cvt_pk_bf16_f32 v75, v76, v77
	global_store_dwordx2 v[178:179], v[74:75], off offset:32
	v_pk_mul_f32 v[70:71], v[70:71], v[152:153] op_sel:[0,1]
	v_pk_mul_f32 v[72:73], v[72:73], v[152:153] op_sel:[0,1]
	s_nop 0
	v_cvt_pk_bf16_f32 v70, v70, v71
	v_cvt_pk_bf16_f32 v71, v72, v73
	global_store_dwordx2 v[180:181], v[70:71], off
	v_pk_mul_f32 v[66:67], v[66:67], v[152:153] op_sel:[0,1]
	v_pk_mul_f32 v[68:69], v[68:69], v[152:153] op_sel:[0,1]
	s_nop 0
	v_cvt_pk_bf16_f32 v66, v66, v67
	v_cvt_pk_bf16_f32 v67, v68, v69
	global_store_dwordx2 v[180:181], v[66:67], off offset:32
	v_pk_mul_f32 v[62:63], v[62:63], v[154:155] op_sel_hi:[1,0]
	v_pk_mul_f32 v[64:65], v[64:65], v[154:155] op_sel_hi:[1,0]
	s_nop 0
	v_cvt_pk_bf16_f32 v62, v62, v63
	v_cvt_pk_bf16_f32 v63, v64, v65
	global_store_dwordx2 v[166:167], v[62:63], off
	v_pk_mul_f32 v[58:59], v[58:59], v[154:155] op_sel_hi:[1,0]
	v_pk_mul_f32 v[60:61], v[60:61], v[154:155] op_sel_hi:[1,0]
	s_nop 0
	v_cvt_pk_bf16_f32 v58, v58, v59
	v_cvt_pk_bf16_f32 v59, v60, v61
	global_store_dwordx2 v[166:167], v[58:59], off offset:32
	v_pk_mul_f32 v[54:55], v[54:55], v[154:155] op_sel:[0,1]
	v_pk_mul_f32 v[56:57], v[56:57], v[154:155] op_sel:[0,1]
	s_nop 0
	v_cvt_pk_bf16_f32 v54, v54, v55
	v_cvt_pk_bf16_f32 v55, v56, v57
	global_store_dwordx2 v[168:169], v[54:55], off
	v_pk_mul_f32 v[50:51], v[50:51], v[154:155] op_sel:[0,1]
	v_pk_mul_f32 v[52:53], v[52:53], v[154:155] op_sel:[0,1]
	s_nop 0
	v_cvt_pk_bf16_f32 v50, v50, v51
	v_cvt_pk_bf16_f32 v51, v52, v53
	global_store_dwordx2 v[168:169], v[50:51], off offset:32
	v_pk_mul_f32 v[46:47], v[46:47], v[156:157] op_sel_hi:[1,0]
	v_pk_mul_f32 v[48:49], v[48:49], v[156:157] op_sel_hi:[1,0]
	s_nop 0
	v_cvt_pk_bf16_f32 v46, v46, v47
	v_cvt_pk_bf16_f32 v47, v48, v49
	global_store_dwordx2 v[170:171], v[46:47], off
	v_pk_mul_f32 v[42:43], v[42:43], v[156:157] op_sel_hi:[1,0]
	v_pk_mul_f32 v[44:45], v[44:45], v[156:157] op_sel_hi:[1,0]
	s_nop 0
	v_cvt_pk_bf16_f32 v42, v42, v43
	v_cvt_pk_bf16_f32 v43, v44, v45
	global_store_dwordx2 v[170:171], v[42:43], off offset:32
	v_pk_mul_f32 v[38:39], v[38:39], v[156:157] op_sel:[0,1]
	v_pk_mul_f32 v[40:41], v[40:41], v[156:157] op_sel:[0,1]
	s_nop 0
	v_cvt_pk_bf16_f32 v38, v38, v39
	v_cvt_pk_bf16_f32 v39, v40, v41
	global_store_dwordx2 v[172:173], v[38:39], off
	v_pk_mul_f32 v[34:35], v[34:35], v[156:157] op_sel:[0,1]
	v_pk_mul_f32 v[36:37], v[36:37], v[156:157] op_sel:[0,1]
	s_nop 0
	v_cvt_pk_bf16_f32 v34, v34, v35
	v_cvt_pk_bf16_f32 v35, v36, v37
	global_store_dwordx2 v[172:173], v[34:35], off offset:32
	v_pk_mul_f32 v[30:31], v[30:31], v[154:155] op_sel_hi:[1,0]
	v_pk_mul_f32 v[32:33], v[32:33], v[154:155] op_sel_hi:[1,0]
	s_nop 0
	v_cvt_pk_bf16_f32 v30, v30, v31
	v_cvt_pk_bf16_f32 v31, v32, v33
	global_store_dwordx2 v[182:183], v[30:31], off
	v_pk_mul_f32 v[26:27], v[26:27], v[154:155] op_sel_hi:[1,0]
	v_pk_mul_f32 v[28:29], v[28:29], v[154:155] op_sel_hi:[1,0]
	s_nop 0
	v_cvt_pk_bf16_f32 v26, v26, v27
	v_cvt_pk_bf16_f32 v27, v28, v29
	global_store_dwordx2 v[182:183], v[26:27], off offset:32
	v_pk_mul_f32 v[22:23], v[22:23], v[154:155] op_sel:[0,1]
	v_pk_mul_f32 v[24:25], v[24:25], v[154:155] op_sel:[0,1]
	s_nop 0
	v_cvt_pk_bf16_f32 v22, v22, v23
	v_cvt_pk_bf16_f32 v23, v24, v25
	global_store_dwordx2 v[184:185], v[22:23], off
	v_pk_mul_f32 v[18:19], v[18:19], v[154:155] op_sel:[0,1]
	v_pk_mul_f32 v[20:21], v[20:21], v[154:155] op_sel:[0,1]
	s_nop 0
	v_cvt_pk_bf16_f32 v18, v18, v19
	v_cvt_pk_bf16_f32 v19, v20, v21
	global_store_dwordx2 v[184:185], v[18:19], off offset:32
	v_pk_mul_f32 v[14:15], v[14:15], v[156:157] op_sel_hi:[1,0]
	v_pk_mul_f32 v[16:17], v[16:17], v[156:157] op_sel_hi:[1,0]
	s_nop 0
	v_cvt_pk_bf16_f32 v14, v14, v15
	v_cvt_pk_bf16_f32 v15, v16, v17
	global_store_dwordx2 v[186:187], v[14:15], off
	v_pk_mul_f32 v[10:11], v[10:11], v[156:157] op_sel_hi:[1,0]
	v_pk_mul_f32 v[12:13], v[12:13], v[156:157] op_sel_hi:[1,0]
	s_nop 0
	v_cvt_pk_bf16_f32 v10, v10, v11
	v_cvt_pk_bf16_f32 v11, v12, v13
	global_store_dwordx2 v[186:187], v[10:11], off offset:32
	v_pk_mul_f32 v[6:7], v[6:7], v[156:157] op_sel:[0,1]
	v_pk_mul_f32 v[8:9], v[8:9], v[156:157] op_sel:[0,1]
	s_nop 0
	v_cvt_pk_bf16_f32 v6, v6, v7
	v_cvt_pk_bf16_f32 v7, v8, v9
	global_store_dwordx2 v[188:189], v[6:7], off
	v_pk_mul_f32 v[2:3], v[2:3], v[156:157] op_sel:[0,1]
	v_pk_mul_f32 v[4:5], v[4:5], v[156:157] op_sel:[0,1]
	s_nop 0
	v_cvt_pk_bf16_f32 v2, v2, v3
	v_cvt_pk_bf16_f32 v3, v4, v5
	global_store_dwordx2 v[188:189], v[2:3], off offset:32
	s_mov_b32 s13, s12
	s_andn2_b64 vcc, exec, s[8:9]
	s_waitcnt vmcnt(0)
	s_cbranch_vccz .LBB0_702

; __device__ void scanC_phase(const Params& p, int l, bool last, char* shm, int w0) {
;     ...
;   const int tid = otid(), wv = tid >> 6, lane = tid & 63, fr = lane & 15, fq = lane >> 4;
;   const float qscale = 0.17677669529663687f;
;   const int NT = 2 * 32 * 4 * 36, G = gridDim.x;
;   auto nextt = [&](int t) { t += G; while (last && t < NT && (t % 36) < 4) t += G; return t; };
;   ScanPre R;
;   int task = (int)blockIdx.x - G; task = nextt(task);
;   if (task < NT) scan_fetch<true>(p, l, task, tid, R);
;   for (; task < NT;) {
;     const int c = task % 36, h = (task / 36) & 3, b = (task / 144) & 31, mx = task / 4608;
;     const int ntask = nextt(task);
;     float kv[4], qv[4], a[8];
;     __syncthreads();
;     scan_stage1<true>(R, mx, c, tid, lrs, VT, kv, qv);
;     { const int idx = (tid & 255) * 8; *(u32x4*)(ST + (idx >> 5) * SSTR + (tid >> 8) * 32 + (idx & 31)) = R.st; }
;     const u32x4 gw = R.gw;
;     __syncthreads();
;     scan_stage2(R, mx, tid, lrs, tot, a);
;     if (ntask < NT) scan_fetch<true>(p, l, ntask, tid, R);
;     __syncthreads();
;     scan_stage3(tid, tot, bc, a);
;     __syncthreads();
;     { const int s = tid >> 3, d0 = (tid & 7) * 4;
; #pragma unroll
;       for (int dir = 0; dir < 2; ++dir) {
;         const f32x4 bv = *(const f32x4*)(bc + (dir * 64 + s) * 32 + d0);
;         float qx[4], kx[4];
; #pragma unroll
;         for (int j = 0; j < 4; ++j) { qx[j] = qv[j] * qscale * __expf(bv[j]); kx[j] = kv[j] * __expf(-bv[j]); }
;         u32x2 wq, wk; wq.x = pk2(qx[0], qx[1]); wq.y = pk2(qx[2], qx[3]); wk.x = pk2(kx[0], kx[1]); wk.y = pk2(kx[2], kx[3]);
;         *(u32x2*)(QFB + s * SSTR + dir * 32 + d0) = wq; *(u32x2*)(KFB + s * SSTR + dir * 32 + d0) = wk;
;       }
;     }
;     __syncthreads();
; #pragma unroll
;     for (int q = 0; q < 2; ++q) {
;       const int id = wv * 2 + q, tt = id >> 2, ts = id & 3;
;       f32x4 af = {0.f, 0.f, 0.f, 0.f}, ab = {0.f, 0.f, 0.f, 0.f};
;       if (ts <= tt) af = mma16(QFB + tt * 16 * SSTR, KFB + ts * 16 * SSTR, af, fr, fq);
;       if (ts >= tt) ab = mma16(QFB + tt * 16 * SSTR + 32, KFB + ts * 16 * SSTR + 32, ab, fr, fq);
; #pragma unroll
;       for (int j = 0; j < 4; ++j) {
;         const int t = tt * 16 + fq * 4 + j, s = ts * 16 + fr;
;         const float v = (s <= t ? af[j] : 0.f) + (s >= t ? ab[j] : 0.f);
;         ATT[t * SSTR + s] = f2bf(v);
;       }
;     }
;     __syncthreads();
.LBB0_714:
	s_and_b64 vcc, exec, s[4:5]
	s_cbranch_vccnz .LBB0_817
	v_ashrrev_i32_e32 v30, 6, v26
	v_readlane_b32 s18, v254, 38
	v_cmp_lt_i32_e64 s[0:1], 2, v30
	v_readlane_b32 s19, v254, 39
	v_mul_u32_u24_e32 v19, 0x240, v21
	v_writelane_b32 v254, s0, 47
	v_lshlrev_b32_e32 v18, 1, v37
	v_lshlrev_b32_e32 v19, 1, v19
	v_writelane_b32 v254, s1, 48
	v_cmp_gt_i32_e64 s[0:1], 3, v30
	v_add3_u32 v65, 16, v18, v19
	v_add3_u32 v86, 16, v19, v18
	v_writelane_b32 v254, s0, 49
	v_bfe_u32 v19, v26, 2, 6
	s_movk_i32 s14, 0x90
	v_writelane_b32 v254, s1, 50
	v_cmp_lt_i32_e64 s[0:1], 3, v30
	v_lshlrev_b32_e32 v76, 4, v26
	v_mad_u32_u24 v19, v19, s14, 16
	v_writelane_b32 v254, s0, 51
	v_and_b32_e32 v18, 0xffffffc0, v18
	v_and_b32_e32 v27, 48, v76
	v_writelane_b32 v254, s1, 52
	v_cmp_gt_i32_e64 s[0:1], 4, v30
	v_and_b32_e32 v31, 15, v20
	v_bfe_u32 v68, v20, 4, 2
	v_writelane_b32 v254, s0, 53
	v_add3_u32 v87, v19, v18, v27
	v_bfe_u32 v74, v20, 5, 1
	v_writelane_b32 v254, s1, 54
	v_cmp_lt_i32_e64 s[0:1], 4, v30
	v_and_b32_e32 v18, 32, v20
	v_lshlrev_b32_e32 v20, 2, v20
	v_writelane_b32 v254, s0, 55
	v_lshlrev_b32_e32 v28, 7, v37
	v_and_b32_e32 v20, 0x7c, v20
	v_writelane_b32 v254, s1, 56
	v_cmp_gt_i32_e64 s[0:1], 5, v30
	v_add_u32_e32 v69, 16, v28
	v_and_b32_e32 v27, 0xfffffc00, v28
	v_writelane_b32 v254, s0, 57
	v_or_b32_e32 v32, 0x380, v28
	v_lshlrev_b32_e32 v34, 7, v74
	v_writelane_b32 v254, s1, 58
	v_cmp_lt_i32_e64 s[0:1], 5, v30
	v_lshlrev_b32_e32 v28, 13, v74
	v_add_u32_e32 v70, 16, v20
	v_writelane_b32 v254, s0, 59
	v_cmp_ne_u32_e64 s[8:9], 0, v18
	v_and_b32_e32 v18, 0x3fffffdf, v26
	v_writelane_b32 v254, s1, 60
	v_cmp_gt_i32_e64 s[0:1], 6, v30
	v_ashrrev_i32_e32 v66, 8, v26
	v_add_u32_e32 v88, v70, v34
	v_writelane_b32 v254, s0, 61
	v_add_u32_e32 v85, v70, v28
	v_ashrrev_i32_e32 v70, 7, v26
	v_writelane_b32 v254, s1, 62
	v_cmp_lt_i32_e64 s[0:1], 6, v30
	v_lshlrev_b32_e32 v26, 2, v68
	v_cmp_gt_i32_e64 s[22:23], 0, v30
	v_writelane_b32 v254, s0, 63
	v_cmp_lt_i32_e64 s[24:25], 0, v30
	v_cmp_gt_i32_e64 s[26:27], 1, v30
	v_writelane_b32 v255, s1, 0
	v_cmp_gt_i32_e64 s[0:1], 7, v30
	v_cmp_lt_i32_e64 s[28:29], 1, v30
	v_cmp_gt_i32_e64 s[30:31], 2, v30
	v_writelane_b32 v255, s0, 1
	v_lshlrev_b32_e32 v84, 10, v30
	v_lshl_or_b32 v72, v70, 4, v26
	v_writelane_b32 v255, s1, 2
	v_cmp_lt_i32_e64 s[0:1], 7, v30
	v_lshlrev_b32_e32 v30, 1, v30
	v_mul_u32_u24_e32 v26, 0x48, v31
	v_lshlrev_b32_e32 v35, 4, v21
	v_and_b32_e32 v71, 2, v30
	v_lshlrev_b32_e32 v26, 1, v26
	v_lshlrev_b32_e32 v30, 4, v68
	v_writelane_b32 v255, s0, 3
	v_add_u32_e32 v89, v69, v35
	v_mul_lo_u32 v69, v37, s14
	v_add3_u32 v26, 16, v26, v30
	s_movk_i32 s2, 0x900
	v_writelane_b32 v255, s1, 4
	v_add3_u32 v90, 16, v69, v0
	v_mad_u64_u32 v[68:69], s[0:1], v70, s2, v[26:27]
	s_movk_i32 s15, 0x104
	v_cmp_gt_u32_e64 s[4:5], 4, v21
	v_cmp_lt_u32_e64 s[20:21], 3, v21
	v_readlane_b32 s0, v253, 27
	v_mul_lo_u32 v30, v37, s15
	v_lshlrev_b32_e32 v21, 5, v21
	v_add3_u32 v69, s0, v30, v21
	v_and_b32_e32 v30, 64, v226
	v_xor_b32_e32 v21, 1, v226
	v_add_u32_e32 v30, 64, v30
	v_cmp_lt_i32_e32 vcc, v21, v30
	v_mov_b32_e32 v64, v0
	s_ashr_i32 s19, s18, 31
	v_cndmask_b32_e32 v21, v226, v21, vcc
	v_lshlrev_b32_e32 v91, 2, v21
	v_xor_b32_e32 v21, 2, v226
	v_cmp_lt_i32_e32 vcc, v21, v30
	s_lshl_b64 s[12:13], s[18:19], 5
	s_lshl_b64 s[10:11], s[18:19], 14
	v_cndmask_b32_e32 v21, v226, v21, vcc
	v_lshlrev_b32_e32 v92, 2, v21
	v_xor_b32_e32 v21, 4, v226
	v_cmp_lt_i32_e32 vcc, v21, v30
	v_lshl_or_b32 v30, s18, 6, v0
	v_lshl_or_b32 v0, v71, 4, v31
	s_lshl_b64 s[6:7], s[18:19], 10
	v_lshl_add_u32 v73, v31, 2, s0
	v_cndmask_b32_e32 v21, v226, v21, vcc
	s_mov_b32 s0, s18
	v_cmp_lt_i32_e64 s[18:19], v0, v72
	v_lshlrev_b32_e32 v93, 2, v21
	v_or_b32_e32 v21, 1, v72
	v_writelane_b32 v255, s18, 5
	v_or_b32_e32 v75, 2, v72
	v_writelane_b32 v254, s0, 38
	v_writelane_b32 v255, s19, 6
	v_cmp_gt_i32_e64 s[18:19], v0, v21
	v_writelane_b32 v254, s1, 39
	v_cmp_le_i32_e64 s[0:1], v71, v70
	v_writelane_b32 v255, s18, 7
	v_or_b32_e32 v77, 3, v72
	v_writelane_b32 v254, s0, 41
	v_writelane_b32 v255, s19, 8
	v_cmp_gt_i32_e64 s[18:19], v0, v75
	v_writelane_b32 v254, s1, 42
	v_cmp_lt_i32_e64 s[0:1], v71, v70
	v_writelane_b32 v255, s18, 9
	v_lshl_add_u32 v102, v0, 1, 16
	v_writelane_b32 v254, s0, 43
	v_writelane_b32 v255, s19, 10
	v_cmp_lt_i32_e64 s[18:19], v0, v75
	v_writelane_b32 v254, s1, 44
	v_cmp_ge_i32_e64 s[0:1], v71, v70
	v_writelane_b32 v255, s18, 11
	v_readlane_b32 s76, v253, 40
	v_writelane_b32 v254, s0, 45
	v_writelane_b32 v255, s19, 12
	v_cmp_gt_i32_e64 s[18:19], v0, v77
	v_writelane_b32 v254, s1, 46
	v_cmp_gt_i32_e64 s[0:1], v0, v72
	v_writelane_b32 v255, s18, 13
	v_readlane_b32 s80, v253, 44
	v_readlane_b32 s81, v253, 45
	v_writelane_b32 v255, s19, 14
	v_cmp_lt_i32_e64 s[18:19], v0, v77
	v_or_b32_e32 v0, 1, v71
	v_lshl_or_b32 v31, v0, 4, v31
	v_writelane_b32 v255, s18, 15
	s_add_u32 s12, s80, s12
	v_readlane_b32 s44, v252, 49
	v_writelane_b32 v255, s19, 16
	v_cmp_ge_i32_e64 s[18:19], v0, v70
	s_addc_u32 s13, s81, s13
	v_readlane_b32 s58, v252, 63
	v_writelane_b32 v255, s18, 17
	v_readlane_b32 s59, v253, 0
	v_mul_lo_u32 v103, v72, s14
	v_writelane_b32 v255, s19, 18
	v_cmp_lt_i32_e64 s[18:19], v31, v72
	v_cmp_gt_i32_e64 s[66:67], v31, v72
	v_lshl_add_u32 v105, v71, 6, v73
	v_writelane_b32 v255, s18, 19
	v_mul_lo_u32 v107, v72, s15
	v_lshl_add_u32 v108, v0, 6, v73
	v_writelane_b32 v255, s19, 20
	v_cmp_gt_i32_e64 s[18:19], v31, v21
	v_mul_u32_u24_e32 v21, 0x480, v71
	v_lshl_add_u32 v96, v21, 1, v26
	v_writelane_b32 v255, s18, 21
	v_mov_b32_e32 v21, v1
	v_readlane_b32 s77, v253, 41
	v_writelane_b32 v255, s19, 22
	v_cmp_gt_i32_e64 s[18:19], v31, v75
; __device__ __forceinline__ unsigned pk2(float lo, float hi) { const f2_t v = {lo, hi}; return __builtin_bit_cast(unsigned, __builtin_convertvector(v, bf2_t)); }
; __device__ __forceinline__ float bflo(unsigned w) { return __uint_as_float(w << 16); }
; __device__ __forceinline__ float bfhi(unsigned w) { return __uint_as_float(w & 0xffff0000u); }
; __device__ __forceinline__ float silu_f(float v) { return v * __builtin_amdgcn_rcpf(1.f + __expf(-v)); }
; __device__ void scanC_phase(const Params& p, int l, bool last, char* shm, int w0) {
;     ...
;     { const int t = tid >> 3, e0 = (tid & 7) * 8; float o[8]; float s = 0.f;
; #pragma unroll
;       for (int j = 0; j < 8; ++j) { o[j] = O[t * 65 + e0 + j]; s += o[j]; }
;       s += __shfl_xor(s, 1); s += __shfl_xor(s, 2); s += __shfl_xor(s, 4);
;       const float mu = mx == 1 ? s * (1.f / 64.f) : 0.f; float qq = 0.f;
; #pragma unroll
;       for (int j = 0; j < 8; ++j) { o[j] -= mu; qq += o[j] * o[j]; }
;       qq += __shfl_xor(qq, 1); qq += __shfl_xor(qq, 2); qq += __shfl_xor(qq, 4);
;       const float rs = rsqrtf(qq * (1.f / 64.f) + EPS);
;       const int row = chunk_row0(b, c) + t;
;       float r[8];
; #pragma unroll
;       for (int j = 0; j < 8; ++j) {
;         const unsigned w = gw[j >> 1]; const float gt = (j & 1) ? bfhi(w) : bflo(w);
;         float y = o[j] * rs; if (mx == 0) y *= p.gla_g[l * 64 + e0 + j];
;         r[j] = y * silu_f(gt);
;       }
;       u32x4 w; w.x = pk2(r[0], r[1]); w.y = pk2(r[2], r[3]); w.z = pk2(r[4], r[5]); w.w = pk2(r[6], r[7]);
;       *(u32x4*)(p.H + (long)row * 1024 + mx * 256 + h * 64 + e0) = w;
;     }
	v_lshlrev_b32_e32 v0, 4, v74
	v_readlane_b32 s45, v252, 50
	v_writelane_b32 v255, s18, 23
	v_readlane_b32 s46, v252, 51
	v_readlane_b32 s47, v252, 52
	v_readlane_b32 s48, v252, 53
	v_readlane_b32 s49, v252, 54
	v_readlane_b32 s50, v252, 55
	v_readlane_b32 s51, v252, 56
	v_readlane_b32 s52, v252, 57
	v_readlane_b32 s53, v252, 58
	v_readlane_b32 s54, v252, 59
	v_readlane_b32 s55, v252, 60
	v_readlane_b32 s56, v252, 61
	v_readlane_b32 s57, v252, 62
	v_lshl_add_u64 v[72:73], s[58:59], 0, v[20:21]
	s_add_u32 s6, s76, s6
	v_mov_b32_e32 v29, v1
	v_mul_u32_u24_e32 v106, 0x900, v71
	v_mad_u32_u24 v94, v71, s2, v26
	v_writelane_b32 v255, s19, 24
	v_cmp_lt_i32_e64 s[18:19], v31, v75
	v_lshl_add_u64 v[70:71], s[12:13], 0, v[0:1]
	v_lshl_add_u64 v[72:73], v[72:73], 0, s[10:11]
	s_addc_u32 s7, s77, s7
	v_lshlrev_b32_e32 v0, 9, v74
	v_readlane_b32 s44, v253, 7
	v_writelane_b32 v255, s18, 25
	v_lshl_add_u64 v[72:73], v[72:73], 0, v[28:29]
	v_lshl_add_u64 v[28:29], s[6:7], 0, v[0:1]
	v_and_b32_e32 v0, 0xff0, v76
	v_readlane_b32 s45, v253, 8
	v_readlane_b32 s46, v253, 9
	v_readlane_b32 s47, v253, 10
	v_readlane_b32 s48, v253, 11
	v_readlane_b32 s49, v253, 12
	v_readlane_b32 s50, v253, 13
	v_readlane_b32 s51, v253, 14
	v_readlane_b32 s52, v253, 15
	v_readlane_b32 s53, v253, 16
	v_readlane_b32 s54, v253, 17
	v_readlane_b32 s55, v253, 18
	v_readlane_b32 s56, v253, 19
	v_readlane_b32 s57, v253, 20
	v_readlane_b32 s58, v253, 21
	v_readlane_b32 s59, v253, 22
	v_writelane_b32 v255, s19, 26
	v_cmp_gt_i32_e64 s[18:19], v31, v77
	v_cmp_lt_i32_e64 s[42:43], v31, v77
	v_lshl_add_u64 v[76:77], s[52:53], 0, v[0:1]
	v_readlane_b32 s44, v252, 3
	v_lshl_add_u32 v19, v74, 6, 16
	v_lshl_add_u32 v33, v18, 2, 16
	v_xor_b32_e32 v18, 16, v36
	v_lshl_add_u32 v104, v31, 1, 16
	v_writelane_b32 v255, s18, 27
	v_ashrrev_i32_e32 v31, 31, v30
	v_readlane_b32 s78, v253, 42
	v_readlane_b32 s79, v253, 43
	v_readlane_b32 s84, v253, 48
	v_readlane_b32 s85, v253, 49
	v_readlane_b32 s86, v253, 50
	v_readlane_b32 s87, v253, 51
	v_readlane_b32 s88, v253, 52
	v_readlane_b32 s89, v253, 53
	v_readlane_b32 s90, v253, 54
	v_readlane_b32 s91, v253, 55
	v_and_b32_e32 v0, 48, v35
	v_readlane_b32 s48, v252, 7
	v_readlane_b32 s49, v252, 8
	v_ashrrev_i32_e32 v67, 31, v66
	v_add_u32_e32 v95, 0x900, v94
	v_writelane_b32 v255, s19, 28
	v_add_u32_e32 v97, 0x900, v96
	s_mov_b64 s[90:91], s[30:31]
	s_mov_b64 s[88:89], s[28:29]
	s_mov_b64 s[86:87], s[26:27]
	s_mov_b64 s[84:85], s[24:25]
	s_mov_b64 s[76:77], s[20:21]
	v_lshl_add_u64 v[74:75], v[28:29], 0, v[20:21]
	v_lshl_add_u64 v[78:79], v[30:31], 2, s[78:79]
	global_load_dwordx4 v[176:179], v[78:79], off
	global_load_dwordx4 v[180:183], v[78:79], off offset:16
	s_mov_b64 s[78:79], s[22:23]
	v_lshl_add_u64 v[80:81], s[48:49], 0, v[0:1]
	v_add_u32_e32 v98, v19, v27
	v_add_u32_e32 v99, v19, v32
	v_add_u32_e32 v100, v33, v34
	v_lshlrev_b32_e32 v82, 1, v18
	v_add_u32_e32 v101, v85, v84
	v_add_u32_e32 v102, v102, v103
	v_add_u32_e32 v103, v104, v103
	v_add_u32_e32 v104, v105, v107
	v_add_u32_e32 v105, v108, v107
	v_add_u32_e32 v106, v26, v106
	v_readlane_b32 s82, v253, 46
	v_readlane_b32 s83, v253, 47
	v_readlane_b32 s45, v252, 4
	v_readlane_b32 s46, v252, 5
	v_readlane_b32 s47, v252, 6
	v_readlane_b32 s50, v252, 9
	v_readlane_b32 s51, v252, 10
	v_readlane_b32 s52, v252, 11
	v_readlane_b32 s53, v252, 12
	v_readlane_b32 s54, v252, 13
	v_readlane_b32 s55, v252, 14
	v_readlane_b32 s56, v252, 15
	v_readlane_b32 s57, v252, 16
	v_readlane_b32 s58, v252, 17
	v_readlane_b32 s59, v252, 18
	s_branch .LBB0_717
.LBB0_716:
	v_lshlrev_b32_e32 v27, 16, v21
	v_mul_f32_e32 v34, 0xbfb8aa3b, v27
	v_exp_f32_e32 v34, v34
	v_and_b32_e32 v21, 0xffff0000, v21
	s_lshr_b32 s2, s20, 5
	s_add_i32 s2, s2, s21
	v_add_f32_e32 v34, 1.0, v34
	v_rcp_f32_e32 v34, v34
	s_and_b32 s2, s2, 31
	s_lshl_b32 s6, s22, 6
	s_cmp_lt_i32 s22, 4
	v_mul_f32_e32 v27, v34, v27
	v_mul_f32_e32 v27, v27, v33
	v_and_b32_e32 v33, 0xffff0000, v20
	v_mul_f32_e32 v34, 0xbfb8aa3b, v33
	v_exp_f32_e32 v34, v34
	v_lshlrev_b32_e32 v20, 16, v20
	s_cselect_b32 s7, 8, 11
	s_cselect_b32 s12, s63, 0xffffff00
	v_add_f32_e32 v34, 1.0, v34
	v_rcp_f32_e32 v34, v34
	s_lshl_b32 s2, s2, s7
	s_add_i32 s2, s2, s12
	s_add_i32 s2, s2, s6
	v_mul_f32_e32 v33, v34, v33
	v_mul_f32_e32 v29, v33, v29
	v_mul_f32_e32 v33, 0xbfb8aa3b, v20
	v_exp_f32_e32 v33, v33
	s_ashr_i32 s7, s20, 10
	s_add_i32 s7, s7, s21
	v_readlane_b32 s44, v252, 20
	v_add_f32_e32 v33, 1.0, v33
	v_rcp_f32_e32 v33, v33
	v_readlane_b32 s50, v252, 26
	v_readlane_b32 s51, v252, 27
	s_lshl_b32 s6, s7, 8
	v_mul_f32_e32 v20, v33, v20
	v_mul_f32_e32 v20, v20, v28
	v_and_b32_e32 v28, 0xffff0000, v19
	v_mul_f32_e32 v33, 0xbfb8aa3b, v28
	v_exp_f32_e32 v33, v33
	v_lshlrev_b32_e32 v19, 16, v19
	s_ashr_i32 s7, s6, 31
	v_cvt_pk_bf16_f32 v20, v20, v29
	v_add_f32_e32 v33, 1.0, v33
	v_rcp_f32_e32 v33, v33
	s_andn2_b64 vcc, exec, s[10:11]
	v_readlane_b32 s45, v252, 21
	v_readlane_b32 s46, v252, 22
	v_mul_f32_e32 v28, v33, v28
	v_mul_f32_e32 v28, v28, v31
	v_mul_f32_e32 v31, 0xbfb8aa3b, v19
	v_exp_f32_e32 v31, v31
	v_readlane_b32 s47, v252, 23
	v_readlane_b32 s48, v252, 24
	v_readlane_b32 s49, v252, 25
	v_add_f32_e32 v31, 1.0, v31
	v_rcp_f32_e32 v31, v31
	v_readlane_b32 s52, v252, 28
	v_readlane_b32 s53, v252, 29
	v_readlane_b32 s54, v252, 30
	v_mul_f32_e32 v19, v31, v19
	v_mul_f32_e32 v19, v19, v30
	v_and_b32_e32 v30, 0xffff0000, v18
	v_mul_f32_e32 v31, 0xbfb8aa3b, v30
	v_exp_f32_e32 v31, v31
	v_lshlrev_b32_e32 v18, 16, v18
	v_cvt_pk_bf16_f32 v19, v19, v28
	v_readlane_b32 s55, v252, 31
	v_add_f32_e32 v31, 1.0, v31
	v_rcp_f32_e32 v31, v31
	v_readlane_b32 s56, v252, 32
	v_readlane_b32 s57, v252, 33
	v_readlane_b32 s58, v252, 34
	v_mul_f32_e32 v30, v31, v30
	v_mul_f32_e32 v31, 0xbfb8aa3b, v18
	v_exp_f32_e32 v31, v31
	v_mul_f32_e32 v30, v30, v32
	v_readlane_b32 s59, v252, 35
	v_add_f32_e32 v31, 1.0, v31
	v_rcp_f32_e32 v31, v31
	s_nop 0
	v_mul_f32_e32 v18, v31, v18
	v_mul_f32_e32 v0, v18, v0
	v_mul_f32_e32 v18, 0xbfb8aa3b, v21
	v_exp_f32_e32 v18, v18
	s_nop 0
	v_add_f32_e32 v18, 1.0, v18
	v_rcp_f32_e32 v18, v18
	s_nop 0
	v_mul_f32_e32 v18, v18, v21
	v_mul_f32_e32 v21, v18, v26
	v_add_u32_e32 v26, s2, v37
	v_cvt_pk_bf16_f32 v21, v27, v21
	v_ashrrev_i32_e32 v27, 31, v26
	v_lshlrev_b64 v[26:27], 11, v[26:27]
	v_lshl_add_u64 v[26:27], s[50:51], 0, v[26:27]
	s_lshl_b32 s2, s18, 7
	v_lshl_add_u64 v[26:27], s[6:7], 1, v[26:27]
	s_and_b32 s2, s2, 0x180
	v_cvt_pk_bf16_f32 v18, v0, v30
	v_lshl_add_u64 v[26:27], v[26:27], 0, s[2:3]
	v_lshlrev_b32_e32 v0, 1, v64
	v_lshl_add_u64 v[26:27], v[26:27], 0, v[0:1]
	v_mov_b32_e32 v184, v18
	v_mov_b32_e32 v185, v19
	v_mov_b32_e32 v186, v20
	v_mov_b32_e32 v187, v21
	global_store_dwordx4 v[26:27], v[184:187], off
	s_cbranch_vccz .LBB0_817

; __device__ __forceinline__ bf16_t f2bf(float f) { return (bf16_t)(pk2(f, 0.f) & 0xffffu); }
; __device__ __forceinline__ float bflo(unsigned w) { return __uint_as_float(w << 16); }
; __device__ void scanC_phase(const Params& p, int l, bool last, char* shm, int w0) {
;     ...
; #pragma unroll
;     for (int q = 0; q < 2; ++q) {
;       const int id = wv * 2 + q, tt = id >> 2, ts = id & 3;
;       f32x4 af = {0.f, 0.f, 0.f, 0.f}, ab = {0.f, 0.f, 0.f, 0.f};
;       if (ts <= tt) af = mma16(QFB + tt * 16 * SSTR, KFB + ts * 16 * SSTR, af, fr, fq);
;       if (ts >= tt) ab = mma16(QFB + tt * 16 * SSTR + 32, KFB + ts * 16 * SSTR + 32, ab, fr, fq);
; #pragma unroll
;       for (int j = 0; j < 4; ++j) {
;         const int t = tt * 16 + fq * 4 + j, s = ts * 16 + fr;
;         const float v = (s <= t ? af[j] : 0.f) + (s >= t ? ab[j] : 0.f);
;         ATT[t * SSTR + s] = f2bf(v);
;       }
;     }
;     __syncthreads();
; #pragma unroll
;     for (int q = 0; q < 2; ++q) {
;       const int id = wv * 2 + q, tt = id >> 2, et = id & 3;
;       f32x4 acc = {0.f, 0.f, 0.f, 0.f};
; #pragma unroll
;       for (int ks = 0; ks < 2; ++ks) {
;         acc = mma16(ATT + tt * 16 * SSTR + ks * 32, VT + et * 16 * SSTR + ks * 32, acc, fr, fq);
;         acc = mma16(QFB + tt * 16 * SSTR + ks * 32, ST + et * 16 * SSTR + ks * 32, acc, fr, fq);
;       }
; #pragma unroll
;       for (int j = 0; j < 4; ++j) O[(tt * 16 + fq * 4 + j) * 65 + et * 16 + fr] = acc[j];
;     }
;     __syncthreads();
;     { const int t = tid >> 3, e0 = (tid & 7) * 8; float o[8]; float s = 0.f;
; #pragma unroll
;       for (int j = 0; j < 8; ++j) { o[j] = O[t * 65 + e0 + j]; s += o[j]; }
;       s += __shfl_xor(s, 1); s += __shfl_xor(s, 2); s += __shfl_xor(s, 4);
;       const float mu = mx == 1 ? s * (1.f / 64.f) : 0.f; float qq = 0.f;
; #pragma unroll
;       for (int j = 0; j < 8; ++j) { o[j] -= mu; qq += o[j] * o[j]; }
;       qq += __shfl_xor(qq, 1); qq += __shfl_xor(qq, 2); qq += __shfl_xor(qq, 4);
;       const float rs = rsqrtf(qq * (1.f / 64.f) + EPS);
;       const int row = chunk_row0(b, c) + t;
;       float r[8];
; #pragma unroll
;       for (int j = 0; j < 8; ++j) {
;         const unsigned w = gw[j >> 1]; const float gt = (j & 1) ? bfhi(w) : bflo(w);
;         float y = o[j] * rs; if (mx == 0) y *= p.gla_g[l * 64 + e0 + j];
.LBB0_785:
	s_or_b64 exec, exec, s[6:7]
	v_readlane_b32 s6, v255, 19
	v_readlane_b32 s7, v255, 20
	v_cndmask_b32_e64 v0, v30, 0, s[66:67]
	s_mov_b32 s2, 0x800000
	s_nop 2
	v_cndmask_b32_e64 v26, v26, 0, s[6:7]
	v_add_f32_e32 v0, v0, v26
	v_readlane_b32 s6, v255, 21
	v_cvt_pk_bf16_f32 v0, v0, s0
	v_readlane_b32 s7, v255, 22
	ds_write_b16 v103, v0 offset:63488
	v_cndmask_b32_e64 v26, 0, v27, s[66:67]
	v_cndmask_b32_e64 v0, v31, 0, s[6:7]
	v_add_f32_e32 v0, v0, v26
	v_readlane_b32 s6, v255, 23
	v_cvt_pk_bf16_f32 v0, v0, s0
	v_readlane_b32 s7, v255, 24
	ds_write_b16 v103, v0 offset:63632
	s_nop 0
	v_cndmask_b32_e64 v0, v32, 0, s[6:7]
	v_readlane_b32 s6, v255, 25
	v_readlane_b32 s7, v255, 26
	s_nop 1
	v_cndmask_b32_e64 v26, v28, 0, s[6:7]
	v_add_f32_e32 v0, v0, v26
	v_readlane_b32 s6, v255, 27
	v_cvt_pk_bf16_f32 v0, v0, s0
	v_readlane_b32 s7, v255, 28
	ds_write_b16 v103, v0 offset:63776
	v_cndmask_b32_e64 v26, v29, 0, s[42:43]
	v_cndmask_b32_e64 v0, v33, 0, s[6:7]
	v_add_f32_e32 v0, v0, v26
	v_cvt_pk_bf16_f32 v0, v0, s0
	ds_write_b16 v103, v0 offset:63920
	s_waitcnt lgkmcnt(0)
	s_barrier
	ds_read_b128 v[26:29], v68 offset:63488
	ds_read_b128 v[30:33], v96 offset:26624
	s_waitcnt lgkmcnt(0)
	v_mfma_f32_16x16x32_bf16 v[26:29], v[26:29], v[30:33], 0
	ds_read_b128 v[30:33], v68 offset:35840
	ds_read_b128 v[108:111], v96 offset:54272
	s_waitcnt lgkmcnt(0)
	v_mfma_f32_16x16x32_bf16 v[26:29], v[30:33], v[108:111], v[26:29]
	ds_read_b128 v[30:33], v68 offset:63552
	ds_read_b128 v[108:111], v96 offset:26688
	s_waitcnt lgkmcnt(0)
	v_mfma_f32_16x16x32_bf16 v[26:29], v[30:33], v[108:111], v[26:29]
	ds_read_b128 v[30:33], v68 offset:35904
	ds_read_b128 v[108:111], v96 offset:54336
	s_waitcnt lgkmcnt(0)
	v_mfma_f32_16x16x32_bf16 v[26:29], v[30:33], v[108:111], v[26:29]
	s_nop 7
	ds_write2_b32 v104, v26, v27 offset1:65
	ds_write2_b32 v104, v28, v29 offset0:130 offset1:195
	ds_read_b128 v[26:29], v68 offset:63488
	ds_read_b128 v[30:33], v97 offset:26624
	s_waitcnt lgkmcnt(0)
	v_mfma_f32_16x16x32_bf16 v[26:29], v[26:29], v[30:33], 0
	ds_read_b128 v[30:33], v68 offset:35840
	ds_read_b128 v[108:111], v97 offset:54272
	s_waitcnt lgkmcnt(0)
	v_mfma_f32_16x16x32_bf16 v[26:29], v[30:33], v[108:111], v[26:29]
	ds_read_b128 v[30:33], v68 offset:63552
	ds_read_b128 v[108:111], v97 offset:26688
	s_waitcnt lgkmcnt(0)
	v_mfma_f32_16x16x32_bf16 v[26:29], v[30:33], v[108:111], v[26:29]
	ds_read_b128 v[30:33], v68 offset:35904
	ds_read_b128 v[108:111], v97 offset:54336
	s_waitcnt lgkmcnt(0)
	v_mfma_f32_16x16x32_bf16 v[26:29], v[30:33], v[108:111], v[26:29]
	s_nop 7
	ds_write2_b32 v105, v26, v27 offset1:65
	ds_write2_b32 v105, v28, v29 offset0:130 offset1:195
	s_waitcnt lgkmcnt(0)
	s_barrier
	ds_read2_b32 v[26:27], v69 offset0:6 offset1:7
	ds_read2_b32 v[28:29], v69 offset0:4 offset1:5
	ds_read2_b32 v[30:31], v69 offset0:2 offset1:3
	ds_read2_b32 v[32:33], v69 offset1:1
	s_waitcnt lgkmcnt(0)
	v_add_f32_e32 v0, 0, v32
	v_add_f32_e32 v0, v0, v33
	v_add_f32_e32 v0, v0, v30
	v_add_f32_e32 v0, v0, v31
	v_add_f32_e32 v0, v0, v28
	v_add_f32_e32 v0, v0, v29
	v_add_f32_e32 v0, v0, v26
	v_add_f32_e32 v0, v0, v27
	ds_bpermute_b32 v34, v91, v0
	s_waitcnt lgkmcnt(0)
	v_add_f32_e32 v0, v0, v34
	ds_bpermute_b32 v34, v92, v0
	s_waitcnt lgkmcnt(0)
	v_add_f32_e32 v0, v0, v34
	ds_bpermute_b32 v34, v93, v0
	s_waitcnt lgkmcnt(0)
	v_add_f32_e32 v0, v0, v34
	v_mul_f32_e32 v0, 0x3c800000, v0
	v_cndmask_b32_e64 v0, 0, v0, s[80:81]
	v_pk_add_f32 v[32:33], v[32:33], v[0:1] op_sel_hi:[1,0] neg_lo:[0,1] neg_hi:[0,1]
	v_pk_add_f32 v[30:31], v[30:31], v[0:1] op_sel_hi:[1,0] neg_lo:[0,1] neg_hi:[0,1]
	v_pk_mul_f32 v[34:35], v[32:33], v[32:33]
	v_pk_mul_f32 v[84:85], v[30:31], v[30:31]
	v_pk_add_f32 v[28:29], v[28:29], v[0:1] op_sel_hi:[1,0] neg_lo:[0,1] neg_hi:[0,1]
	v_pk_add_f32 v[26:27], v[26:27], v[0:1] op_sel_hi:[1,0] neg_lo:[0,1] neg_hi:[0,1]
	v_add_f32_e32 v0, v34, v35
	v_add_f32_e32 v0, v84, v0
	v_pk_mul_f32 v[108:109], v[28:29], v[28:29]
	v_add_f32_e32 v0, v85, v0
	v_add_f32_e32 v0, v108, v0
	v_pk_mul_f32 v[110:111], v[26:27], v[26:27]
	v_add_f32_e32 v0, v109, v0
	v_add_f32_e32 v0, v110, v0
	v_add_f32_e32 v0, v111, v0
	ds_bpermute_b32 v34, v91, v0
	s_waitcnt lgkmcnt(0)
	v_add_f32_e32 v0, v0, v34
	ds_bpermute_b32 v34, v92, v0
	s_waitcnt lgkmcnt(0)
	v_add_f32_e32 v0, v0, v34
	ds_bpermute_b32 v34, v93, v0
	s_waitcnt lgkmcnt(0)
	v_add_f32_e32 v0, v0, v34
	v_mov_b32_e32 v34, 0x358637bd
	v_fmamk_f32 v0, v0, 0x3c800000, v34
	v_cmp_gt_f32_e32 vcc, s2, v0
	v_mul_f32_e32 v34, 0x4b800000, v0
	s_nop 0
	v_cndmask_b32_e32 v0, v0, v34, vcc
	v_rsq_f32_e32 v0, v0
	s_nop 0
	v_mul_f32_e32 v34, 0x45800000, v0
	v_cndmask_b32_e32 v34, v0, v34, vcc
	v_mul_f32_e32 v0, v32, v34
	v_cndmask_b32_e64 v32, 0, 1, s[12:13]
	v_cmp_ne_u32_e64 s[80:81], 1, v32
	s_andn2_b64 vcc, exec, s[12:13]
	s_cbranch_vccnz .LBB0_809
	v_mov_b32_e32 v32, v176
	v_mul_f32_e32 v0, v0, v32
	s_and_b64 vcc, exec, s[80:81]
	v_mul_f32_e32 v32, v33, v34
	s_cbranch_vccz .LBB0_810

; __device__ __forceinline__ float bflo(unsigned w) { return __uint_as_float(w << 16); }
; __device__ __forceinline__ float bfhi(unsigned w) { return __uint_as_float(w & 0xffff0000u); }
; __device__ __forceinline__ float silu_f(float v) { return v * __builtin_amdgcn_rcpf(1.f + __expf(-v)); }
; __device__ void scanC_phase(const Params& p, int l, bool last, char* shm, int w0) {
;     ...
;       for (int j = 0; j < 8; ++j) {
;         const unsigned w = gw[j >> 1]; const float gt = (j & 1) ? bfhi(w) : bflo(w);
;         float y = o[j] * rs; if (mx == 0) y *= p.gla_g[l * 64 + e0 + j];
;         r[j] = y * silu_f(gt);
.LBB0_788:
	v_mov_b32_e32 v33, v178
	v_mul_f32_e32 v30, v30, v33
	s_and_b64 vcc, exec, s[80:81]
	v_mul_f32_e32 v31, v31, v34
	s_cbranch_vccz .LBB0_812

; __device__ __forceinline__ float bflo(unsigned w) { return __uint_as_float(w << 16); }
; __device__ __forceinline__ float bfhi(unsigned w) { return __uint_as_float(w & 0xffff0000u); }
; __device__ __forceinline__ float silu_f(float v) { return v * __builtin_amdgcn_rcpf(1.f + __expf(-v)); }
; __device__ void scanC_phase(const Params& p, int l, bool last, char* shm, int w0) {
;     ...
;       for (int j = 0; j < 8; ++j) {
;         const unsigned w = gw[j >> 1]; const float gt = (j & 1) ? bfhi(w) : bflo(w);
;         float y = o[j] * rs; if (mx == 0) y *= p.gla_g[l * 64 + e0 + j];
;         r[j] = y * silu_f(gt);
.LBB0_790:
	v_mov_b32_e32 v33, v180
	v_mul_f32_e32 v28, v28, v33
	s_and_b64 vcc, exec, s[80:81]
	v_mul_f32_e32 v29, v29, v34
	s_cbranch_vccz .LBB0_814

; __device__ __forceinline__ float bflo(unsigned w) { return __uint_as_float(w << 16); }
; __device__ __forceinline__ float bfhi(unsigned w) { return __uint_as_float(w & 0xffff0000u); }
; __device__ __forceinline__ float silu_f(float v) { return v * __builtin_amdgcn_rcpf(1.f + __expf(-v)); }
; __device__ void scanC_phase(const Params& p, int l, bool last, char* shm, int w0) {
;     ...
;       for (int j = 0; j < 8; ++j) {
;         const unsigned w = gw[j >> 1]; const float gt = (j & 1) ? bfhi(w) : bflo(w);
;         float y = o[j] * rs; if (mx == 0) y *= p.gla_g[l * 64 + e0 + j];
;         r[j] = y * silu_f(gt);
.LBB0_792:
	v_mov_b32_e32 v26, v182
	v_mul_f32_e32 v33, v33, v26
	s_and_b64 vcc, exec, s[80:81]
	v_mul_f32_e32 v26, v27, v34
	s_cbranch_vccnz .LBB0_716
	s_branch .LBB0_816

; __device__ __forceinline__ float bflo(unsigned w) { return __uint_as_float(w << 16); }
; __device__ __forceinline__ float bfhi(unsigned w) { return __uint_as_float(w & 0xffff0000u); }
; __device__ __forceinline__ float silu_f(float v) { return v * __builtin_amdgcn_rcpf(1.f + __expf(-v)); }
; __device__ void scanC_phase(const Params& p, int l, bool last, char* shm, int w0) {
;     ...
;       for (int j = 0; j < 8; ++j) {
;         const unsigned w = gw[j >> 1]; const float gt = (j & 1) ? bfhi(w) : bflo(w);
;         float y = o[j] * rs; if (mx == 0) y *= p.gla_g[l * 64 + e0 + j];
;         r[j] = y * silu_f(gt);
.LBB0_810:
	v_mov_b32_e32 v33, v177
	v_mul_f32_e32 v32, v32, v33
	s_and_b64 vcc, exec, s[80:81]
	v_mul_f32_e32 v30, v30, v34
	s_cbranch_vccz .LBB0_788

; __device__ __forceinline__ float bflo(unsigned w) { return __uint_as_float(w << 16); }
; __device__ __forceinline__ float bfhi(unsigned w) { return __uint_as_float(w & 0xffff0000u); }
; __device__ __forceinline__ float silu_f(float v) { return v * __builtin_amdgcn_rcpf(1.f + __expf(-v)); }
; __device__ void scanC_phase(const Params& p, int l, bool last, char* shm, int w0) {
;     ...
;       for (int j = 0; j < 8; ++j) {
;         const unsigned w = gw[j >> 1]; const float gt = (j & 1) ? bfhi(w) : bflo(w);
;         float y = o[j] * rs; if (mx == 0) y *= p.gla_g[l * 64 + e0 + j];
;         r[j] = y * silu_f(gt);
.LBB0_812:
	v_mov_b32_e32 v33, v179
	v_mul_f32_e32 v31, v31, v33
	s_and_b64 vcc, exec, s[80:81]
	v_mul_f32_e32 v28, v28, v34
	s_cbranch_vccz .LBB0_790

; __device__ __forceinline__ float bflo(unsigned w) { return __uint_as_float(w << 16); }
; __device__ __forceinline__ float bfhi(unsigned w) { return __uint_as_float(w & 0xffff0000u); }
; __device__ __forceinline__ float silu_f(float v) { return v * __builtin_amdgcn_rcpf(1.f + __expf(-v)); }
; __device__ void scanC_phase(const Params& p, int l, bool last, char* shm, int w0) {
;     ...
;       for (int j = 0; j < 8; ++j) {
;         const unsigned w = gw[j >> 1]; const float gt = (j & 1) ? bfhi(w) : bflo(w);
;         float y = o[j] * rs; if (mx == 0) y *= p.gla_g[l * 64 + e0 + j];
;         r[j] = y * silu_f(gt);
.LBB0_814:
	v_mov_b32_e32 v33, v181
	v_mul_f32_e32 v29, v29, v33
	s_and_b64 vcc, exec, s[80:81]
	v_mul_f32_e32 v33, v26, v34
	s_cbranch_vccz .LBB0_792

; __device__ __forceinline__ float bflo(unsigned w) { return __uint_as_float(w << 16); }
; __device__ __forceinline__ float bfhi(unsigned w) { return __uint_as_float(w & 0xffff0000u); }
; __device__ __forceinline__ float silu_f(float v) { return v * __builtin_amdgcn_rcpf(1.f + __expf(-v)); }
; __device__ void scanC_phase(const Params& p, int l, bool last, char* shm, int w0) {
;     ...
;       for (int j = 0; j < 8; ++j) {
;         const unsigned w = gw[j >> 1]; const float gt = (j & 1) ? bfhi(w) : bflo(w);
;         float y = o[j] * rs; if (mx == 0) y *= p.gla_g[l * 64 + e0 + j];
;         r[j] = y * silu_f(gt);
.LBB0_816:
	v_mov_b32_e32 v27, v183
	v_mul_f32_e32 v26, v26, v27
	s_branch .LBB0_716

; __device__ __forceinline__ unsigned pk2(float lo, float hi) { const f2_t v = {lo, hi}; return __builtin_bit_cast(unsigned, __builtin_convertvector(v, bf2_t)); }
; __device__ __forceinline__ float bflo(unsigned w) { return __uint_as_float(w << 16); }
; __device__ __forceinline__ float bfhi(unsigned w) { return __uint_as_float(w & 0xffff0000u); }
; __device__ void scanB_phase(const Params& p, int w0) {
;     ...
;   for (int task = blockIdx.x; task < 512 * 2; task += gridDim.x) {
;     const int chain = task >> 1, i = ((task & 1) * 512 + tid) * 2, d = i & 31, dir = chain & 1;
;     bf16_t* st = p.St + (long)chain * 36 * 2048 + i; const float* dc = p.dec + (long)chain * 36 * 32 + d;
;     unsigned loc[36]; float dv0[36], dv1[36];
; #pragma unroll
;     for (int k = 0; k < 36; ++k) { const int c = dir == 0 ? k : (k < 4 ? 3 - k : 39 - k); loc[k] = *(const unsigned*)(st + (long)c * 2048); dv0[k] = dc[c * 32]; dv1[k] = dc[c * 32 + 1]; }
;     float r0 = 0.f, r1 = 0.f;
; #pragma unroll
;     for (int k = 0; k < 36; ++k) { const int c = dir == 0 ? k : (k < 4 ? 3 - k : 39 - k); *(unsigned*)(st + (long)c * 2048) = pk2(r0, r1); r0 = r0 * dv0[k] + bflo(loc[k]); r1 = r1 * dv1[k] + bfhi(loc[k]); }
.LBB0_822:
	s_ashr_i32 s2, s5, 1
	s_and_b32 s0, s4, 0x200
	v_add_u32_e32 v0, s0, v144
	s_mul_i32 s0, s2, 0x24000
	s_mul_hi_i32 s1, s2, 0x24000
	s_add_u32 s0, s48, s0
	s_addc_u32 s1, s49, s1
	s_mul_hi_i32 s7, s2, 0x1200
	s_mulk_i32 s2, 0x1200
	s_add_u32 s6, s50, s2
	s_addc_u32 s7, s51, s7
	v_lshlrev_b32_e32 v2, 2, v0
	v_lshlrev_b32_e32 v3, 3, v0
	v_and_b32_e32 v3, 0x78, v3
	s_bfe_u32 s12, s5, 0x10001
	s_mul_i32 s13, s12, 0x2000
	s_sub_i32 s8, 0x1000, s13
	s_mul_i32 s13, s12, 0x100
	s_sub_i32 s9, 0x80, s13
	s_mul_i32 s13, s12, 0x3000
	s_mul_i32 s14, s12, 0x180
	s_mul_i32 s20, s12, 0x24000
	s_mul_i32 s21, s12, 0x1200
	v_add_u32_e32 v8, s13, v2
	v_add_u32_e32 v9, s14, v3
	v_mov_b32_e32 v118, v8
	global_load_dwordx2 v[10:11], v9, s[6:7]
	v_add_u32_e32 v9, s9, v9
	global_load_dword v82, v8, s[0:1]
	v_add_u32_e32 v8, s8, v8
	global_load_dwordx2 v[12:13], v9, s[6:7]
	v_add_u32_e32 v9, s9, v9
	global_load_dword v83, v8, s[0:1]
	v_add_u32_e32 v8, s8, v8
	global_load_dwordx2 v[14:15], v9, s[6:7]
	v_add_u32_e32 v9, s9, v9
	global_load_dword v84, v8, s[0:1]
	v_add_u32_e32 v8, s8, v8
	global_load_dwordx2 v[16:17], v9, s[6:7]
	v_add_u32_e32 v9, s9, v9
	v_add_u32_e32 v9, s21, v9
	global_load_dword v85, v8, s[0:1]
	v_add_u32_e32 v8, s8, v8
	v_add_u32_e32 v8, s20, v8
	global_load_dwordx2 v[18:19], v9, s[6:7]
	v_add_u32_e32 v9, s9, v9
	global_load_dword v86, v8, s[0:1]
	v_add_u32_e32 v8, s8, v8
	global_load_dwordx2 v[20:21], v9, s[6:7]
	v_add_u32_e32 v9, s9, v9
	global_load_dword v87, v8, s[0:1]
	v_add_u32_e32 v8, s8, v8
	global_load_dwordx2 v[22:23], v9, s[6:7]
	v_add_u32_e32 v9, s9, v9
	global_load_dword v88, v8, s[0:1]
	v_add_u32_e32 v8, s8, v8
	global_load_dwordx2 v[24:25], v9, s[6:7]
	v_add_u32_e32 v9, s9, v9
	global_load_dword v89, v8, s[0:1]
	v_add_u32_e32 v8, s8, v8
	global_load_dwordx2 v[26:27], v9, s[6:7]
	v_add_u32_e32 v9, s9, v9
	global_load_dword v90, v8, s[0:1]
	v_add_u32_e32 v8, s8, v8
	global_load_dwordx2 v[28:29], v9, s[6:7]
	v_add_u32_e32 v9, s9, v9
	global_load_dword v91, v8, s[0:1]
	v_add_u32_e32 v8, s8, v8
	global_load_dwordx2 v[30:31], v9, s[6:7]
	v_add_u32_e32 v9, s9, v9
	global_load_dword v92, v8, s[0:1]
	v_add_u32_e32 v8, s8, v8
	global_load_dwordx2 v[32:33], v9, s[6:7]
	v_add_u32_e32 v9, s9, v9
	global_load_dword v93, v8, s[0:1]
	v_add_u32_e32 v8, s8, v8
	global_load_dwordx2 v[34:35], v9, s[6:7]
	v_add_u32_e32 v9, s9, v9
	global_load_dword v94, v8, s[0:1]
	v_add_u32_e32 v8, s8, v8
	global_load_dwordx2 v[36:37], v9, s[6:7]
	v_add_u32_e32 v9, s9, v9
	global_load_dword v95, v8, s[0:1]
	v_add_u32_e32 v8, s8, v8
	global_load_dwordx2 v[38:39], v9, s[6:7]
	v_add_u32_e32 v9, s9, v9
	global_load_dword v96, v8, s[0:1]
	v_add_u32_e32 v8, s8, v8
	global_load_dwordx2 v[40:41], v9, s[6:7]
	v_add_u32_e32 v9, s9, v9
	global_load_dword v97, v8, s[0:1]
	v_add_u32_e32 v8, s8, v8
	global_load_dwordx2 v[42:43], v9, s[6:7]
	v_add_u32_e32 v9, s9, v9
	global_load_dword v98, v8, s[0:1]
	v_add_u32_e32 v8, s8, v8
	global_load_dwordx2 v[44:45], v9, s[6:7]
	v_add_u32_e32 v9, s9, v9
	global_load_dword v99, v8, s[0:1]
	v_add_u32_e32 v8, s8, v8
	global_load_dwordx2 v[46:47], v9, s[6:7]
	v_add_u32_e32 v9, s9, v9
	global_load_dword v100, v8, s[0:1]
	v_add_u32_e32 v8, s8, v8
	global_load_dwordx2 v[48:49], v9, s[6:7]
	v_add_u32_e32 v9, s9, v9
	global_load_dword v101, v8, s[0:1]
	v_add_u32_e32 v8, s8, v8
	global_load_dwordx2 v[50:51], v9, s[6:7]
	v_add_u32_e32 v9, s9, v9
	global_load_dword v102, v8, s[0:1]
	v_add_u32_e32 v8, s8, v8
	global_load_dwordx2 v[52:53], v9, s[6:7]
	v_add_u32_e32 v9, s9, v9
	global_load_dword v103, v8, s[0:1]
	v_add_u32_e32 v8, s8, v8
	global_load_dwordx2 v[54:55], v9, s[6:7]
	v_add_u32_e32 v9, s9, v9
	global_load_dword v104, v8, s[0:1]
	v_add_u32_e32 v8, s8, v8
	global_load_dwordx2 v[56:57], v9, s[6:7]
	v_add_u32_e32 v9, s9, v9
	global_load_dword v105, v8, s[0:1]
	v_add_u32_e32 v8, s8, v8
	global_load_dwordx2 v[58:59], v9, s[6:7]
	v_add_u32_e32 v9, s9, v9
	global_load_dword v106, v8, s[0:1]
	v_add_u32_e32 v8, s8, v8
	global_load_dwordx2 v[60:61], v9, s[6:7]
	v_add_u32_e32 v9, s9, v9
	global_load_dword v107, v8, s[0:1]
	v_add_u32_e32 v8, s8, v8
	global_load_dwordx2 v[62:63], v9, s[6:7]
	v_add_u32_e32 v9, s9, v9
	global_load_dword v108, v8, s[0:1]
	v_add_u32_e32 v8, s8, v8
	global_load_dword v109, v8, s[0:1]
	v_add_u32_e32 v8, s8, v8
	global_load_dword v110, v8, s[0:1]
	v_add_u32_e32 v8, s8, v8
	global_load_dword v111, v8, s[0:1]
	v_add_u32_e32 v8, s8, v8
	global_load_dword v112, v8, s[0:1]
	v_add_u32_e32 v8, s8, v8
	global_load_dword v113, v8, s[0:1]
	v_add_u32_e32 v8, s8, v8
	global_load_dword v114, v8, s[0:1]
	v_add_u32_e32 v8, s8, v8
	global_load_dword v115, v8, s[0:1]
	v_add_u32_e32 v8, s8, v8
	global_load_dword v116, v8, s[0:1]
	v_add_u32_e32 v8, s8, v8
	global_load_dword v117, v8, s[0:1]
	s_waitcnt vmcnt(61)
	global_store_dword v118, v1, s[0:1]
	v_lshlrev_b32_e32 v4, 16, v82
	v_and_b32_e32 v5, 0xffff0000, v82
	v_pk_fma_f32 v[6:7], v[10:11], 0, v[4:5] op_sel_hi:[1,0,1]
	v_add_u32_e32 v118, s8, v118
	global_load_dwordx2 v[64:65], v9, s[6:7]
	v_add_u32_e32 v9, s9, v9
	s_nop 0
	s_waitcnt vmcnt(61)
	v_cvt_pk_bf16_f32 v120, v6, v7
	global_store_dword v118, v120, s[0:1]
	v_lshlrev_b32_e32 v4, 16, v83
	v_and_b32_e32 v5, 0xffff0000, v83
	v_pk_fma_f32 v[6:7], v[6:7], v[12:13], v[4:5]
	v_add_u32_e32 v118, s8, v118
	global_load_dwordx2 v[66:67], v9, s[6:7]
	v_add_u32_e32 v9, s9, v9
	s_nop 0
	s_waitcnt vmcnt(61)
	v_cvt_pk_bf16_f32 v121, v6, v7
	global_store_dword v118, v121, s[0:1]
	v_lshlrev_b32_e32 v4, 16, v84
	v_and_b32_e32 v5, 0xffff0000, v84
	v_pk_fma_f32 v[6:7], v[6:7], v[14:15], v[4:5]
	v_add_u32_e32 v118, s8, v118
	global_load_dwordx2 v[68:69], v9, s[6:7]
	v_add_u32_e32 v9, s9, v9
	s_nop 0
	s_waitcnt vmcnt(61)
; __device__ __forceinline__ unsigned pk2(float lo, float hi) { const f2_t v = {lo, hi}; return __builtin_bit_cast(unsigned, __builtin_convertvector(v, bf2_t)); }
; __device__ __forceinline__ float bflo(unsigned w) { return __uint_as_float(w << 16); }
; __device__ __forceinline__ float bfhi(unsigned w) { return __uint_as_float(w & 0xffff0000u); }
; __device__ void scanB_phase(const Params& p, int w0) {
;     ...
;     for (int k = 0; k < 36; ++k) { const int c = dir == 0 ? k : (k < 4 ? 3 - k : 39 - k); *(unsigned*)(st + (long)c * 2048) = pk2(r0, r1); r0 = r0 * dv0[k] + bflo(loc[k]); r1 = r1 * dv1[k] + bfhi(loc[k]); }
	v_cvt_pk_bf16_f32 v122, v6, v7
	global_store_dword v118, v122, s[0:1]
	v_lshlrev_b32_e32 v4, 16, v85
	v_and_b32_e32 v5, 0xffff0000, v85
	v_pk_fma_f32 v[6:7], v[6:7], v[16:17], v[4:5]
	v_add_u32_e32 v118, s8, v118
	v_add_u32_e32 v118, s20, v118
	global_load_dwordx2 v[70:71], v9, s[6:7]
	v_add_u32_e32 v9, s9, v9
	s_nop 0
	s_waitcnt vmcnt(61)
	v_cvt_pk_bf16_f32 v119, v6, v7
	global_store_dword v118, v119, s[0:1]
	v_lshlrev_b32_e32 v4, 16, v86
	v_and_b32_e32 v5, 0xffff0000, v86
	v_pk_fma_f32 v[6:7], v[6:7], v[18:19], v[4:5]
	v_add_u32_e32 v118, s8, v118
	global_load_dwordx2 v[72:73], v9, s[6:7]
	v_add_u32_e32 v9, s9, v9
	s_nop 0
	s_waitcnt vmcnt(61)
	v_cvt_pk_bf16_f32 v120, v6, v7
	global_store_dword v118, v120, s[0:1]
	v_lshlrev_b32_e32 v4, 16, v87
	v_and_b32_e32 v5, 0xffff0000, v87
	v_pk_fma_f32 v[6:7], v[6:7], v[20:21], v[4:5]
	v_add_u32_e32 v118, s8, v118
	global_load_dwordx2 v[74:75], v9, s[6:7]
	v_add_u32_e32 v9, s9, v9
	s_nop 0
	s_waitcnt vmcnt(61)
	v_cvt_pk_bf16_f32 v121, v6, v7
	global_store_dword v118, v121, s[0:1]
	v_lshlrev_b32_e32 v4, 16, v88
	v_and_b32_e32 v5, 0xffff0000, v88
	v_pk_fma_f32 v[6:7], v[6:7], v[22:23], v[4:5]
	v_add_u32_e32 v118, s8, v118
	global_load_dwordx2 v[76:77], v9, s[6:7]
	v_add_u32_e32 v9, s9, v9
	s_nop 0
	s_waitcnt vmcnt(61)
	v_cvt_pk_bf16_f32 v122, v6, v7
	global_store_dword v118, v122, s[0:1]
	v_lshlrev_b32_e32 v4, 16, v89
	v_and_b32_e32 v5, 0xffff0000, v89
	v_pk_fma_f32 v[6:7], v[6:7], v[24:25], v[4:5]
	v_add_u32_e32 v118, s8, v118
	global_load_dwordx2 v[78:79], v9, s[6:7]
	v_add_u32_e32 v9, s9, v9
	s_nop 0
	s_waitcnt vmcnt(61)
	v_cvt_pk_bf16_f32 v119, v6, v7
	global_store_dword v118, v119, s[0:1]
	v_lshlrev_b32_e32 v4, 16, v90
	v_and_b32_e32 v5, 0xffff0000, v90
	v_pk_fma_f32 v[6:7], v[6:7], v[26:27], v[4:5]
	v_add_u32_e32 v118, s8, v118
	global_load_dwordx2 v[80:81], v9, s[6:7]
	s_nop 0
	s_waitcnt vmcnt(61)
	v_cvt_pk_bf16_f32 v120, v6, v7
	global_store_dword v118, v120, s[0:1]
	v_lshlrev_b32_e32 v4, 16, v91
	v_and_b32_e32 v5, 0xffff0000, v91
	v_pk_fma_f32 v[6:7], v[6:7], v[28:29], v[4:5]
	v_add_u32_e32 v118, s8, v118
	s_nop 0
	s_waitcnt vmcnt(60)
	v_cvt_pk_bf16_f32 v121, v6, v7
	global_store_dword v118, v121, s[0:1]
	v_lshlrev_b32_e32 v4, 16, v92
	v_and_b32_e32 v5, 0xffff0000, v92
	v_pk_fma_f32 v[6:7], v[6:7], v[30:31], v[4:5]
	v_add_u32_e32 v118, s8, v118
	s_nop 0
	s_waitcnt vmcnt(59)
	v_cvt_pk_bf16_f32 v122, v6, v7
	global_store_dword v118, v122, s[0:1]
	v_lshlrev_b32_e32 v4, 16, v93
	v_and_b32_e32 v5, 0xffff0000, v93
	v_pk_fma_f32 v[6:7], v[6:7], v[32:33], v[4:5]
	v_add_u32_e32 v118, s8, v118
	s_nop 0
	s_waitcnt vmcnt(58)
	v_cvt_pk_bf16_f32 v119, v6, v7
	global_store_dword v118, v119, s[0:1]
	v_lshlrev_b32_e32 v4, 16, v94
	v_and_b32_e32 v5, 0xffff0000, v94
	v_pk_fma_f32 v[6:7], v[6:7], v[34:35], v[4:5]
	v_add_u32_e32 v118, s8, v118
	s_nop 0
	s_waitcnt vmcnt(57)
	v_cvt_pk_bf16_f32 v120, v6, v7
	global_store_dword v118, v120, s[0:1]
	v_lshlrev_b32_e32 v4, 16, v95
	v_and_b32_e32 v5, 0xffff0000, v95
	v_pk_fma_f32 v[6:7], v[6:7], v[36:37], v[4:5]
	v_add_u32_e32 v118, s8, v118
	s_nop 0
	s_waitcnt vmcnt(56)
	v_cvt_pk_bf16_f32 v121, v6, v7
	global_store_dword v118, v121, s[0:1]
	v_lshlrev_b32_e32 v4, 16, v96
	v_and_b32_e32 v5, 0xffff0000, v96
	v_pk_fma_f32 v[6:7], v[6:7], v[38:39], v[4:5]
	v_add_u32_e32 v118, s8, v118
	s_nop 0
	s_waitcnt vmcnt(55)
	v_cvt_pk_bf16_f32 v122, v6, v7
	global_store_dword v118, v122, s[0:1]
	v_lshlrev_b32_e32 v4, 16, v97
	v_and_b32_e32 v5, 0xffff0000, v97
	v_pk_fma_f32 v[6:7], v[6:7], v[40:41], v[4:5]
	v_add_u32_e32 v118, s8, v118
	s_nop 0
	s_waitcnt vmcnt(54)
	v_cvt_pk_bf16_f32 v119, v6, v7
	global_store_dword v118, v119, s[0:1]
	v_lshlrev_b32_e32 v4, 16, v98
	v_and_b32_e32 v5, 0xffff0000, v98
	v_pk_fma_f32 v[6:7], v[6:7], v[42:43], v[4:5]
	v_add_u32_e32 v118, s8, v118
	s_nop 0
	s_waitcnt vmcnt(53)
	v_cvt_pk_bf16_f32 v120, v6, v7
	global_store_dword v118, v120, s[0:1]
	v_lshlrev_b32_e32 v4, 16, v99
	v_and_b32_e32 v5, 0xffff0000, v99
	v_pk_fma_f32 v[6:7], v[6:7], v[44:45], v[4:5]
	v_add_u32_e32 v118, s8, v118
	s_nop 0
	s_waitcnt vmcnt(52)
	v_cvt_pk_bf16_f32 v121, v6, v7
	global_store_dword v118, v121, s[0:1]
	v_lshlrev_b32_e32 v4, 16, v100
	v_and_b32_e32 v5, 0xffff0000, v100
	v_pk_fma_f32 v[6:7], v[6:7], v[46:47], v[4:5]
	v_add_u32_e32 v118, s8, v118
	s_nop 0
	s_waitcnt vmcnt(51)
; __device__ __forceinline__ unsigned pk2(float lo, float hi) { const f2_t v = {lo, hi}; return __builtin_bit_cast(unsigned, __builtin_convertvector(v, bf2_t)); }
; __device__ __forceinline__ float bflo(unsigned w) { return __uint_as_float(w << 16); }
; __device__ __forceinline__ float bfhi(unsigned w) { return __uint_as_float(w & 0xffff0000u); }
; __device__ void scanB_phase(const Params& p, int w0) {
;     ...
;     for (int k = 0; k < 36; ++k) { const int c = dir == 0 ? k : (k < 4 ? 3 - k : 39 - k); *(unsigned*)(st + (long)c * 2048) = pk2(r0, r1); r0 = r0 * dv0[k] + bflo(loc[k]); r1 = r1 * dv1[k] + bfhi(loc[k]); }
;   }
	v_cvt_pk_bf16_f32 v122, v6, v7
	global_store_dword v118, v122, s[0:1]
	v_lshlrev_b32_e32 v4, 16, v101
	v_and_b32_e32 v5, 0xffff0000, v101
	v_pk_fma_f32 v[6:7], v[6:7], v[48:49], v[4:5]
	v_add_u32_e32 v118, s8, v118
	s_nop 0
	s_waitcnt vmcnt(50)
	v_cvt_pk_bf16_f32 v119, v6, v7
	global_store_dword v118, v119, s[0:1]
	v_lshlrev_b32_e32 v4, 16, v102
	v_and_b32_e32 v5, 0xffff0000, v102
	v_pk_fma_f32 v[6:7], v[6:7], v[50:51], v[4:5]
	v_add_u32_e32 v118, s8, v118
	s_nop 0
	s_waitcnt vmcnt(49)
	v_cvt_pk_bf16_f32 v120, v6, v7
	global_store_dword v118, v120, s[0:1]
	v_lshlrev_b32_e32 v4, 16, v103
	v_and_b32_e32 v5, 0xffff0000, v103
	v_pk_fma_f32 v[6:7], v[6:7], v[52:53], v[4:5]
	v_add_u32_e32 v118, s8, v118
	s_nop 0
	s_waitcnt vmcnt(48)
	v_cvt_pk_bf16_f32 v121, v6, v7
	global_store_dword v118, v121, s[0:1]
	v_lshlrev_b32_e32 v4, 16, v104
	v_and_b32_e32 v5, 0xffff0000, v104
	v_pk_fma_f32 v[6:7], v[6:7], v[54:55], v[4:5]
	v_add_u32_e32 v118, s8, v118
	s_nop 0
	s_waitcnt vmcnt(47)
	v_cvt_pk_bf16_f32 v122, v6, v7
	global_store_dword v118, v122, s[0:1]
	v_lshlrev_b32_e32 v4, 16, v105
	v_and_b32_e32 v5, 0xffff0000, v105
	v_pk_fma_f32 v[6:7], v[6:7], v[56:57], v[4:5]
	v_add_u32_e32 v118, s8, v118
	s_nop 0
	s_waitcnt vmcnt(46)
	v_cvt_pk_bf16_f32 v119, v6, v7
	global_store_dword v118, v119, s[0:1]
	v_lshlrev_b32_e32 v4, 16, v106
	v_and_b32_e32 v5, 0xffff0000, v106
	v_pk_fma_f32 v[6:7], v[6:7], v[58:59], v[4:5]
	v_add_u32_e32 v118, s8, v118
	s_nop 0
	s_waitcnt vmcnt(45)
	v_cvt_pk_bf16_f32 v120, v6, v7
	global_store_dword v118, v120, s[0:1]
	v_lshlrev_b32_e32 v4, 16, v107
	v_and_b32_e32 v5, 0xffff0000, v107
	v_pk_fma_f32 v[6:7], v[6:7], v[60:61], v[4:5]
	v_add_u32_e32 v118, s8, v118
	s_nop 0
	s_waitcnt vmcnt(44)
	v_cvt_pk_bf16_f32 v121, v6, v7
	global_store_dword v118, v121, s[0:1]
	v_lshlrev_b32_e32 v4, 16, v108
	v_and_b32_e32 v5, 0xffff0000, v108
	v_pk_fma_f32 v[6:7], v[6:7], v[62:63], v[4:5]
	v_add_u32_e32 v118, s8, v118
	s_nop 0
	s_waitcnt vmcnt(34)
	v_cvt_pk_bf16_f32 v122, v6, v7
	global_store_dword v118, v122, s[0:1]
	v_lshlrev_b32_e32 v4, 16, v109
	v_and_b32_e32 v5, 0xffff0000, v109
	v_pk_fma_f32 v[6:7], v[6:7], v[64:65], v[4:5]
	v_add_u32_e32 v118, s8, v118
	s_nop 0
	s_waitcnt vmcnt(33)
	v_cvt_pk_bf16_f32 v119, v6, v7
	global_store_dword v118, v119, s[0:1]
	v_lshlrev_b32_e32 v4, 16, v110
	v_and_b32_e32 v5, 0xffff0000, v110
	v_pk_fma_f32 v[6:7], v[6:7], v[66:67], v[4:5]
	v_add_u32_e32 v118, s8, v118
	s_nop 0
	s_waitcnt vmcnt(32)
	v_cvt_pk_bf16_f32 v120, v6, v7
	global_store_dword v118, v120, s[0:1]
	v_lshlrev_b32_e32 v4, 16, v111
	v_and_b32_e32 v5, 0xffff0000, v111
	v_pk_fma_f32 v[6:7], v[6:7], v[68:69], v[4:5]
	v_add_u32_e32 v118, s8, v118
	s_nop 0
	s_waitcnt vmcnt(31)
	v_cvt_pk_bf16_f32 v121, v6, v7
	global_store_dword v118, v121, s[0:1]
	v_lshlrev_b32_e32 v4, 16, v112
	v_and_b32_e32 v5, 0xffff0000, v112
	v_pk_fma_f32 v[6:7], v[6:7], v[70:71], v[4:5]
	v_add_u32_e32 v118, s8, v118
	s_nop 0
	s_waitcnt vmcnt(30)
	v_cvt_pk_bf16_f32 v122, v6, v7
	global_store_dword v118, v122, s[0:1]
	v_lshlrev_b32_e32 v4, 16, v113
	v_and_b32_e32 v5, 0xffff0000, v113
	v_pk_fma_f32 v[6:7], v[6:7], v[72:73], v[4:5]
	v_add_u32_e32 v118, s8, v118
	s_nop 0
	s_waitcnt vmcnt(29)
	v_cvt_pk_bf16_f32 v119, v6, v7
	global_store_dword v118, v119, s[0:1]
	v_lshlrev_b32_e32 v4, 16, v114
	v_and_b32_e32 v5, 0xffff0000, v114
	v_pk_fma_f32 v[6:7], v[6:7], v[74:75], v[4:5]
	v_add_u32_e32 v118, s8, v118
	s_nop 0
	s_waitcnt vmcnt(28)
	v_cvt_pk_bf16_f32 v120, v6, v7
	global_store_dword v118, v120, s[0:1]
	v_lshlrev_b32_e32 v4, 16, v115
	v_and_b32_e32 v5, 0xffff0000, v115
	v_pk_fma_f32 v[6:7], v[6:7], v[76:77], v[4:5]
	v_add_u32_e32 v118, s8, v118
	s_nop 0
	s_waitcnt vmcnt(27)
	v_cvt_pk_bf16_f32 v121, v6, v7
	global_store_dword v118, v121, s[0:1]
	v_lshlrev_b32_e32 v4, 16, v116
	v_and_b32_e32 v5, 0xffff0000, v116
	v_pk_fma_f32 v[6:7], v[6:7], v[78:79], v[4:5]
	v_add_u32_e32 v118, s8, v118
	s_nop 0
	s_waitcnt vmcnt(26)
	v_cvt_pk_bf16_f32 v122, v6, v7
	global_store_dword v118, v122, s[0:1]
	v_lshlrev_b32_e32 v4, 16, v117
	v_and_b32_e32 v5, 0xffff0000, v117
	v_pk_fma_f32 v[6:7], v[6:7], v[80:81], v[4:5]
	s_nop 0
	s_add_i32 s5, s5, s62
	s_add_i32 s4, s4, s16
	s_cmpk_lt_i32 s5, 0x400
	s_cbranch_scc1 .LBB0_822
